# cross-attention: all 16 QK/PV stage bodies use hoisted LDS fragment reads (pool of 8 operand quads) with counted waits; mixing wait fixes kept
# baseline (speedup 1.0000x reference)
.LBB0_318:
	s_or_b64 exec, exec, s[6:7]
	s_lshl_b32 s6, s52, 7
	s_add_u32 s6, s71, s6
	s_waitcnt lgkmcnt(0)
	s_barrier
	s_addc_u32 s7, s72, 0
	v_lshlrev_b32_e32 v1, 5, v144
	global_load_dwordx4 v[136:139], v1, s[6:7] offset:16
	global_load_dwordx4 v[144:147], v1, s[6:7]
	s_waitcnt lgkmcnt(0)
	global_load_dwordx4 v[132:135], v1, s[6:7] offset:528
	global_load_dwordx4 v[140:143], v1, s[6:7] offset:512
	s_lshl_b32 s6, s55, 10
	s_add_i32 s6, s6, 0
	v_lshl_add_u32 v3, v3, 4, s6
	v_add_u32_e32 v1, 0x20000, v3
	ds_read_b128 v[154:157], v1
	s_lshl_b32 s8, s52, 6
	s_add_i32 s15, s8, 0
	s_movk_i32 s16, 0x210
	s_ashr_i32 s6, s54, 3
	s_waitcnt lgkmcnt(0)
	v_mov_b32_e32 v158, v155
	v_mov_b32_e32 v159, v156
	v_mov_b32_e32 v155, v157
	v_pk_add_f32 v[154:155], v[158:159], v[154:155]
	v_readlane_b32 s10, v254, 18
	v_add_f32_e32 v1, v154, v155
	v_fmamk_f32 v1, v1, 0x3b800000, v213
	v_rsq_f32_e32 v1, v1
	v_readlane_b32 s11, v254, 19
	v_readlane_b32 s48, v254, 41
	v_readlane_b32 s49, v254, 42
	v_mul_f32_e32 v160, v0, v1
	v_add_u32_e32 v0, 0x20100, v3
	ds_read_b128 v[154:157], v0
	v_pk_mul_f32 v[128:129], v[128:129], v[160:161] op_sel_hi:[1,0]
	v_pk_mul_f32 v[120:121], v[120:121], v[160:161] op_sel_hi:[1,0]
	v_pk_mul_f32 v[124:125], v[124:125], v[160:161] op_sel_hi:[1,0]
	v_pk_mul_f32 v[126:127], v[126:127], v[160:161] op_sel_hi:[1,0]
	s_waitcnt lgkmcnt(0)
	v_mov_b32_e32 v0, v155
	v_mov_b32_e32 v1, v156
	v_mov_b32_e32 v155, v157
	v_pk_add_f32 v[0:1], v[0:1], v[154:155]
	v_pk_mul_f32 v[116:117], v[116:117], v[160:161] op_sel_hi:[1,0]
	v_add_f32_e32 v0, v0, v1
	v_fmamk_f32 v0, v0, 0x3b800000, v213
	v_rsq_f32_e32 v0, v0
	v_pk_mul_f32 v[118:119], v[118:119], v[160:161] op_sel_hi:[1,0]
	v_pk_mul_f32 v[130:131], v[130:131], v[160:161] op_sel_hi:[1,0]
	v_pk_mul_f32 v[122:123], v[122:123], v[160:161] op_sel_hi:[1,0]
	v_mul_f32_e32 v158, v148, v0
	v_add_u32_e32 v0, 0x20200, v3
	ds_read_b128 v[154:157], v0
	v_pk_mul_f32 v[112:113], v[112:113], v[158:159] op_sel_hi:[1,0]
	v_pk_mul_f32 v[100:101], v[100:101], v[158:159] op_sel_hi:[1,0]
	v_pk_mul_f32 v[108:109], v[108:109], v[158:159] op_sel_hi:[1,0]
	v_pk_mul_f32 v[110:111], v[110:111], v[158:159] op_sel_hi:[1,0]
	s_waitcnt lgkmcnt(0)
	v_mov_b32_e32 v0, v155
	v_mov_b32_e32 v1, v156
	v_mov_b32_e32 v155, v157
	v_pk_add_f32 v[0:1], v[0:1], v[154:155]
	v_pk_mul_f32 v[92:93], v[92:93], v[158:159] op_sel_hi:[1,0]
	v_add_f32_e32 v0, v0, v1
	v_fmamk_f32 v0, v0, 0x3b800000, v213
	v_rsq_f32_e32 v0, v0
	v_pk_mul_f32 v[94:95], v[94:95], v[158:159] op_sel_hi:[1,0]
	v_pk_mul_f32 v[102:103], v[102:103], v[158:159] op_sel_hi:[1,0]
	v_pk_mul_f32 v[114:115], v[114:115], v[158:159] op_sel_hi:[1,0]
	v_mul_f32_e32 v156, v150, v0
	v_add_u32_e32 v0, 0x20300, v3
	ds_read_b128 v[174:177], v0
	v_pk_mul_f32 v[84:85], v[84:85], v[156:157] op_sel_hi:[1,0]
	v_pk_mul_f32 v[96:97], v[96:97], v[156:157] op_sel_hi:[1,0]
	v_pk_mul_f32 v[98:99], v[98:99], v[156:157] op_sel_hi:[1,0]
	v_pk_mul_f32 v[76:77], v[76:77], v[156:157] op_sel_hi:[1,0]
	s_waitcnt lgkmcnt(0)
	v_mov_b32_e32 v0, v175
	v_mov_b32_e32 v1, v176
	v_mov_b32_e32 v175, v177
	v_pk_add_f32 v[0:1], v[0:1], v[174:175]
	v_pk_mul_f32 v[78:79], v[78:79], v[156:157] op_sel_hi:[1,0]
	v_add_f32_e32 v0, v0, v1
	v_fmamk_f32 v0, v0, 0x3b800000, v213
	v_rsq_f32_e32 v0, v0
	v_pk_mul_f32 v[86:87], v[86:87], v[156:157] op_sel_hi:[1,0]
	v_mul_f32_e32 v154, v152, v0
	v_add_u32_e32 v0, 0x20800, v3
	ds_read_b128 v[174:177], v0
	s_waitcnt vmcnt(0)
	v_pk_mul_f32 v[128:129], v[144:145], v[128:129]
	v_pk_mul_f32 v[112:113], v[144:145], v[112:113]
	v_pk_mul_f32 v[120:121], v[140:141], v[120:121]
	v_pk_mul_f32 v[100:101], v[140:141], v[100:101]
	s_waitcnt lgkmcnt(0)
	v_mov_b32_e32 v0, v175
	v_mov_b32_e32 v1, v176
	v_mov_b32_e32 v175, v177
	v_pk_add_f32 v[0:1], v[0:1], v[174:175]
	v_pk_mul_f32 v[84:85], v[140:141], v[84:85]
	v_add_f32_e32 v0, v0, v1
	v_fmamk_f32 v0, v0, 0x3b800000, v213
	v_rsq_f32_e32 v0, v0
	v_pk_mul_f32 v[72:73], v[72:73], v[154:155] op_sel_hi:[1,0]
	v_pk_mul_f32 v[80:81], v[80:81], v[154:155] op_sel_hi:[1,0]
	v_pk_mul_f32 v[82:83], v[82:83], v[154:155] op_sel_hi:[1,0]
	v_mul_f32_e32 v152, v162, v0
	v_add_u32_e32 v0, 0x20900, v3
	ds_read_b128 v[174:177], v0
	v_pk_mul_f32 v[72:73], v[140:141], v[72:73]
	v_pk_mul_f32 v[68:69], v[68:69], v[154:155] op_sel_hi:[1,0]
	v_pk_mul_f32 v[70:71], v[70:71], v[154:155] op_sel_hi:[1,0]
	v_pk_mul_f32 v[102:103], v[142:143], v[102:103]
	s_waitcnt lgkmcnt(0)
	v_mov_b32_e32 v0, v175
	v_mov_b32_e32 v1, v176
	v_mov_b32_e32 v175, v177
	v_pk_add_f32 v[0:1], v[0:1], v[174:175]
	v_pk_mul_f32 v[86:87], v[142:143], v[86:87]
	v_add_f32_e32 v0, v0, v1
	v_fmamk_f32 v0, v0, 0x3b800000, v213
	v_rsq_f32_e32 v0, v0
	v_pk_mul_f32 v[130:131], v[146:147], v[130:131]
	v_pk_mul_f32 v[74:75], v[74:75], v[154:155] op_sel_hi:[1,0]
	v_pk_mul_f32 v[122:123], v[142:143], v[122:123]
	v_mul_f32_e32 v150, v164, v0
	v_add_u32_e32 v0, 0x20a00, v3
	ds_read_b128 v[162:165], v0
	v_pk_mul_f32 v[56:57], v[56:57], v[150:151] op_sel_hi:[1,0]
	v_pk_mul_f32 v[20:21], v[20:21], v[150:151] op_sel_hi:[1,0]
	v_pk_mul_f32 v[22:23], v[22:23], v[150:151] op_sel_hi:[1,0]
	v_pk_mul_f32 v[56:57], v[136:137], v[56:57]
	s_waitcnt lgkmcnt(0)
	v_mov_b32_e32 v0, v163
	v_mov_b32_e32 v1, v164
	v_mov_b32_e32 v163, v165
	v_pk_add_f32 v[0:1], v[0:1], v[162:163]
	v_pk_mul_f32 v[22:23], v[142:143], v[22:23]
	v_add_f32_e32 v0, v0, v1
	v_fmamk_f32 v0, v0, 0x3b800000, v213
	v_rsq_f32_e32 v0, v0
	v_pk_mul_f32 v[20:21], v[140:141], v[20:21]
	v_pk_mul_f32 v[16:17], v[16:17], v[150:151] op_sel_hi:[1,0]
	v_pk_mul_f32 v[18:19], v[18:19], v[150:151] op_sel_hi:[1,0]
	v_mul_f32_e32 v148, v166, v0
	v_add_u32_e32 v0, 0x20b00, v3
	ds_read_b128 v[162:165], v0
	v_mov_b32_e32 v3, v217
	v_pk_mul_f32 v[48:49], v[48:49], v[148:149] op_sel_hi:[1,0]
	v_and_b32_e32 v153, 48, v3
	s_waitcnt lgkmcnt(0)
	v_mov_b32_e32 v0, v163
	v_mov_b32_e32 v1, v164
	v_mov_b32_e32 v163, v165
	v_pk_add_f32 v[0:1], v[0:1], v[162:163]
	v_pk_mul_f32 v[162:163], v[138:139], v[126:127]
	v_pk_mul_f32 v[126:127], v[136:137], v[124:125]
	v_cvt_pk_bf16_f32 v124, v128, v129
	v_pk_mul_f32 v[128:129], v[134:135], v[118:119]
	v_pk_mul_f32 v[118:119], v[132:133], v[116:117]
	v_cvt_pk_bf16_f32 v116, v120, v121
	v_pk_mul_f32 v[120:121], v[138:139], v[110:111]
	v_pk_mul_f32 v[110:111], v[136:137], v[108:109]
	v_cvt_pk_bf16_f32 v108, v112, v113
	v_pk_mul_f32 v[112:113], v[134:135], v[94:95]
	v_pk_mul_f32 v[94:95], v[132:133], v[92:93]
	v_cvt_pk_bf16_f32 v92, v100, v101
	v_pk_mul_f32 v[100:101], v[104:105], v[156:157] op_sel_hi:[1,0]
	v_add_f32_e32 v0, v0, v1
	v_pk_mul_f32 v[100:101], v[144:145], v[100:101]
	v_fmamk_f32 v0, v0, 0x3b800000, v213
	v_pk_mul_f32 v[104:105], v[138:139], v[98:99]
	v_pk_mul_f32 v[98:99], v[136:137], v[96:97]
	v_cvt_pk_bf16_f32 v96, v100, v101
	v_pk_mul_f32 v[100:101], v[134:135], v[78:79]
	v_pk_mul_f32 v[78:79], v[132:133], v[76:77]
	v_cvt_pk_bf16_f32 v76, v84, v85
	v_pk_mul_f32 v[84:85], v[88:89], v[154:155] op_sel_hi:[1,0]
	v_pk_mul_f32 v[64:65], v[64:65], v[152:153] op_sel_hi:[1,0]
	v_pk_mul_f32 v[12:13], v[12:13], v[152:153] op_sel_hi:[1,0]
	v_pk_mul_f32 v[14:15], v[14:15], v[152:153] op_sel_hi:[1,0]
	v_rsq_f32_e32 v0, v0
	v_pk_mul_f32 v[84:85], v[144:145], v[84:85]
	v_pk_mul_f32 v[64:65], v[144:145], v[64:65]
	v_pk_mul_f32 v[4:5], v[4:5], v[152:153] op_sel_hi:[1,0]
	v_pk_mul_f32 v[6:7], v[6:7], v[152:153] op_sel_hi:[1,0]
	v_pk_mul_f32 v[14:15], v[142:143], v[14:15]
	v_pk_mul_f32 v[12:13], v[140:141], v[12:13]
	v_pk_mul_f32 v[8:9], v[8:9], v[152:153] op_sel_hi:[1,0]
	v_pk_mul_f32 v[10:11], v[10:11], v[152:153] op_sel_hi:[1,0]
	v_pk_mul_f32 v[88:89], v[138:139], v[82:83]
	v_pk_mul_f32 v[82:83], v[136:137], v[80:81]
	v_cvt_pk_bf16_f32 v80, v84, v85
	v_pk_mul_f32 v[84:85], v[134:135], v[70:71]
	v_pk_mul_f32 v[70:71], v[132:133], v[68:69]
	v_cvt_pk_bf16_f32 v68, v72, v73
	v_pk_mul_f32 v[72:73], v[138:139], v[6:7]
	v_pk_mul_f32 v[6:7], v[136:137], v[4:5]
	v_cvt_pk_bf16_f32 v4, v64, v65
	v_pk_mul_f32 v[64:65], v[134:135], v[10:11]
	v_pk_mul_f32 v[10:11], v[132:133], v[8:9]
	v_cvt_pk_bf16_f32 v8, v12, v13
	v_cvt_pk_bf16_f32 v9, v14, v15
	v_pk_mul_f32 v[12:13], v[60:61], v[150:151] op_sel_hi:[1,0]
	v_pk_mul_f32 v[14:15], v[62:63], v[150:151] op_sel_hi:[1,0]
	v_pk_mul_f32 v[12:13], v[144:145], v[12:13]
	v_pk_mul_f32 v[14:15], v[146:147], v[14:15]
	v_cvt_pk_bf16_f32 v12, v12, v13
	v_cvt_pk_bf16_f32 v13, v14, v15
	v_cvt_pk_bf16_f32 v14, v56, v57
	v_pk_mul_f32 v[56:57], v[134:135], v[18:19]
	v_pk_mul_f32 v[18:19], v[132:133], v[16:17]
	v_cvt_pk_bf16_f32 v16, v20, v21
	v_cvt_pk_bf16_f32 v17, v22, v23
	v_pk_mul_f32 v[20:21], v[52:53], v[148:149] op_sel_hi:[1,0]
	v_pk_mul_f32 v[22:23], v[54:55], v[148:149] op_sel_hi:[1,0]
	v_pk_mul_f32 v[28:29], v[28:29], v[148:149] op_sel_hi:[1,0]
	v_pk_mul_f32 v[30:31], v[30:31], v[148:149] op_sel_hi:[1,0]
	v_mul_f32_e32 v0, v168, v0
	v_pk_mul_f32 v[22:23], v[146:147], v[22:23]
	v_pk_mul_f32 v[20:21], v[144:145], v[20:21]
	v_pk_mul_f32 v[48:49], v[136:137], v[48:49]
	v_pk_mul_f32 v[30:31], v[142:143], v[30:31]
	v_pk_mul_f32 v[28:29], v[140:141], v[28:29]
	v_pk_mul_f32 v[24:25], v[24:25], v[148:149] op_sel_hi:[1,0]
	v_pk_mul_f32 v[26:27], v[26:27], v[148:149] op_sel_hi:[1,0]
	v_cvt_pk_bf16_f32 v20, v20, v21
	v_cvt_pk_bf16_f32 v21, v22, v23
	v_cvt_pk_bf16_f32 v22, v48, v49
	v_pk_mul_f32 v[48:49], v[134:135], v[26:27]
	v_pk_mul_f32 v[26:27], v[132:133], v[24:25]
	v_cvt_pk_bf16_f32 v24, v28, v29
	v_cvt_pk_bf16_f32 v25, v30, v31
	v_pk_mul_f32 v[28:29], v[44:45], v[0:1] op_sel_hi:[1,0]
	v_pk_mul_f32 v[30:31], v[46:47], v[0:1] op_sel_hi:[1,0]
	v_pk_mul_f32 v[40:41], v[40:41], v[0:1] op_sel_hi:[1,0]
	v_pk_mul_f32 v[42:43], v[42:43], v[0:1] op_sel_hi:[1,0]
	v_pk_mul_f32 v[36:37], v[36:37], v[0:1] op_sel_hi:[1,0]
	v_pk_mul_f32 v[38:39], v[38:39], v[0:1] op_sel_hi:[1,0]
	v_pk_mul_f32 v[32:33], v[32:33], v[0:1] op_sel_hi:[1,0]
	v_pk_mul_f32 v[0:1], v[34:35], v[0:1] op_sel_hi:[1,0]
	v_readfirstlane_b32 s7, v3
	v_pk_mul_f32 v[0:1], v[134:135], v[0:1]
	v_pk_mul_f32 v[34:35], v[132:133], v[32:33]
	s_ashr_i32 s8, s7, 2
	v_pk_mul_f32 v[36:37], v[140:141], v[36:37]
	v_cvt_pk_bf16_f32 v34, v34, v35
	v_cvt_pk_bf16_f32 v35, v0, v1
	v_bfi_b32 v1, -16, s8, v3
	v_cvt_pk_bf16_f32 v32, v36, v37
	v_mul_lo_u32 v36, v1, s16
	v_add3_u32 v175, 0, v36, v153
	v_ashrrev_i32_e32 v36, 3, v3
	v_pk_mul_f32 v[30:31], v[146:147], v[30:31]
	v_pk_mul_f32 v[28:29], v[144:145], v[28:29]
	v_pk_mul_f32 v[40:41], v[136:137], v[40:41]
	v_pk_mul_f32 v[38:39], v[142:143], v[38:39]
	v_ashrrev_i32_e32 v37, 31, v36
	v_cvt_pk_bf16_f32 v28, v28, v29
	v_cvt_pk_bf16_f32 v29, v30, v31
	v_cvt_pk_bf16_f32 v30, v40, v41
	v_cvt_pk_bf16_f32 v33, v38, v39
	v_and_b32_e32 v38, 15, v3
	v_bfe_u32 v39, v3, 4, 2
	v_lshlrev_b64 v[44:45], 13, v[36:37]
	v_lshlrev_b32_e32 v37, 3, v3
	v_lshlrev_b32_e32 v40, 4, v3
	v_bfe_u32 v3, v3, 2, 2
	v_mul_lo_u32 v36, v36, s16
	v_and_b32_e32 v180, 0x70, v40
	v_lshl_or_b32 v3, v39, 2, v3
	s_ashr_i32 s7, s6, 31
	s_lshl_b32 s8, s53, 8
	v_add3_u32 v170, s10, v36, v180
	v_mul_u32_u24_e32 v38, 0x210, v38
	v_add3_u32 v168, s11, v36, v180
	v_mul_u32_u24_e32 v3, 0x210, v3
	v_and_b32_e32 v36, 24, v37
	s_lshl_b64 s[12:13], s[6:7], 21
	s_ashr_i32 s9, s8, 31
	v_add3_u32 v174, s10, v153, v38
	v_add3_u32 v173, s11, v153, v38
	v_add3_u32 v169, s10, v3, v36
	v_add3_u32 v3, s11, v3, v36
	s_lshl_b64 s[10:11], s[6:7], 22
	s_add_u32 s12, s60, s12
	s_addc_u32 s13, s61, s13
	v_lshl_add_u64 v[44:45], s[12:13], 0, v[44:45]
	s_lshl_b32 s12, s0, 11
	s_ashr_i32 s13, s12, 31
	v_cvt_pk_bf16_f32 v93, v102, v103
	v_pk_mul_f32 v[102:103], v[106:107], v[156:157] op_sel_hi:[1,0]
	v_cvt_pk_bf16_f32 v77, v86, v87
	v_pk_mul_f32 v[86:87], v[90:91], v[154:155] op_sel_hi:[1,0]
	v_mul_lo_u32 v36, v149, s16
	v_lshl_add_u64 v[44:45], s[12:13], 1, v[44:45]
	s_lshl_b64 s[8:9], s[8:9], 1
	v_cvt_pk_bf16_f32 v125, v130, v131
	v_cvt_pk_bf16_f32 v126, v126, v127
	v_cvt_pk_bf16_f32 v127, v162, v163
	v_pk_mul_f32 v[114:115], v[146:147], v[114:115]
	v_pk_mul_f32 v[102:103], v[146:147], v[102:103]
	v_pk_mul_f32 v[86:87], v[146:147], v[86:87]
	v_pk_mul_f32 v[74:75], v[142:143], v[74:75]
	v_add3_u32 v176, s15, v151, v36
	v_lshl_add_u64 v[44:45], v[44:45], 0, s[8:9]
	v_cvt_pk_bf16_f32 v117, v122, v123
	v_cvt_pk_bf16_f32 v118, v118, v119
	v_cvt_pk_bf16_f32 v119, v128, v129
	v_cvt_pk_bf16_f32 v109, v114, v115
	v_cvt_pk_bf16_f32 v110, v110, v111
	v_cvt_pk_bf16_f32 v111, v120, v121
	v_cvt_pk_bf16_f32 v94, v94, v95
	v_cvt_pk_bf16_f32 v95, v112, v113
	v_cvt_pk_bf16_f32 v97, v102, v103
	v_cvt_pk_bf16_f32 v98, v98, v99
	v_cvt_pk_bf16_f32 v99, v104, v105
	v_cvt_pk_bf16_f32 v78, v78, v79
	v_cvt_pk_bf16_f32 v79, v100, v101
	v_cvt_pk_bf16_f32 v81, v86, v87
	v_cvt_pk_bf16_f32 v82, v82, v83
	v_cvt_pk_bf16_f32 v83, v88, v89
	v_cvt_pk_bf16_f32 v69, v74, v75
	v_cvt_pk_bf16_f32 v70, v70, v71
	v_cvt_pk_bf16_f32 v71, v84, v85
	s_waitcnt lgkmcnt(0)
	s_barrier
	ds_write_b128 v176, v[124:127]
	ds_write_b128 v176, v[116:119] offset:256
	ds_write_b128 v176, v[108:111] offset:8448
	ds_write_b128 v176, v[92:95] offset:8704
	ds_write_b128 v176, v[96:99] offset:16896
	ds_write_b128 v176, v[76:79] offset:17152
	ds_write_b128 v176, v[80:83] offset:25344
	ds_write_b128 v176, v[68:71] offset:25600
	v_lshl_add_u64 v[166:167], v[44:45], 0, v[180:181]
	s_mov_b32 s7, 0x80000
	v_pk_mul_f32 v[66:67], v[66:67], v[152:153] op_sel_hi:[1,0]
	v_pk_mul_f32 v[58:59], v[58:59], v[150:151] op_sel_hi:[1,0]
	v_pk_mul_f32 v[50:51], v[50:51], v[148:149] op_sel_hi:[1,0]
	v_pk_mul_f32 v[42:43], v[138:139], v[42:43]
	s_waitcnt lgkmcnt(0)
	s_barrier
	v_add_co_u32_e32 v164, vcc, s7, v166
	v_pk_mul_f32 v[66:67], v[146:147], v[66:67]
	v_pk_mul_f32 v[58:59], v[138:139], v[58:59]
	v_pk_mul_f32 v[50:51], v[138:139], v[50:51]
	v_cvt_pk_bf16_f32 v31, v42, v43
	v_lshlrev_b32_e32 v0, 3, v39
	ds_read_b128 v[124:127], v175
	ds_read_b128 v[120:123], v175 offset:64
	ds_read_b128 v[116:119], v175 offset:128
	ds_read_b128 v[108:111], v175 offset:192
	ds_read_b128 v[80:83], v175 offset:256
	ds_read_b128 v[76:79], v175 offset:320
	ds_read_b128 v[40:43], v175 offset:384
	ds_read_b128 v[36:39], v175 offset:448
	global_load_dwordx4 v[60:63], v[166:167], off
	v_addc_co_u32_e32 v165, vcc, 0, v167, vcc
	v_cvt_pk_bf16_f32 v5, v66, v67
	v_cvt_pk_bf16_f32 v6, v6, v7
	v_cvt_pk_bf16_f32 v7, v72, v73
	v_cvt_pk_bf16_f32 v10, v10, v11
	v_cvt_pk_bf16_f32 v11, v64, v65
	v_cvt_pk_bf16_f32 v15, v58, v59
	v_cvt_pk_bf16_f32 v18, v18, v19
	v_cvt_pk_bf16_f32 v19, v56, v57
	v_cvt_pk_bf16_f32 v23, v50, v51
	v_cvt_pk_bf16_f32 v26, v26, v27
	v_cvt_pk_bf16_f32 v27, v48, v49
	global_load_dwordx4 v[44:47], v[164:165], off
	global_load_dwordx4 v[64:67], v[166:167], off offset:128
	global_load_dwordx4 v[48:51], v[164:165], off offset:128
	global_load_dwordx4 v[68:71], v[166:167], off offset:256
	global_load_dwordx4 v[52:55], v[164:165], off offset:256
	global_load_dwordx4 v[72:75], v[166:167], off offset:384
	global_load_dwordx4 v[56:59], v[164:165], off offset:384
	s_mov_b32 s7, 0x100000
	v_add_co_u32_e32 v162, vcc, s7, v166
	s_waitcnt vmcnt(7)
	ds_write_b128 v170, v[60:63]
	s_waitcnt vmcnt(5)
	ds_write_b128 v170, v[64:67] offset:128
	s_waitcnt vmcnt(3)
	ds_write_b128 v170, v[68:71] offset:256
	s_waitcnt vmcnt(1)
	ds_write_b128 v170, v[72:75] offset:384
	v_addc_co_u32_e32 v163, vcc, 0, v167, vcc
	global_load_dwordx4 v[60:63], v[162:163], off
	global_load_dwordx4 v[64:67], v[162:163], off offset:128
	global_load_dwordx4 v[68:71], v[162:163], off offset:256
	global_load_dwordx4 v[72:75], v[162:163], off offset:384
	s_waitcnt lgkmcnt(0)
	s_barrier
	ds_read_b128 v[204:207], v174
	ds_read_b128 v[208:211], v174 offset:64
	ds_read_b128 v[218:221], v174 offset:128
	ds_read_b128 v[224:227], v174 offset:192
	ds_read_b128 v[228:231], v174 offset:256
	ds_read_b128 v[232:235], v174 offset:320
	ds_read_b128 v[236:239], v174 offset:384
	ds_read_b128 v[240:243], v174 offset:448
	s_waitcnt lgkmcnt(7)
	v_mfma_f32_16x16x32_bf16 v[84:87], v[204:207], v[124:127], 0
	ds_read_b128 v[204:207], v174 offset:8448
	s_waitcnt lgkmcnt(7)
	v_mfma_f32_16x16x32_bf16 v[84:87], v[208:211], v[120:123], v[84:87]
	ds_read_b128 v[208:211], v174 offset:8512
	s_mov_b32 s7, 0x180000
	v_add_co_u32_e32 v160, vcc, s7, v166
	s_nop 1
	s_waitcnt lgkmcnt(7)
	v_mfma_f32_16x16x32_bf16 v[84:87], v[218:221], v[116:119], v[84:87]
	ds_read_b128 v[218:221], v174 offset:8576
	v_addc_co_u32_e32 v161, vcc, 0, v167, vcc
	s_nop 1
	s_waitcnt lgkmcnt(7)
	v_mfma_f32_16x16x32_bf16 v[84:87], v[224:227], v[108:111], v[84:87]
	ds_read_b128 v[224:227], v174 offset:8640
	s_mov_b32 s7, 0xf149f2ca
	s_waitcnt lgkmcnt(7)
	v_mfma_f32_16x16x32_bf16 v[84:87], v[228:231], v[80:83], v[84:87]
	ds_read_b128 v[228:231], v174 offset:8704
	s_waitcnt lgkmcnt(7)
	v_mfma_f32_16x16x32_bf16 v[84:87], v[232:235], v[76:79], v[84:87]
	ds_read_b128 v[232:235], v174 offset:8768
	s_waitcnt lgkmcnt(7)
	v_mfma_f32_16x16x32_bf16 v[84:87], v[236:239], v[40:43], v[84:87]
	ds_read_b128 v[236:239], v174 offset:8832
	s_waitcnt lgkmcnt(7)
	v_mfma_f32_16x16x32_bf16 v[84:87], v[240:243], v[36:39], v[84:87]
	ds_read_b128 v[240:243], v174 offset:8896
	s_waitcnt lgkmcnt(7)
	v_mfma_f32_16x16x32_bf16 v[88:91], v[204:207], v[124:127], 0
	ds_read_b128 v[204:207], v174 offset:16896
	s_waitcnt lgkmcnt(7)
	v_mfma_f32_16x16x32_bf16 v[88:91], v[208:211], v[120:123], v[88:91]
	ds_read_b128 v[208:211], v174 offset:16960
	s_waitcnt lgkmcnt(7)
	v_mfma_f32_16x16x32_bf16 v[88:91], v[218:221], v[116:119], v[88:91]
	ds_read_b128 v[218:221], v174 offset:17024
	s_waitcnt lgkmcnt(7)
	v_mfma_f32_16x16x32_bf16 v[88:91], v[224:227], v[108:111], v[88:91]
	ds_read_b128 v[224:227], v174 offset:17088
	s_waitcnt lgkmcnt(7)
	v_mfma_f32_16x16x32_bf16 v[88:91], v[228:231], v[80:83], v[88:91]
	ds_read_b128 v[228:231], v174 offset:17152
	s_waitcnt lgkmcnt(7)
	v_mfma_f32_16x16x32_bf16 v[88:91], v[232:235], v[76:79], v[88:91]
	ds_read_b128 v[232:235], v174 offset:17216
	s_waitcnt lgkmcnt(7)
	v_mfma_f32_16x16x32_bf16 v[88:91], v[236:239], v[40:43], v[88:91]
	ds_read_b128 v[236:239], v174 offset:17280
	s_waitcnt lgkmcnt(7)
	v_mfma_f32_16x16x32_bf16 v[88:91], v[240:243], v[36:39], v[88:91]
	ds_read_b128 v[240:243], v174 offset:17344
	s_waitcnt lgkmcnt(7)
	v_mfma_f32_16x16x32_bf16 v[92:95], v[204:207], v[124:127], 0
	ds_read_b128 v[204:207], v174 offset:25344
	s_waitcnt lgkmcnt(7)
	v_mfma_f32_16x16x32_bf16 v[92:95], v[208:211], v[120:123], v[92:95]
	ds_read_b128 v[208:211], v174 offset:25408
	s_waitcnt lgkmcnt(7)
	v_mfma_f32_16x16x32_bf16 v[92:95], v[218:221], v[116:119], v[92:95]
	ds_read_b128 v[218:221], v174 offset:25472
	s_waitcnt lgkmcnt(7)
	v_mfma_f32_16x16x32_bf16 v[92:95], v[224:227], v[108:111], v[92:95]
	ds_read_b128 v[224:227], v174 offset:25536
	s_waitcnt lgkmcnt(7)
	v_mfma_f32_16x16x32_bf16 v[92:95], v[228:231], v[80:83], v[92:95]
	ds_read_b128 v[228:231], v174 offset:25600
	s_waitcnt lgkmcnt(7)
	v_mfma_f32_16x16x32_bf16 v[92:95], v[232:235], v[76:79], v[92:95]
	ds_read_b128 v[232:235], v174 offset:25664
	s_waitcnt lgkmcnt(7)
	v_mfma_f32_16x16x32_bf16 v[92:95], v[236:239], v[40:43], v[92:95]
	ds_read_b128 v[236:239], v174 offset:25728
	s_waitcnt lgkmcnt(7)
	v_mfma_f32_16x16x32_bf16 v[92:95], v[240:243], v[36:39], v[92:95]
	s_waitcnt lgkmcnt(6)
	v_mfma_f32_16x16x32_bf16 v[96:99], v[204:207], v[124:127], 0
	s_waitcnt lgkmcnt(5)
	v_mfma_f32_16x16x32_bf16 v[96:99], v[208:211], v[120:123], v[96:99]
	s_waitcnt lgkmcnt(4)
	v_mfma_f32_16x16x32_bf16 v[96:99], v[218:221], v[116:119], v[96:99]
	s_waitcnt lgkmcnt(3)
	v_mfma_f32_16x16x32_bf16 v[96:99], v[224:227], v[108:111], v[96:99]
	s_waitcnt lgkmcnt(2)
	v_mfma_f32_16x16x32_bf16 v[96:99], v[228:231], v[80:83], v[96:99]
	s_waitcnt lgkmcnt(1)
	v_mfma_f32_16x16x32_bf16 v[96:99], v[232:235], v[76:79], v[96:99]
	s_waitcnt lgkmcnt(0)
	v_mfma_f32_16x16x32_bf16 v[96:99], v[236:239], v[40:43], v[96:99]
	s_nop 7
	ds_read_b128 v[100:103], v174 offset:25792
	ds_write_b128 v168, v[44:47]
	ds_write_b128 v168, v[48:51] offset:128
	ds_write_b128 v168, v[52:55] offset:256
	s_waitcnt vmcnt(4)
	ds_write_b128 v168, v[56:59] offset:384
	global_load_dwordx4 v[44:47], v[160:161], off
	global_load_dwordx4 v[48:51], v[160:161], off offset:128
	global_load_dwordx4 v[52:55], v[160:161], off offset:256
	global_load_dwordx4 v[56:59], v[160:161], off offset:384
	s_waitcnt lgkmcnt(0)
	s_barrier
	s_waitcnt lgkmcnt(4)
	v_mfma_f32_16x16x32_bf16 v[96:99], v[100:103], v[36:39], v[96:99]
	ds_read_b128 v[204:207], v173
	ds_read_b128 v[208:211], v173 offset:64
	ds_read_b128 v[218:221], v173 offset:128
	ds_read_b128 v[224:227], v173 offset:192
	ds_read_b128 v[228:231], v173 offset:256
	ds_read_b128 v[232:235], v173 offset:320
	ds_read_b128 v[236:239], v173 offset:384
	ds_read_b128 v[240:243], v173 offset:448
	s_waitcnt lgkmcnt(7)
	v_mfma_f32_16x16x32_bf16 v[100:103], v[204:207], v[124:127], 0
	ds_read_b128 v[204:207], v173 offset:8448
	s_waitcnt lgkmcnt(7)
	v_mfma_f32_16x16x32_bf16 v[100:103], v[208:211], v[120:123], v[100:103]
	ds_read_b128 v[208:211], v173 offset:8512
	s_waitcnt lgkmcnt(7)
	v_mfma_f32_16x16x32_bf16 v[100:103], v[218:221], v[116:119], v[100:103]
	ds_read_b128 v[218:221], v173 offset:8576
	s_waitcnt lgkmcnt(7)
	v_mfma_f32_16x16x32_bf16 v[100:103], v[224:227], v[108:111], v[100:103]
	ds_read_b128 v[224:227], v173 offset:8640
	s_waitcnt lgkmcnt(7)
	v_mfma_f32_16x16x32_bf16 v[100:103], v[228:231], v[80:83], v[100:103]
	ds_read_b128 v[228:231], v173 offset:8704
	s_waitcnt lgkmcnt(7)
	v_mfma_f32_16x16x32_bf16 v[100:103], v[232:235], v[76:79], v[100:103]
	ds_read_b128 v[232:235], v173 offset:8768
	s_waitcnt lgkmcnt(7)
	v_mfma_f32_16x16x32_bf16 v[100:103], v[236:239], v[40:43], v[100:103]
	ds_read_b128 v[236:239], v173 offset:8832
	s_waitcnt lgkmcnt(7)
	v_mfma_f32_16x16x32_bf16 v[100:103], v[240:243], v[36:39], v[100:103]
	ds_read_b128 v[240:243], v173 offset:8896
	s_waitcnt lgkmcnt(7)
	v_mfma_f32_16x16x32_bf16 v[104:107], v[204:207], v[124:127], 0
	ds_read_b128 v[204:207], v173 offset:16896
	s_waitcnt lgkmcnt(7)
	v_mfma_f32_16x16x32_bf16 v[104:107], v[208:211], v[120:123], v[104:107]
	ds_read_b128 v[208:211], v173 offset:16960
	s_waitcnt lgkmcnt(7)
	v_mfma_f32_16x16x32_bf16 v[104:107], v[218:221], v[116:119], v[104:107]
	ds_read_b128 v[218:221], v173 offset:17024
	s_waitcnt lgkmcnt(7)
	v_mfma_f32_16x16x32_bf16 v[104:107], v[224:227], v[108:111], v[104:107]
	ds_read_b128 v[224:227], v173 offset:17088
	s_waitcnt lgkmcnt(7)
	v_mfma_f32_16x16x32_bf16 v[104:107], v[228:231], v[80:83], v[104:107]
	ds_read_b128 v[228:231], v173 offset:17152
	s_waitcnt lgkmcnt(7)
	v_mfma_f32_16x16x32_bf16 v[104:107], v[232:235], v[76:79], v[104:107]
	ds_read_b128 v[232:235], v173 offset:17216
	s_waitcnt lgkmcnt(7)
	v_mfma_f32_16x16x32_bf16 v[104:107], v[236:239], v[40:43], v[104:107]
	ds_read_b128 v[236:239], v173 offset:17280
	s_waitcnt lgkmcnt(7)
	v_mfma_f32_16x16x32_bf16 v[104:107], v[240:243], v[36:39], v[104:107]
	ds_read_b128 v[240:243], v173 offset:17344
	s_waitcnt lgkmcnt(7)
	v_mfma_f32_16x16x32_bf16 v[112:115], v[204:207], v[124:127], 0
	ds_read_b128 v[204:207], v173 offset:25344
	s_waitcnt lgkmcnt(7)
	v_mfma_f32_16x16x32_bf16 v[112:115], v[208:211], v[120:123], v[112:115]
	ds_read_b128 v[208:211], v173 offset:25408
	s_waitcnt lgkmcnt(7)
	v_mfma_f32_16x16x32_bf16 v[112:115], v[218:221], v[116:119], v[112:115]
	ds_read_b128 v[218:221], v173 offset:25472
	s_waitcnt lgkmcnt(7)
	v_mfma_f32_16x16x32_bf16 v[112:115], v[224:227], v[108:111], v[112:115]
	ds_read_b128 v[224:227], v173 offset:25536
	s_waitcnt lgkmcnt(7)
	v_mfma_f32_16x16x32_bf16 v[112:115], v[228:231], v[80:83], v[112:115]
	ds_read_b128 v[228:231], v173 offset:25600
	s_waitcnt lgkmcnt(7)
	v_mfma_f32_16x16x32_bf16 v[112:115], v[232:235], v[76:79], v[112:115]
	ds_read_b128 v[232:235], v173 offset:25664
	s_waitcnt lgkmcnt(7)
	v_mfma_f32_16x16x32_bf16 v[112:115], v[236:239], v[40:43], v[112:115]
	ds_read_b128 v[236:239], v173 offset:25728
	s_waitcnt lgkmcnt(7)
	v_mfma_f32_16x16x32_bf16 v[112:115], v[240:243], v[36:39], v[112:115]
	s_waitcnt lgkmcnt(6)
	v_mfma_f32_16x16x32_bf16 v[128:131], v[204:207], v[124:127], 0
	s_waitcnt lgkmcnt(5)
	v_mfma_f32_16x16x32_bf16 v[128:131], v[208:211], v[120:123], v[128:131]
	s_waitcnt lgkmcnt(4)
	v_mfma_f32_16x16x32_bf16 v[128:131], v[218:221], v[116:119], v[128:131]
	s_waitcnt lgkmcnt(3)
	v_mfma_f32_16x16x32_bf16 v[128:131], v[224:227], v[108:111], v[128:131]
	s_waitcnt lgkmcnt(2)
	v_mfma_f32_16x16x32_bf16 v[128:131], v[228:231], v[80:83], v[128:131]
	s_waitcnt lgkmcnt(1)
	v_mfma_f32_16x16x32_bf16 v[128:131], v[232:235], v[76:79], v[128:131]
	s_waitcnt lgkmcnt(0)
	v_mfma_f32_16x16x32_bf16 v[128:131], v[236:239], v[40:43], v[128:131]
	s_nop 7
	ds_read_b128 v[132:135], v173 offset:25792
	s_waitcnt vmcnt(7)
	ds_write_b128 v170, v[60:63]
	s_waitcnt vmcnt(6)
	ds_write_b128 v170, v[64:67] offset:128
	s_waitcnt vmcnt(5)
	ds_write_b128 v170, v[68:71] offset:256
	s_waitcnt vmcnt(4)
	ds_write_b128 v170, v[72:75] offset:384
	global_load_dwordx4 v[60:63], v[166:167], off offset:2048
	global_load_dwordx4 v[64:67], v[166:167], off offset:2176
	global_load_dwordx4 v[68:71], v[166:167], off offset:2304
	global_load_dwordx4 v[72:75], v[166:167], off offset:2432
	s_waitcnt lgkmcnt(0)
	s_barrier
	s_waitcnt lgkmcnt(4)
	v_mfma_f32_16x16x32_bf16 v[128:131], v[132:135], v[36:39], v[128:131]
	ds_read_b128 v[204:207], v174
	ds_read_b128 v[208:211], v174 offset:64
	ds_read_b128 v[218:221], v174 offset:128
	ds_read_b128 v[224:227], v174 offset:192
	ds_read_b128 v[228:231], v174 offset:256
	ds_read_b128 v[232:235], v174 offset:320
	ds_read_b128 v[236:239], v174 offset:384
	ds_read_b128 v[240:243], v174 offset:448
	s_waitcnt lgkmcnt(7)
	v_mfma_f32_16x16x32_bf16 v[132:135], v[204:207], v[124:127], 0
	ds_read_b128 v[204:207], v174 offset:8448
	s_waitcnt lgkmcnt(7)
	v_mfma_f32_16x16x32_bf16 v[132:135], v[208:211], v[120:123], v[132:135]
	ds_read_b128 v[208:211], v174 offset:8512
	s_waitcnt lgkmcnt(7)
	v_mfma_f32_16x16x32_bf16 v[132:135], v[218:221], v[116:119], v[132:135]
	ds_read_b128 v[218:221], v174 offset:8576
	s_waitcnt lgkmcnt(7)
	v_mfma_f32_16x16x32_bf16 v[132:135], v[224:227], v[108:111], v[132:135]
	ds_read_b128 v[224:227], v174 offset:8640
	s_waitcnt lgkmcnt(7)
	v_mfma_f32_16x16x32_bf16 v[132:135], v[228:231], v[80:83], v[132:135]
	ds_read_b128 v[228:231], v174 offset:8704
	s_waitcnt lgkmcnt(7)
	v_mfma_f32_16x16x32_bf16 v[132:135], v[232:235], v[76:79], v[132:135]
	ds_read_b128 v[232:235], v174 offset:8768
	s_waitcnt lgkmcnt(7)
	v_mfma_f32_16x16x32_bf16 v[132:135], v[236:239], v[40:43], v[132:135]
	ds_read_b128 v[236:239], v174 offset:8832
	s_waitcnt lgkmcnt(7)
	v_mfma_f32_16x16x32_bf16 v[132:135], v[240:243], v[36:39], v[132:135]
	ds_read_b128 v[240:243], v174 offset:8896
	s_waitcnt lgkmcnt(7)
	v_mfma_f32_16x16x32_bf16 v[136:139], v[204:207], v[124:127], 0
	ds_read_b128 v[204:207], v174 offset:16896
	s_waitcnt lgkmcnt(7)
	v_mfma_f32_16x16x32_bf16 v[136:139], v[208:211], v[120:123], v[136:139]
	ds_read_b128 v[208:211], v174 offset:16960
	s_waitcnt lgkmcnt(7)
	v_mfma_f32_16x16x32_bf16 v[136:139], v[218:221], v[116:119], v[136:139]
	ds_read_b128 v[218:221], v174 offset:17024
	s_waitcnt lgkmcnt(7)
	v_mfma_f32_16x16x32_bf16 v[136:139], v[224:227], v[108:111], v[136:139]
	ds_read_b128 v[224:227], v174 offset:17088
	s_waitcnt lgkmcnt(7)
	v_mfma_f32_16x16x32_bf16 v[136:139], v[228:231], v[80:83], v[136:139]
	ds_read_b128 v[228:231], v174 offset:17152
	s_waitcnt lgkmcnt(7)
	v_mfma_f32_16x16x32_bf16 v[136:139], v[232:235], v[76:79], v[136:139]
	ds_read_b128 v[232:235], v174 offset:17216
	s_waitcnt lgkmcnt(7)
	v_mfma_f32_16x16x32_bf16 v[136:139], v[236:239], v[40:43], v[136:139]
	ds_read_b128 v[236:239], v174 offset:17280
	s_waitcnt lgkmcnt(7)
	v_mfma_f32_16x16x32_bf16 v[136:139], v[240:243], v[36:39], v[136:139]
	ds_read_b128 v[240:243], v174 offset:17344
	s_waitcnt lgkmcnt(7)
	v_mfma_f32_16x16x32_bf16 v[140:143], v[204:207], v[124:127], 0
	ds_read_b128 v[204:207], v174 offset:25344
	s_waitcnt lgkmcnt(7)
	v_mfma_f32_16x16x32_bf16 v[140:143], v[208:211], v[120:123], v[140:143]
	ds_read_b128 v[208:211], v174 offset:25408
	s_waitcnt lgkmcnt(7)
	v_mfma_f32_16x16x32_bf16 v[140:143], v[218:221], v[116:119], v[140:143]
	ds_read_b128 v[218:221], v174 offset:25472
	s_waitcnt lgkmcnt(7)
	v_mfma_f32_16x16x32_bf16 v[140:143], v[224:227], v[108:111], v[140:143]
	ds_read_b128 v[224:227], v174 offset:25536
	s_waitcnt lgkmcnt(7)
	v_mfma_f32_16x16x32_bf16 v[140:143], v[228:231], v[80:83], v[140:143]
	ds_read_b128 v[228:231], v174 offset:25600
	s_waitcnt lgkmcnt(7)
	v_mfma_f32_16x16x32_bf16 v[140:143], v[232:235], v[76:79], v[140:143]
	ds_read_b128 v[232:235], v174 offset:25664
	s_waitcnt lgkmcnt(7)
	v_mfma_f32_16x16x32_bf16 v[140:143], v[236:239], v[40:43], v[140:143]
	ds_read_b128 v[236:239], v174 offset:25728
	s_waitcnt lgkmcnt(7)
	v_mfma_f32_16x16x32_bf16 v[140:143], v[240:243], v[36:39], v[140:143]
	s_waitcnt lgkmcnt(6)
	v_mfma_f32_16x16x32_bf16 v[144:147], v[204:207], v[124:127], 0
	s_waitcnt lgkmcnt(5)
	v_mfma_f32_16x16x32_bf16 v[144:147], v[208:211], v[120:123], v[144:147]
	s_waitcnt lgkmcnt(4)
	v_mfma_f32_16x16x32_bf16 v[144:147], v[218:221], v[116:119], v[144:147]
	s_waitcnt lgkmcnt(3)
	v_mfma_f32_16x16x32_bf16 v[144:147], v[224:227], v[108:111], v[144:147]
	s_waitcnt lgkmcnt(2)
	v_mfma_f32_16x16x32_bf16 v[144:147], v[228:231], v[80:83], v[144:147]
	s_waitcnt lgkmcnt(1)
	v_mfma_f32_16x16x32_bf16 v[144:147], v[232:235], v[76:79], v[144:147]
	s_waitcnt lgkmcnt(0)
	v_mfma_f32_16x16x32_bf16 v[144:147], v[236:239], v[40:43], v[144:147]
	s_nop 7
	ds_read_b128 v[148:151], v174 offset:25792
	s_waitcnt vmcnt(7)
	ds_write_b128 v168, v[44:47]
	s_waitcnt vmcnt(6)
	ds_write_b128 v168, v[48:51] offset:128
	s_waitcnt vmcnt(5)
	ds_write_b128 v168, v[52:55] offset:256
	s_waitcnt vmcnt(4)
	ds_write_b128 v168, v[56:59] offset:384
	global_load_dwordx4 v[44:47], v[164:165], off offset:2048
	global_load_dwordx4 v[48:51], v[164:165], off offset:2176
	global_load_dwordx4 v[52:55], v[164:165], off offset:2304
	global_load_dwordx4 v[56:59], v[164:165], off offset:2432
	s_waitcnt lgkmcnt(0)
	s_barrier
	s_waitcnt lgkmcnt(4)
	v_mfma_f32_16x16x32_bf16 v[144:147], v[148:151], v[36:39], v[144:147]
	ds_read_b128 v[204:207], v173
	ds_read_b128 v[208:211], v173 offset:64
	ds_read_b128 v[218:221], v173 offset:128
	ds_read_b128 v[224:227], v173 offset:192
	ds_read_b128 v[228:231], v173 offset:256
	ds_read_b128 v[232:235], v173 offset:320
	ds_read_b128 v[236:239], v173 offset:384
	ds_read_b128 v[240:243], v173 offset:448
	s_waitcnt lgkmcnt(7)
	v_mfma_f32_16x16x32_bf16 v[148:151], v[204:207], v[124:127], 0
	ds_read_b128 v[204:207], v173 offset:8448
	s_waitcnt lgkmcnt(7)
	v_mfma_f32_16x16x32_bf16 v[148:151], v[208:211], v[120:123], v[148:151]
	ds_read_b128 v[208:211], v173 offset:8512
	s_waitcnt lgkmcnt(7)
	v_mfma_f32_16x16x32_bf16 v[148:151], v[218:221], v[116:119], v[148:151]
	ds_read_b128 v[218:221], v173 offset:8576
	s_waitcnt lgkmcnt(7)
	v_mfma_f32_16x16x32_bf16 v[148:151], v[224:227], v[108:111], v[148:151]
	ds_read_b128 v[224:227], v173 offset:8640
	s_waitcnt lgkmcnt(7)
	v_mfma_f32_16x16x32_bf16 v[148:151], v[228:231], v[80:83], v[148:151]
	ds_read_b128 v[228:231], v173 offset:8704
	s_waitcnt lgkmcnt(7)
	v_mfma_f32_16x16x32_bf16 v[148:151], v[232:235], v[76:79], v[148:151]
	ds_read_b128 v[232:235], v173 offset:8768
	s_waitcnt lgkmcnt(7)
	v_mfma_f32_16x16x32_bf16 v[148:151], v[236:239], v[40:43], v[148:151]
	ds_read_b128 v[236:239], v173 offset:8832
	s_waitcnt lgkmcnt(7)
	v_mfma_f32_16x16x32_bf16 v[148:151], v[240:243], v[36:39], v[148:151]
	ds_read_b128 v[240:243], v173 offset:8896
	s_waitcnt lgkmcnt(7)
	v_mfma_f32_16x16x32_bf16 v[152:155], v[204:207], v[124:127], 0
	ds_read_b128 v[204:207], v173 offset:16896
	s_waitcnt lgkmcnt(7)
	v_mfma_f32_16x16x32_bf16 v[152:155], v[208:211], v[120:123], v[152:155]
	ds_read_b128 v[208:211], v173 offset:16960
	s_waitcnt lgkmcnt(7)
	v_mfma_f32_16x16x32_bf16 v[152:155], v[218:221], v[116:119], v[152:155]
	ds_read_b128 v[218:221], v173 offset:17024
	s_waitcnt lgkmcnt(7)
	v_mfma_f32_16x16x32_bf16 v[152:155], v[224:227], v[108:111], v[152:155]
	ds_read_b128 v[224:227], v173 offset:17088
	s_waitcnt lgkmcnt(7)
	v_mfma_f32_16x16x32_bf16 v[152:155], v[228:231], v[80:83], v[152:155]
	ds_read_b128 v[228:231], v173 offset:17152
	s_waitcnt lgkmcnt(7)
	v_mfma_f32_16x16x32_bf16 v[152:155], v[232:235], v[76:79], v[152:155]
	ds_read_b128 v[232:235], v173 offset:17216
	s_waitcnt lgkmcnt(7)
	v_mfma_f32_16x16x32_bf16 v[152:155], v[236:239], v[40:43], v[152:155]
	ds_read_b128 v[236:239], v173 offset:17280
	s_waitcnt lgkmcnt(7)
	v_mfma_f32_16x16x32_bf16 v[152:155], v[240:243], v[36:39], v[152:155]
	ds_read_b128 v[240:243], v173 offset:17344
	s_waitcnt lgkmcnt(7)
	v_mfma_f32_16x16x32_bf16 v[156:159], v[204:207], v[124:127], 0
	ds_read_b128 v[204:207], v173 offset:25344
	s_waitcnt lgkmcnt(7)
	v_mfma_f32_16x16x32_bf16 v[156:159], v[208:211], v[120:123], v[156:159]
	ds_read_b128 v[208:211], v173 offset:25408
	s_waitcnt lgkmcnt(7)
	v_mfma_f32_16x16x32_bf16 v[156:159], v[218:221], v[116:119], v[156:159]
	ds_read_b128 v[218:221], v173 offset:25472
	s_waitcnt lgkmcnt(7)
	v_mfma_f32_16x16x32_bf16 v[156:159], v[224:227], v[108:111], v[156:159]
	ds_read_b128 v[224:227], v173 offset:25536
	s_waitcnt lgkmcnt(7)
	v_mfma_f32_16x16x32_bf16 v[156:159], v[228:231], v[80:83], v[156:159]
	ds_read_b128 v[228:231], v173 offset:25600
	s_waitcnt lgkmcnt(7)
	v_mfma_f32_16x16x32_bf16 v[156:159], v[232:235], v[76:79], v[156:159]
	ds_read_b128 v[232:235], v173 offset:25664
	s_waitcnt lgkmcnt(7)
	v_mfma_f32_16x16x32_bf16 v[156:159], v[236:239], v[40:43], v[156:159]
	ds_read_b128 v[236:239], v173 offset:25728
	s_waitcnt lgkmcnt(7)
	v_mfma_f32_16x16x32_bf16 v[156:159], v[240:243], v[36:39], v[156:159]
	ds_read_b128 v[240:243], v173 offset:25792
	s_waitcnt lgkmcnt(7)
	v_mfma_f32_16x16x32_bf16 v[124:127], v[204:207], v[124:127], 0
	s_waitcnt lgkmcnt(6)
	v_mfma_f32_16x16x32_bf16 v[120:123], v[208:211], v[120:123], v[124:127]
	s_nop 4
	s_waitcnt lgkmcnt(5)
	v_mfma_f32_16x16x32_bf16 v[116:119], v[218:221], v[116:119], v[120:123]
	s_nop 2
	s_waitcnt lgkmcnt(4)
	v_mfma_f32_16x16x32_bf16 v[108:111], v[224:227], v[108:111], v[116:119]
	s_nop 2
	s_waitcnt lgkmcnt(3)
	v_mfma_f32_16x16x32_bf16 v[80:83], v[228:231], v[80:83], v[108:111]
	s_nop 2
	s_waitcnt lgkmcnt(2)
	v_mfma_f32_16x16x32_bf16 v[76:79], v[232:235], v[76:79], v[80:83]
	s_nop 2
	s_waitcnt lgkmcnt(1)
	v_mfma_f32_16x16x32_bf16 v[40:43], v[236:239], v[40:43], v[76:79]
	s_nop 2
	s_waitcnt vmcnt(7)
	ds_write_b128 v170, v[60:63]
	s_waitcnt vmcnt(6)
	ds_write_b128 v170, v[64:67] offset:128
	s_waitcnt vmcnt(5)
	ds_write_b128 v170, v[68:71] offset:256
	s_waitcnt vmcnt(4)
	ds_write_b128 v170, v[72:75] offset:384
	global_load_dwordx4 v[60:63], v[162:163], off offset:2048
	global_load_dwordx4 v[64:67], v[162:163], off offset:2176
	global_load_dwordx4 v[68:71], v[162:163], off offset:2304
	global_load_dwordx4 v[72:75], v[162:163], off offset:2432
	s_waitcnt lgkmcnt(4)
	v_mfma_f32_16x16x32_bf16 v[36:39], v[240:243], v[36:39], v[40:43]
	s_nop 7
	s_nop 2
	v_max_f32_e32 v40, v87, v87
	v_max_f32_e32 v41, v86, v86
	v_max_f32_e32 v40, v41, v40
	v_max_f32_e32 v41, v91, v91
	v_max_f32_e32 v42, v90, v90
	v_max_f32_e32 v41, v42, v41
	v_max3_f32 v40, v84, v85, v40
	v_max3_f32 v41, v88, v89, v41
	v_max3_f32 v40, v40, s7, v41
	v_max_f32_e32 v41, v95, v95
	v_max_f32_e32 v42, v94, v94
	v_max_f32_e32 v41, v42, v41
	v_max_f32_e32 v42, v99, v99
	v_max_f32_e32 v43, v98, v98
	v_max_f32_e32 v42, v43, v42
	v_max3_f32 v41, v92, v93, v41
	v_max3_f32 v42, v96, v97, v42
	v_max3_f32 v40, v40, v41, v42
	v_max_f32_e32 v41, v103, v103
	v_max_f32_e32 v42, v102, v102
	v_max_f32_e32 v41, v42, v41
	v_max_f32_e32 v42, v107, v107
	v_max_f32_e32 v43, v106, v106
	v_max_f32_e32 v42, v43, v42
	v_max3_f32 v41, v100, v101, v41
	v_max3_f32 v42, v104, v105, v42
	v_max3_f32 v40, v40, v41, v42
	v_max_f32_e32 v41, v115, v115
	v_max_f32_e32 v42, v114, v114
	v_max_f32_e32 v41, v42, v41
	v_max_f32_e32 v42, v131, v131
	v_max_f32_e32 v43, v130, v130
	v_max_f32_e32 v42, v43, v42
	v_max3_f32 v41, v112, v113, v41
	v_max3_f32 v42, v128, v129, v42
	v_max3_f32 v40, v40, v41, v42
	v_max_f32_e32 v41, v135, v135
	v_max_f32_e32 v42, v134, v134
	v_max_f32_e32 v41, v42, v41
	v_max_f32_e32 v42, v139, v139
	v_max_f32_e32 v43, v138, v138
	v_max_f32_e32 v42, v43, v42
	v_max3_f32 v41, v132, v133, v41
	v_max3_f32 v42, v136, v137, v42
	v_max3_f32 v40, v40, v41, v42
	v_max_f32_e32 v41, v143, v143
	v_max_f32_e32 v42, v142, v142
	v_max_f32_e32 v41, v42, v41
	v_max_f32_e32 v42, v147, v147
	v_max_f32_e32 v43, v146, v146
	v_max_f32_e32 v42, v43, v42
	v_max3_f32 v41, v140, v141, v41
	v_max3_f32 v42, v144, v145, v42
	v_max3_f32 v40, v40, v41, v42
	v_max_f32_e32 v41, v151, v151
	v_max_f32_e32 v42, v150, v150
	v_max_f32_e32 v41, v42, v41
	v_max_f32_e32 v42, v155, v155
	v_max_f32_e32 v43, v154, v154
	v_max_f32_e32 v42, v43, v42
	v_max3_f32 v41, v148, v149, v41
	v_max3_f32 v42, v152, v153, v42
	v_max3_f32 v40, v40, v41, v42
	v_max_f32_e32 v41, v159, v159
	v_max_f32_e32 v42, v158, v158
	v_max_f32_e32 v41, v42, v41
	v_max_f32_e32 v42, v39, v39
	v_max_f32_e32 v43, v38, v38
	v_max_f32_e32 v42, v43, v42
	v_max3_f32 v41, v156, v157, v41
	v_max3_f32 v42, v36, v37, v42
	v_max3_f32 v40, v40, v41, v42
	ds_bpermute_b32 v41, v171, v40
	s_waitcnt lgkmcnt(0)
	s_barrier
	s_waitcnt lgkmcnt(0)
	v_max_f32_e32 v41, v41, v41
	v_max_f32_e32 v40, v40, v41
	ds_bpermute_b32 v41, v172, v40
	s_waitcnt lgkmcnt(0)
	v_max_f32_e32 v41, v41, v41
	v_max_f32_e32 v182, v40, v41
	v_sub_f32_e32 v40, v84, v182
	v_mul_f32_e32 v40, 0x3d800000, v40
	v_sub_f32_e32 v41, v85, v182
	v_mul_f32_e32 v40, 0x3fb8aa3b, v40
	v_mul_f32_e32 v41, 0x3d800000, v41
	v_exp_f32_e32 v40, v40
	v_mul_f32_e32 v41, 0x3fb8aa3b, v41
	v_exp_f32_e32 v41, v41
	v_sub_f32_e32 v85, v96, v182
	v_add_f32_e32 v42, 0, v40
	v_mul_f32_e32 v85, 0x3d800000, v85
	v_add_f32_e32 v43, v41, v42
	v_sub_f32_e32 v42, v86, v182
	v_mul_f32_e32 v42, 0x3d800000, v42
	v_mul_f32_e32 v42, 0x3fb8aa3b, v42
	v_exp_f32_e32 v42, v42
	v_mul_f32_e32 v85, 0x3fb8aa3b, v85
	v_sub_f32_e32 v36, v36, v182
	v_mul_f32_e32 v36, 0x3d800000, v36
	v_add_f32_e32 v76, v42, v43
	v_sub_f32_e32 v43, v87, v182
	v_mul_f32_e32 v43, 0x3d800000, v43
	v_mul_f32_e32 v43, 0x3fb8aa3b, v43
	v_exp_f32_e32 v43, v43
	v_mul_f32_e32 v36, 0x3fb8aa3b, v36
	v_exp_f32_e32 v195, v36
	v_sub_f32_e32 v37, v37, v182
	v_add_f32_e32 v77, v43, v76
	v_sub_f32_e32 v76, v88, v182
	v_mul_f32_e32 v76, 0x3d800000, v76
	v_mul_f32_e32 v76, 0x3fb8aa3b, v76
	v_exp_f32_e32 v76, v76
	v_exp_f32_e32 v88, v85
	v_sub_f32_e32 v85, v97, v182
	v_mul_f32_e32 v85, 0x3d800000, v85
	v_add_f32_e32 v78, v76, v77
	v_sub_f32_e32 v77, v89, v182
	v_mul_f32_e32 v77, 0x3d800000, v77
	v_mul_f32_e32 v77, 0x3fb8aa3b, v77
	v_exp_f32_e32 v77, v77
	v_mul_f32_e32 v85, 0x3fb8aa3b, v85
	v_exp_f32_e32 v89, v85
	v_sub_f32_e32 v85, v98, v182
	v_add_f32_e32 v79, v77, v78
	v_sub_f32_e32 v78, v90, v182
	v_mul_f32_e32 v78, 0x3d800000, v78
	v_mul_f32_e32 v78, 0x3fb8aa3b, v78
	v_mul_f32_e32 v85, 0x3d800000, v85
	v_exp_f32_e32 v78, v78
	v_mul_f32_e32 v85, 0x3fb8aa3b, v85
	v_exp_f32_e32 v90, v85
	v_sub_f32_e32 v85, v99, v182
	v_mul_f32_e32 v85, 0x3d800000, v85
	v_mul_f32_e32 v85, 0x3fb8aa3b, v85
	v_add_f32_e32 v80, v78, v79
	v_sub_f32_e32 v79, v91, v182
	v_exp_f32_e32 v91, v85
	v_sub_f32_e32 v85, v100, v182
	v_mul_f32_e32 v85, 0x3d800000, v85
	v_mul_f32_e32 v85, 0x3fb8aa3b, v85
	v_exp_f32_e32 v96, v85
	v_sub_f32_e32 v85, v101, v182
	v_mul_f32_e32 v85, 0x3d800000, v85
	v_mul_f32_e32 v85, 0x3fb8aa3b, v85
	v_exp_f32_e32 v97, v85
	v_sub_f32_e32 v85, v102, v182
	v_mul_f32_e32 v85, 0x3d800000, v85
	v_mul_f32_e32 v85, 0x3fb8aa3b, v85
	v_exp_f32_e32 v98, v85
	v_sub_f32_e32 v85, v103, v182
	v_mul_f32_e32 v85, 0x3d800000, v85
	v_mul_f32_e32 v85, 0x3fb8aa3b, v85
	v_exp_f32_e32 v99, v85
	v_sub_f32_e32 v85, v104, v182
	v_mul_f32_e32 v85, 0x3d800000, v85
	v_mul_f32_e32 v85, 0x3fb8aa3b, v85
	v_exp_f32_e32 v100, v85
	v_sub_f32_e32 v85, v105, v182
	v_mul_f32_e32 v85, 0x3d800000, v85
	v_mul_f32_e32 v85, 0x3fb8aa3b, v85
	v_exp_f32_e32 v101, v85
	v_sub_f32_e32 v85, v106, v182
	v_mul_f32_e32 v85, 0x3d800000, v85
	v_mul_f32_e32 v85, 0x3fb8aa3b, v85
	v_exp_f32_e32 v102, v85
	v_sub_f32_e32 v85, v107, v182
	v_mul_f32_e32 v85, 0x3d800000, v85
	v_mul_f32_e32 v85, 0x3fb8aa3b, v85
	v_exp_f32_e32 v103, v85
	v_sub_f32_e32 v85, v112, v182
	v_mul_f32_e32 v85, 0x3d800000, v85
	v_mul_f32_e32 v85, 0x3fb8aa3b, v85
	v_exp_f32_e32 v104, v85
	v_sub_f32_e32 v85, v113, v182
	v_mul_f32_e32 v85, 0x3d800000, v85
	v_mul_f32_e32 v85, 0x3fb8aa3b, v85
	v_exp_f32_e32 v105, v85
	v_sub_f32_e32 v85, v114, v182
	v_mul_f32_e32 v85, 0x3d800000, v85
	v_mul_f32_e32 v85, 0x3fb8aa3b, v85
	v_exp_f32_e32 v106, v85
	v_sub_f32_e32 v85, v115, v182
	v_mul_f32_e32 v85, 0x3d800000, v85
	v_mul_f32_e32 v85, 0x3fb8aa3b, v85
	v_exp_f32_e32 v107, v85
	v_sub_f32_e32 v85, v128, v182
	v_mul_f32_e32 v85, 0x3d800000, v85
	v_mul_f32_e32 v85, 0x3fb8aa3b, v85
	v_exp_f32_e32 v108, v85
	v_sub_f32_e32 v85, v129, v182
	v_mul_f32_e32 v85, 0x3d800000, v85
	v_mul_f32_e32 v85, 0x3fb8aa3b, v85
	v_exp_f32_e32 v109, v85
	v_sub_f32_e32 v85, v130, v182
	v_mul_f32_e32 v85, 0x3d800000, v85
	v_mul_f32_e32 v85, 0x3fb8aa3b, v85
	v_exp_f32_e32 v110, v85
	v_sub_f32_e32 v85, v131, v182
	v_mul_f32_e32 v85, 0x3d800000, v85
	v_mul_f32_e32 v85, 0x3fb8aa3b, v85
	v_exp_f32_e32 v111, v85
	v_sub_f32_e32 v85, v132, v182
	v_mul_f32_e32 v85, 0x3d800000, v85
	v_mul_f32_e32 v85, 0x3fb8aa3b, v85
	v_exp_f32_e32 v112, v85
	v_sub_f32_e32 v85, v133, v182
	v_mul_f32_e32 v85, 0x3d800000, v85
	v_mul_f32_e32 v85, 0x3fb8aa3b, v85
	v_mul_f32_e32 v79, 0x3d800000, v79
	v_exp_f32_e32 v113, v85
	v_sub_f32_e32 v85, v134, v182
	v_mul_f32_e32 v79, 0x3fb8aa3b, v79
	v_mul_f32_e32 v85, 0x3d800000, v85
	v_exp_f32_e32 v79, v79
	v_mul_f32_e32 v85, 0x3fb8aa3b, v85
	v_exp_f32_e32 v114, v85
	v_sub_f32_e32 v85, v135, v182
	v_mul_f32_e32 v85, 0x3d800000, v85
	v_mul_f32_e32 v85, 0x3fb8aa3b, v85
	v_add_f32_e32 v81, v79, v80
	v_sub_f32_e32 v80, v92, v182
	v_exp_f32_e32 v115, v85
	v_sub_f32_e32 v85, v136, v182
	v_mul_f32_e32 v80, 0x3d800000, v80
	v_mul_f32_e32 v85, 0x3d800000, v85
	v_mul_f32_e32 v80, 0x3fb8aa3b, v80
	v_mul_f32_e32 v85, 0x3fb8aa3b, v85
	v_exp_f32_e32 v80, v80
	v_exp_f32_e32 v116, v85
	v_sub_f32_e32 v85, v137, v182
	v_mul_f32_e32 v85, 0x3d800000, v85
	v_mul_f32_e32 v85, 0x3fb8aa3b, v85
	v_exp_f32_e32 v117, v85
	v_sub_f32_e32 v85, v138, v182
	v_add_f32_e32 v82, v80, v81
	v_sub_f32_e32 v81, v93, v182
	v_mul_f32_e32 v85, 0x3d800000, v85
	v_mul_f32_e32 v81, 0x3d800000, v81
	v_mul_f32_e32 v85, 0x3fb8aa3b, v85
	v_mul_f32_e32 v81, 0x3fb8aa3b, v81
	v_exp_f32_e32 v118, v85
	v_sub_f32_e32 v85, v139, v182
	v_exp_f32_e32 v81, v81
	v_mul_f32_e32 v85, 0x3d800000, v85
	v_mul_f32_e32 v85, 0x3fb8aa3b, v85
	v_exp_f32_e32 v119, v85
	v_sub_f32_e32 v85, v140, v182
	v_mul_f32_e32 v85, 0x3d800000, v85
	v_add_f32_e32 v83, v81, v82
	v_sub_f32_e32 v82, v94, v182
	v_mul_f32_e32 v85, 0x3fb8aa3b, v85
	v_mul_f32_e32 v82, 0x3d800000, v82
	v_exp_f32_e32 v120, v85
	v_sub_f32_e32 v85, v141, v182
	v_mul_f32_e32 v82, 0x3fb8aa3b, v82
	v_mul_f32_e32 v85, 0x3d800000, v85
	v_exp_f32_e32 v82, v82
	v_mul_f32_e32 v85, 0x3fb8aa3b, v85
	v_exp_f32_e32 v121, v85
	v_sub_f32_e32 v85, v142, v182
	v_mul_f32_e32 v85, 0x3d800000, v85
	v_mul_f32_e32 v85, 0x3fb8aa3b, v85
	v_add_f32_e32 v84, v82, v83
	v_sub_f32_e32 v83, v95, v182
	v_exp_f32_e32 v122, v85
	v_sub_f32_e32 v85, v143, v182
	v_mul_f32_e32 v83, 0x3d800000, v83
	v_mul_f32_e32 v85, 0x3d800000, v85
	v_mul_f32_e32 v83, 0x3fb8aa3b, v83
	v_mul_f32_e32 v85, 0x3fb8aa3b, v85
	v_exp_f32_e32 v83, v83
	v_exp_f32_e32 v123, v85
	v_sub_f32_e32 v85, v144, v182
	v_mul_f32_e32 v85, 0x3d800000, v85
	v_mul_f32_e32 v85, 0x3fb8aa3b, v85
	v_exp_f32_e32 v124, v85
	v_sub_f32_e32 v85, v145, v182
	v_add_f32_e32 v84, v83, v84
	v_mul_f32_e32 v85, 0x3d800000, v85
	v_add_f32_e32 v84, v88, v84
	v_mul_f32_e32 v85, 0x3fb8aa3b, v85
	v_add_f32_e32 v84, v89, v84
	v_exp_f32_e32 v125, v85
	v_sub_f32_e32 v85, v146, v182
	v_add_f32_e32 v84, v90, v84
	v_mul_f32_e32 v85, 0x3d800000, v85
	v_add_f32_e32 v84, v91, v84
	v_mul_f32_e32 v85, 0x3fb8aa3b, v85
	v_add_f32_e32 v84, v96, v84
	v_exp_f32_e32 v126, v85
	v_sub_f32_e32 v85, v147, v182
	v_add_f32_e32 v84, v97, v84
	v_mul_f32_e32 v85, 0x3d800000, v85
	v_add_f32_e32 v84, v98, v84
	v_mul_f32_e32 v85, 0x3fb8aa3b, v85
	v_add_f32_e32 v84, v99, v84
	v_exp_f32_e32 v127, v85
	v_sub_f32_e32 v85, v148, v182
	v_add_f32_e32 v84, v100, v84
	v_mul_f32_e32 v85, 0x3d800000, v85
	v_add_f32_e32 v84, v101, v84
	v_mul_f32_e32 v85, 0x3fb8aa3b, v85
	v_add_f32_e32 v84, v102, v84
	v_exp_f32_e32 v177, v85
	v_sub_f32_e32 v85, v149, v182
	v_add_f32_e32 v84, v103, v84
	v_mul_f32_e32 v85, 0x3d800000, v85
	v_add_f32_e32 v84, v104, v84
	v_mul_f32_e32 v85, 0x3fb8aa3b, v85
	v_add_f32_e32 v84, v105, v84
	v_exp_f32_e32 v178, v85
	v_sub_f32_e32 v85, v150, v182
	v_add_f32_e32 v84, v106, v84
	v_mul_f32_e32 v85, 0x3d800000, v85
	v_add_f32_e32 v84, v107, v84
	v_mul_f32_e32 v85, 0x3fb8aa3b, v85
	v_add_f32_e32 v84, v108, v84
	v_exp_f32_e32 v179, v85
	v_sub_f32_e32 v85, v151, v182
	v_add_f32_e32 v84, v109, v84
	v_mul_f32_e32 v85, 0x3d800000, v85
	v_add_f32_e32 v84, v110, v84
	v_mul_f32_e32 v85, 0x3fb8aa3b, v85
	v_add_f32_e32 v84, v111, v84
	v_exp_f32_e32 v180, v85
	v_sub_f32_e32 v85, v152, v182
	v_add_f32_e32 v84, v112, v84
	v_mul_f32_e32 v85, 0x3d800000, v85
	v_add_f32_e32 v84, v113, v84
	v_mul_f32_e32 v85, 0x3fb8aa3b, v85
	v_add_f32_e32 v84, v114, v84
	v_exp_f32_e32 v187, v85
	v_sub_f32_e32 v85, v153, v182
	v_add_f32_e32 v84, v115, v84
	v_mul_f32_e32 v85, 0x3d800000, v85
	v_add_f32_e32 v84, v116, v84
	v_mul_f32_e32 v85, 0x3fb8aa3b, v85
	v_add_f32_e32 v84, v117, v84
	v_exp_f32_e32 v190, v85
	v_sub_f32_e32 v85, v154, v182
	v_add_f32_e32 v84, v118, v84
	v_mul_f32_e32 v85, 0x3d800000, v85
	v_add_f32_e32 v84, v119, v84
	v_mul_f32_e32 v85, 0x3fb8aa3b, v85
	v_add_f32_e32 v84, v120, v84
	v_exp_f32_e32 v191, v85
	v_sub_f32_e32 v85, v155, v182
	v_add_f32_e32 v84, v121, v84
	v_mul_f32_e32 v85, 0x3d800000, v85
	v_add_f32_e32 v84, v122, v84
	v_mul_f32_e32 v85, 0x3fb8aa3b, v85
	v_add_f32_e32 v84, v123, v84
	v_exp_f32_e32 v192, v85
	v_sub_f32_e32 v85, v156, v182
	v_add_f32_e32 v84, v124, v84
	v_mul_f32_e32 v85, 0x3d800000, v85
	v_add_f32_e32 v84, v125, v84
	v_mul_f32_e32 v85, 0x3fb8aa3b, v85
	v_add_f32_e32 v84, v126, v84
	v_exp_f32_e32 v193, v85
	v_sub_f32_e32 v85, v157, v182
	v_add_f32_e32 v84, v127, v84
	v_mul_f32_e32 v85, 0x3d800000, v85
	v_add_f32_e32 v84, v177, v84
	v_mul_f32_e32 v85, 0x3fb8aa3b, v85
	v_add_f32_e32 v84, v178, v84
	v_exp_f32_e32 v194, v85
	v_sub_f32_e32 v85, v158, v182
	v_add_f32_e32 v84, v179, v84
	v_mul_f32_e32 v85, 0x3d800000, v85
	v_add_f32_e32 v84, v180, v84
	v_mul_f32_e32 v85, 0x3fb8aa3b, v85
	v_add_f32_e32 v84, v187, v84
	v_exp_f32_e32 v158, v85
	v_sub_f32_e32 v85, v159, v182
	v_add_f32_e32 v84, v190, v84
	v_mul_f32_e32 v85, 0x3d800000, v85
	v_add_f32_e32 v84, v191, v84
	v_mul_f32_e32 v85, 0x3fb8aa3b, v85
	v_add_f32_e32 v84, v192, v84
	v_exp_f32_e32 v159, v85
	v_add_f32_e32 v84, v193, v84
	v_add_f32_e32 v84, v194, v84
	v_add_f32_e32 v84, v158, v84
	v_cvt_pk_bf16_f32 v92, v80, v81
	v_cvt_pk_bf16_f32 v93, v82, v83
	v_cvt_pk_bf16_f32 v94, v88, v89
	v_cvt_pk_bf16_f32 v95, v90, v91
	v_cvt_pk_bf16_f32 v80, v96, v97
	v_cvt_pk_bf16_f32 v81, v98, v99
	v_cvt_pk_bf16_f32 v82, v100, v101
	ds_read_b64_tr_b16 v[204:205], v169
	ds_read_b64_tr_b16 v[206:207], v169 offset:8448
	ds_read_b64_tr_b16 v[208:209], v169 offset:16896
	ds_read_b64_tr_b16 v[210:211], v169 offset:25344
	ds_read_b64_tr_b16 v[218:219], v169 offset:32
	ds_read_b64_tr_b16 v[220:221], v169 offset:8480
	ds_read_b64_tr_b16 v[224:225], v169 offset:16928
	ds_read_b64_tr_b16 v[226:227], v169 offset:25376
	ds_read_b64_tr_b16 v[228:229], v169 offset:64
	ds_read_b64_tr_b16 v[230:231], v169 offset:8512
	ds_read_b64_tr_b16 v[232:233], v169 offset:16960
	ds_read_b64_tr_b16 v[234:235], v169 offset:25408
	ds_read_b64_tr_b16 v[236:237], v169 offset:96
	ds_read_b64_tr_b16 v[238:239], v169 offset:8544
	ds_read_b64_tr_b16 v[240:241], v169 offset:16992
	ds_read_b64_tr_b16 v[242:243], v169 offset:25440
	v_add_f32_e32 v84, v159, v84
	v_add_f32_e32 v36, v195, v84
	v_cvt_pk_bf16_f32 v84, v40, v41
	v_cvt_pk_bf16_f32 v85, v42, v43
	v_cvt_pk_bf16_f32 v86, v76, v77
	v_cvt_pk_bf16_f32 v87, v78, v79
	v_cvt_pk_bf16_f32 v83, v102, v103
	v_mul_f32_e32 v37, 0x3d800000, v37
	s_nop 1
	s_waitcnt lgkmcnt(14)
	v_mfma_f32_16x16x32_bf16 v[88:91], v[204:207], v[84:87], 0
	ds_read_b64_tr_b16 v[204:205], v169 offset:128
	ds_read_b64_tr_b16 v[206:207], v169 offset:8576
	v_mul_f32_e32 v37, 0x3fb8aa3b, v37
	v_exp_f32_e32 v196, v37
	v_sub_f32_e32 v37, v38, v182
	s_nop 1
	s_waitcnt lgkmcnt(14)
	v_mfma_f32_16x16x32_bf16 v[152:155], v[208:211], v[92:95], v[88:91]
	ds_read_b64_tr_b16 v[208:209], v169 offset:17024
	ds_read_b64_tr_b16 v[210:211], v169 offset:25472
	s_nop 1
	v_mul_f32_e32 v37, 0x3d800000, v37
	v_mul_f32_e32 v37, 0x3fb8aa3b, v37
	s_nop 1
	s_waitcnt lgkmcnt(14)
	v_mfma_f32_16x16x32_bf16 v[96:99], v[218:221], v[84:87], 0
	ds_read_b64_tr_b16 v[218:219], v169 offset:160
	ds_read_b64_tr_b16 v[220:221], v169 offset:8608
	v_cvt_pk_bf16_f32 v76, v104, v105
	v_cvt_pk_bf16_f32 v77, v106, v107
	v_exp_f32_e32 v197, v37
	s_nop 1
	s_waitcnt lgkmcnt(14)
	v_mfma_f32_16x16x32_bf16 v[88:91], v[224:227], v[92:95], v[96:99]
	ds_read_b64_tr_b16 v[224:225], v169 offset:17056
	ds_read_b64_tr_b16 v[226:227], v169 offset:25504
	s_nop 2
	v_sub_f32_e32 v37, v39, v182
	v_mul_f32_e32 v37, 0x3d800000, v37
	s_nop 1
	s_waitcnt lgkmcnt(14)
	v_mfma_f32_16x16x32_bf16 v[96:99], v[228:231], v[84:87], 0
	ds_read_b64_tr_b16 v[228:229], v169 offset:192
	ds_read_b64_tr_b16 v[230:231], v169 offset:8640
	v_mul_f32_e32 v37, 0x3fb8aa3b, v37
	v_exp_f32_e32 v198, v37
	v_add_f32_e32 v36, v196, v36
	s_nop 1
	s_waitcnt lgkmcnt(14)
	v_mfma_f32_16x16x32_bf16 v[128:131], v[232:235], v[92:95], v[96:99]
	ds_read_b64_tr_b16 v[232:233], v169 offset:17088
	ds_read_b64_tr_b16 v[234:235], v169 offset:25536
	s_nop 2
	v_add_f32_e32 v36, v197, v36
	v_add_f32_e32 v36, v198, v36
	s_nop 1
	s_waitcnt lgkmcnt(14)
	v_mfma_f32_16x16x32_bf16 v[96:99], v[236:239], v[84:87], 0
	ds_read_b64_tr_b16 v[236:237], v169 offset:224
	ds_read_b64_tr_b16 v[238:239], v169 offset:8672
	ds_bpermute_b32 v37, v171, v36
	v_cvt_pk_bf16_f32 v38, v124, v125
	v_cvt_pk_bf16_f32 v39, v126, v127
	s_nop 1
	s_waitcnt lgkmcnt(15)
	v_mfma_f32_16x16x32_bf16 v[104:107], v[240:243], v[92:95], v[96:99]
	ds_read_b64_tr_b16 v[240:241], v169 offset:17120
	ds_read_b64_tr_b16 v[242:243], v169 offset:25568
	s_nop 2
	s_waitcnt lgkmcnt(2)
	v_add_f32_e32 v156, v36, v37
	v_cvt_pk_bf16_f32 v36, v120, v121
	s_nop 1
	s_waitcnt lgkmcnt(15)
	v_mfma_f32_16x16x32_bf16 v[96:99], v[204:207], v[84:87], 0
	ds_read_b64_tr_b16 v[204:205], v169 offset:256
	ds_read_b64_tr_b16 v[206:207], v169 offset:8704
	v_cvt_pk_bf16_f32 v37, v122, v123
	v_cvt_pk_bf16_f32 v78, v108, v109
	v_cvt_pk_bf16_f32 v79, v110, v111
	s_nop 1
	s_waitcnt lgkmcnt(15)
	v_mfma_f32_16x16x32_bf16 v[148:151], v[208:211], v[92:95], v[96:99]
	ds_read_b64_tr_b16 v[208:209], v169 offset:17152
	ds_read_b64_tr_b16 v[210:211], v169 offset:25600
	s_nop 2
	v_cvt_pk_bf16_f32 v40, v112, v113
	v_cvt_pk_bf16_f32 v41, v114, v115
	s_nop 1
	s_waitcnt lgkmcnt(15)
	v_mfma_f32_16x16x32_bf16 v[96:99], v[218:221], v[84:87], 0
	ds_read_b64_tr_b16 v[218:219], v169 offset:288
	ds_read_b64_tr_b16 v[220:221], v169 offset:8736
	v_cvt_pk_bf16_f32 v42, v116, v117
	v_cvt_pk_bf16_f32 v43, v118, v119
	ds_bpermute_b32 v157, v172, v156
	s_waitcnt lgkmcnt(15)
	v_mfma_f32_16x16x32_bf16 v[120:123], v[224:227], v[92:95], v[96:99]
	ds_read_b64_tr_b16 v[224:225], v169 offset:17184
	ds_read_b64_tr_b16 v[226:227], v169 offset:25632
	s_nop 2
	s_waitcnt lgkmcnt(15)
	v_mfma_f32_16x16x32_bf16 v[96:99], v[228:231], v[84:87], 0
	ds_read_b64_tr_b16 v[228:229], v169 offset:320
	ds_read_b64_tr_b16 v[230:231], v169 offset:8768
	s_waitcnt lgkmcnt(15)
	v_mfma_f32_16x16x32_bf16 v[124:127], v[232:235], v[92:95], v[96:99]
	ds_read_b64_tr_b16 v[232:233], v169 offset:17216
	ds_read_b64_tr_b16 v[234:235], v169 offset:25664
	s_nop 5
	s_waitcnt lgkmcnt(15)
	v_mfma_f32_16x16x32_bf16 v[96:99], v[236:239], v[84:87], 0
	ds_read_b64_tr_b16 v[236:237], v169 offset:352
	ds_read_b64_tr_b16 v[238:239], v169 offset:8800
	s_waitcnt lgkmcnt(15)
	v_mfma_f32_16x16x32_bf16 v[108:111], v[240:243], v[92:95], v[96:99]
	ds_read_b64_tr_b16 v[240:241], v169 offset:17248
	ds_read_b64_tr_b16 v[242:243], v169 offset:25696
	s_nop 5
	s_waitcnt lgkmcnt(15)
	v_mfma_f32_16x16x32_bf16 v[96:99], v[204:207], v[84:87], 0
	ds_read_b64_tr_b16 v[204:205], v169 offset:384
	ds_read_b64_tr_b16 v[206:207], v169 offset:8832
	s_waitcnt lgkmcnt(15)
	v_mfma_f32_16x16x32_bf16 v[100:103], v[208:211], v[92:95], v[96:99]
	ds_read_b64_tr_b16 v[208:209], v169 offset:17280
	ds_read_b64_tr_b16 v[210:211], v169 offset:25728
	s_nop 5
	s_waitcnt lgkmcnt(15)
	v_mfma_f32_16x16x32_bf16 v[96:99], v[218:221], v[84:87], 0
	ds_read_b64_tr_b16 v[218:219], v169 offset:416
	ds_read_b64_tr_b16 v[220:221], v169 offset:8864
	s_waitcnt lgkmcnt(14)
	v_mfma_f32_16x16x32_bf16 v[112:115], v[224:227], v[92:95], v[96:99]
	ds_read_b64_tr_b16 v[224:225], v169 offset:17312
	ds_read_b64_tr_b16 v[226:227], v169 offset:25760
	s_nop 5
	s_waitcnt lgkmcnt(14)
	v_mfma_f32_16x16x32_bf16 v[96:99], v[228:231], v[84:87], 0
	ds_read_b64_tr_b16 v[228:229], v169 offset:448
	ds_read_b64_tr_b16 v[230:231], v169 offset:8896
	s_waitcnt lgkmcnt(14)
	v_mfma_f32_16x16x32_bf16 v[116:119], v[232:235], v[92:95], v[96:99]
	ds_read_b64_tr_b16 v[232:233], v169 offset:17344
	ds_read_b64_tr_b16 v[234:235], v169 offset:25792
	s_nop 5
	s_waitcnt lgkmcnt(14)
	v_mfma_f32_16x16x32_bf16 v[96:99], v[236:239], v[84:87], 0
	ds_read_b64_tr_b16 v[236:237], v169 offset:480
	ds_read_b64_tr_b16 v[238:239], v169 offset:8928
	s_waitcnt lgkmcnt(14)
	v_mfma_f32_16x16x32_bf16 v[132:135], v[240:243], v[92:95], v[96:99]
	s_nop 5
	s_waitcnt lgkmcnt(12)
	v_mfma_f32_16x16x32_bf16 v[96:99], v[204:207], v[84:87], 0
	s_waitcnt lgkmcnt(10)
	v_mfma_f32_16x16x32_bf16 v[136:139], v[208:211], v[92:95], v[96:99]
	s_nop 5
	s_waitcnt lgkmcnt(8)
	v_mfma_f32_16x16x32_bf16 v[96:99], v[218:221], v[84:87], 0
	s_waitcnt lgkmcnt(6)
	v_mfma_f32_16x16x32_bf16 v[140:143], v[224:227], v[92:95], v[96:99]
	s_nop 5
	s_waitcnt lgkmcnt(4)
	v_mfma_f32_16x16x32_bf16 v[96:99], v[228:231], v[84:87], 0
	s_waitcnt lgkmcnt(2)
	v_mfma_f32_16x16x32_bf16 v[144:147], v[232:235], v[92:95], v[96:99]
	s_nop 5
	ds_read_b64_tr_b16 v[200:201], v169 offset:17376
	ds_read_b64_tr_b16 v[202:203], v169 offset:25824
	s_waitcnt vmcnt(7)
	ds_write_b128 v168, v[44:47]
	s_waitcnt vmcnt(6)
	ds_write_b128 v168, v[48:51] offset:128
	s_waitcnt vmcnt(5)
	ds_write_b128 v168, v[52:55] offset:256
	s_waitcnt vmcnt(4)
	ds_write_b128 v168, v[56:59] offset:384
	global_load_dwordx4 v[44:47], v[160:161], off offset:2048
	global_load_dwordx4 v[48:51], v[160:161], off offset:2176
	global_load_dwordx4 v[52:55], v[160:161], off offset:2304
	global_load_dwordx4 v[56:59], v[160:161], off offset:2432
	s_waitcnt lgkmcnt(6)
	v_mfma_f32_16x16x32_bf16 v[84:87], v[236:239], v[84:87], 0
	s_nop 7
	s_waitcnt lgkmcnt(0)
	s_barrier
	s_waitcnt lgkmcnt(4)
	v_mfma_f32_16x16x32_bf16 v[96:99], v[200:203], v[92:95], v[84:87]
	s_nop 4
	ds_read_b64_tr_b16 v[204:205], v3
	ds_read_b64_tr_b16 v[206:207], v3 offset:8448
	ds_read_b64_tr_b16 v[208:209], v3 offset:32
	ds_read_b64_tr_b16 v[210:211], v3 offset:8480
	ds_read_b64_tr_b16 v[218:219], v3 offset:16928
	ds_read_b64_tr_b16 v[220:221], v3 offset:25376
	ds_read_b64_tr_b16 v[224:225], v3 offset:64
	ds_read_b64_tr_b16 v[226:227], v3 offset:8512
	ds_read_b64_tr_b16 v[228:229], v3 offset:16960
	ds_read_b64_tr_b16 v[230:231], v3 offset:25408
	ds_read_b64_tr_b16 v[232:233], v3 offset:96
	ds_read_b64_tr_b16 v[234:235], v3 offset:8544
	ds_read_b64_tr_b16 v[236:237], v3 offset:16992
	ds_read_b64_tr_b16 v[238:239], v3 offset:25440
	ds_read_b64_tr_b16 v[240:241], v3 offset:128
	ds_read_b64_tr_b16 v[242:243], v3 offset:8576
	s_waitcnt lgkmcnt(14)
	v_mfma_f32_16x16x32_bf16 v[84:87], v[204:207], v[80:83], v[152:155]
	ds_read_b64_tr_b16 v[204:205], v3 offset:17024
	ds_read_b64_tr_b16 v[206:207], v3 offset:25472
	s_nop 1
	s_waitcnt lgkmcnt(14)
	v_mfma_f32_16x16x32_bf16 v[88:91], v[208:211], v[80:83], v[88:91]
	ds_read_b64_tr_b16 v[208:209], v3 offset:160
	ds_read_b64_tr_b16 v[210:211], v3 offset:8608
	s_waitcnt lgkmcnt(14)
	v_mfma_f32_16x16x32_bf16 v[92:95], v[218:221], v[76:79], v[88:91]
	ds_read_b64_tr_b16 v[218:219], v3 offset:17056
	ds_read_b64_tr_b16 v[220:221], v3 offset:25504
	s_nop 5
	s_waitcnt lgkmcnt(14)
	v_mfma_f32_16x16x32_bf16 v[88:91], v[224:227], v[80:83], v[128:131]
	ds_read_b64_tr_b16 v[224:225], v3 offset:192
	ds_read_b64_tr_b16 v[226:227], v3 offset:8640
	s_waitcnt lgkmcnt(14)
	v_mfma_f32_16x16x32_bf16 v[88:91], v[228:231], v[76:79], v[88:91]
	ds_read_b64_tr_b16 v[228:229], v3 offset:17088
	ds_read_b64_tr_b16 v[230:231], v3 offset:25536
	s_nop 0
	s_waitcnt lgkmcnt(14)
	v_mfma_f32_16x16x32_bf16 v[104:107], v[232:235], v[80:83], v[104:107]
	ds_read_b64_tr_b16 v[232:233], v3 offset:224
	ds_read_b64_tr_b16 v[234:235], v3 offset:8672
	s_waitcnt lgkmcnt(14)
	v_mfma_f32_16x16x32_bf16 v[128:131], v[236:239], v[76:79], v[104:107]
	ds_read_b64_tr_b16 v[236:237], v3 offset:17120
	ds_read_b64_tr_b16 v[238:239], v3 offset:25568
	s_nop 5
	s_waitcnt lgkmcnt(14)
	v_mfma_f32_16x16x32_bf16 v[104:107], v[240:243], v[80:83], v[148:151]
	ds_read_b64_tr_b16 v[240:241], v3 offset:256
	ds_read_b64_tr_b16 v[242:243], v3 offset:8704
	s_waitcnt lgkmcnt(14)
	v_mfma_f32_16x16x32_bf16 v[104:107], v[204:207], v[76:79], v[104:107]
	ds_read_b64_tr_b16 v[204:205], v3 offset:17152
	ds_read_b64_tr_b16 v[206:207], v3 offset:25600
	s_nop 0
	s_waitcnt lgkmcnt(14)
	v_mfma_f32_16x16x32_bf16 v[120:123], v[208:211], v[80:83], v[120:123]
	ds_read_b64_tr_b16 v[208:209], v3 offset:288
	ds_read_b64_tr_b16 v[210:211], v3 offset:8736
	s_waitcnt lgkmcnt(14)
	v_mfma_f32_16x16x32_bf16 v[120:123], v[218:221], v[76:79], v[120:123]
	ds_read_b64_tr_b16 v[218:219], v3 offset:17184
	ds_read_b64_tr_b16 v[220:221], v3 offset:25632
	s_waitcnt lgkmcnt(14)
	v_mfma_f32_16x16x32_bf16 v[124:127], v[224:227], v[80:83], v[124:127]
	ds_read_b64_tr_b16 v[224:225], v3 offset:320
	ds_read_b64_tr_b16 v[226:227], v3 offset:8768
	s_waitcnt lgkmcnt(14)
	v_mfma_f32_16x16x32_bf16 v[124:127], v[228:231], v[76:79], v[124:127]
	ds_read_b64_tr_b16 v[228:229], v3 offset:17216
	ds_read_b64_tr_b16 v[230:231], v3 offset:25664
	s_waitcnt lgkmcnt(14)
	v_mfma_f32_16x16x32_bf16 v[108:111], v[232:235], v[80:83], v[108:111]
	ds_read_b64_tr_b16 v[232:233], v3 offset:352
	ds_read_b64_tr_b16 v[234:235], v3 offset:8800
	s_waitcnt lgkmcnt(14)
	v_mfma_f32_16x16x32_bf16 v[108:111], v[236:239], v[76:79], v[108:111]
	ds_read_b64_tr_b16 v[236:237], v3 offset:17248
	ds_read_b64_tr_b16 v[238:239], v3 offset:25696
	s_waitcnt lgkmcnt(14)
	v_mfma_f32_16x16x32_bf16 v[100:103], v[240:243], v[80:83], v[100:103]
	ds_read_b64_tr_b16 v[240:241], v3 offset:384
	ds_read_b64_tr_b16 v[242:243], v3 offset:8832
	s_waitcnt lgkmcnt(14)
	v_mfma_f32_16x16x32_bf16 v[100:103], v[204:207], v[76:79], v[100:103]
	ds_read_b64_tr_b16 v[204:205], v3 offset:17280
	ds_read_b64_tr_b16 v[206:207], v3 offset:25728
	s_waitcnt lgkmcnt(14)
	v_mfma_f32_16x16x32_bf16 v[112:115], v[208:211], v[80:83], v[112:115]
	ds_read_b64_tr_b16 v[208:209], v3 offset:416
	ds_read_b64_tr_b16 v[210:211], v3 offset:8864
	s_waitcnt lgkmcnt(14)
	v_mfma_f32_16x16x32_bf16 v[112:115], v[218:221], v[76:79], v[112:115]
	ds_read_b64_tr_b16 v[218:219], v3 offset:17312
	ds_read_b64_tr_b16 v[220:221], v3 offset:25760
	s_waitcnt lgkmcnt(14)
	v_mfma_f32_16x16x32_bf16 v[116:119], v[224:227], v[80:83], v[116:119]
	ds_read_b64_tr_b16 v[224:225], v3 offset:448
	ds_read_b64_tr_b16 v[226:227], v3 offset:8896
	s_waitcnt lgkmcnt(14)
	v_mfma_f32_16x16x32_bf16 v[116:119], v[228:231], v[76:79], v[116:119]
	ds_read_b64_tr_b16 v[228:229], v3 offset:17344
	ds_read_b64_tr_b16 v[230:231], v3 offset:25792
	s_waitcnt lgkmcnt(14)
	v_mfma_f32_16x16x32_bf16 v[132:135], v[232:235], v[80:83], v[132:135]
	ds_read_b64_tr_b16 v[232:233], v3 offset:16896
	ds_read_b64_tr_b16 v[234:235], v3 offset:25344
	s_waitcnt lgkmcnt(14)
	v_mfma_f32_16x16x32_bf16 v[132:135], v[236:239], v[76:79], v[132:135]
	s_waitcnt lgkmcnt(12)
	v_mfma_f32_16x16x32_bf16 v[136:139], v[240:243], v[80:83], v[136:139]
	s_waitcnt lgkmcnt(10)
	v_mfma_f32_16x16x32_bf16 v[136:139], v[204:207], v[76:79], v[136:139]
	s_waitcnt lgkmcnt(8)
	v_mfma_f32_16x16x32_bf16 v[140:143], v[208:211], v[80:83], v[140:143]
	s_waitcnt lgkmcnt(6)
	v_mfma_f32_16x16x32_bf16 v[140:143], v[218:221], v[76:79], v[140:143]
	s_waitcnt lgkmcnt(4)
	v_mfma_f32_16x16x32_bf16 v[144:147], v[224:227], v[80:83], v[144:147]
	s_waitcnt lgkmcnt(2)
	v_mfma_f32_16x16x32_bf16 v[144:147], v[228:231], v[76:79], v[144:147]
	ds_read_b64_tr_b16 v[152:153], v3 offset:480
	ds_read_b64_tr_b16 v[154:155], v3 offset:8928
	ds_read_b64_tr_b16 v[148:149], v3 offset:17376
	ds_read_b64_tr_b16 v[150:151], v3 offset:25824
	s_waitcnt vmcnt(7)
	ds_write_b128 v170, v[60:63]
	s_waitcnt vmcnt(6)
	ds_write_b128 v170, v[64:67] offset:128
	s_waitcnt vmcnt(5)
	ds_write_b128 v170, v[68:71] offset:256
	s_waitcnt vmcnt(4)
	ds_write_b128 v170, v[72:75] offset:384
	s_waitcnt lgkmcnt(0)
	s_waitcnt lgkmcnt(8)
	v_mfma_f32_16x16x32_bf16 v[84:87], v[232:235], v[76:79], v[84:87]
	s_nop 7
	s_barrier
	ds_read_b64_tr_b16 v[204:205], v169
	ds_read_b64_tr_b16 v[206:207], v169 offset:8448
	ds_read_b64_tr_b16 v[208:209], v169 offset:16896
	ds_read_b64_tr_b16 v[210:211], v169 offset:25344
	ds_read_b64_tr_b16 v[218:219], v169 offset:32
	ds_read_b64_tr_b16 v[220:221], v169 offset:8480
	ds_read_b64_tr_b16 v[224:225], v169 offset:16928
	ds_read_b64_tr_b16 v[226:227], v169 offset:25376
	ds_read_b64_tr_b16 v[228:229], v169 offset:64
	ds_read_b64_tr_b16 v[230:231], v169 offset:8512
	ds_read_b64_tr_b16 v[232:233], v169 offset:16960
	ds_read_b64_tr_b16 v[234:235], v169 offset:25408
	ds_read_b64_tr_b16 v[236:237], v169 offset:96
	ds_read_b64_tr_b16 v[238:239], v169 offset:8544
	ds_read_b64_tr_b16 v[240:241], v169 offset:16992
	ds_read_b64_tr_b16 v[242:243], v169 offset:25440
	s_waitcnt lgkmcnt(14)
	v_mfma_f32_16x16x32_bf16 v[60:63], v[204:207], v[40:43], v[84:87]
	ds_read_b64_tr_b16 v[204:205], v169 offset:128
	ds_read_b64_tr_b16 v[206:207], v169 offset:8576
	s_waitcnt lgkmcnt(14)
	v_mfma_f32_16x16x32_bf16 v[60:63], v[208:211], v[36:39], v[60:63]
	ds_read_b64_tr_b16 v[208:209], v169 offset:17024
	ds_read_b64_tr_b16 v[210:211], v169 offset:25472
	s_waitcnt lgkmcnt(14)
	v_mfma_f32_16x16x32_bf16 v[64:67], v[218:221], v[40:43], v[92:95]
	ds_read_b64_tr_b16 v[218:219], v169 offset:160
	ds_read_b64_tr_b16 v[220:221], v169 offset:8608
	s_waitcnt lgkmcnt(14)
	v_mfma_f32_16x16x32_bf16 v[64:67], v[224:227], v[36:39], v[64:67]
	ds_read_b64_tr_b16 v[224:225], v169 offset:17056
	ds_read_b64_tr_b16 v[226:227], v169 offset:25504
	v_mfma_f32_16x16x32_bf16 v[80:83], v[152:155], v[80:83], v[96:99]
	v_mov_b32_e32 v155, 0xa00000
	s_nop 1
	s_waitcnt lgkmcnt(14)
	v_mfma_f32_16x16x32_bf16 v[68:71], v[228:231], v[40:43], v[88:91]
	ds_read_b64_tr_b16 v[228:229], v169 offset:192
	ds_read_b64_tr_b16 v[230:231], v169 offset:8640
	v_mfma_f32_16x16x32_bf16 v[76:79], v[148:151], v[76:79], v[80:83]
	s_waitcnt lgkmcnt(14)
	v_mfma_f32_16x16x32_bf16 v[68:71], v[232:235], v[36:39], v[68:71]
	ds_read_b64_tr_b16 v[232:233], v169 offset:17088
	ds_read_b64_tr_b16 v[234:235], v169 offset:25536
	s_waitcnt lgkmcnt(14)
	v_mfma_f32_16x16x32_bf16 v[72:75], v[236:239], v[40:43], v[128:131]
	ds_read_b64_tr_b16 v[236:237], v169 offset:224
	ds_read_b64_tr_b16 v[238:239], v169 offset:8672
	s_waitcnt lgkmcnt(14)
	v_mfma_f32_16x16x32_bf16 v[128:131], v[240:243], v[36:39], v[72:75]
	ds_read_b64_tr_b16 v[240:241], v169 offset:17120
	ds_read_b64_tr_b16 v[242:243], v169 offset:25568
	s_nop 5
	s_waitcnt lgkmcnt(14)
	v_mfma_f32_16x16x32_bf16 v[72:75], v[204:207], v[40:43], v[104:107]
	ds_read_b64_tr_b16 v[204:205], v169 offset:256
	ds_read_b64_tr_b16 v[206:207], v169 offset:8704
	s_waitcnt lgkmcnt(14)
	v_mfma_f32_16x16x32_bf16 v[72:75], v[208:211], v[36:39], v[72:75]
	ds_read_b64_tr_b16 v[208:209], v169 offset:17152
	ds_read_b64_tr_b16 v[210:211], v169 offset:25600
	s_waitcnt lgkmcnt(14)
	v_mfma_f32_16x16x32_bf16 v[80:83], v[218:221], v[40:43], v[120:123]
	ds_read_b64_tr_b16 v[218:219], v169 offset:288
	ds_read_b64_tr_b16 v[220:221], v169 offset:8736
	s_waitcnt lgkmcnt(14)
	v_mfma_f32_16x16x32_bf16 v[80:83], v[224:227], v[36:39], v[80:83]
	ds_read_b64_tr_b16 v[224:225], v169 offset:17184
	ds_read_b64_tr_b16 v[226:227], v169 offset:25632
	s_waitcnt lgkmcnt(14)
	v_mfma_f32_16x16x32_bf16 v[84:87], v[228:231], v[40:43], v[124:127]
	ds_read_b64_tr_b16 v[228:229], v169 offset:320
	ds_read_b64_tr_b16 v[230:231], v169 offset:8768
	s_waitcnt lgkmcnt(14)
	v_mfma_f32_16x16x32_bf16 v[84:87], v[232:235], v[36:39], v[84:87]
	ds_read_b64_tr_b16 v[232:233], v169 offset:17216
	ds_read_b64_tr_b16 v[234:235], v169 offset:25664
	s_waitcnt lgkmcnt(14)
	v_mfma_f32_16x16x32_bf16 v[88:91], v[236:239], v[40:43], v[108:111]
	ds_read_b64_tr_b16 v[236:237], v169 offset:352
	ds_read_b64_tr_b16 v[238:239], v169 offset:8800
	s_waitcnt lgkmcnt(14)
	v_mfma_f32_16x16x32_bf16 v[120:123], v[240:243], v[36:39], v[88:91]
	ds_read_b64_tr_b16 v[240:241], v169 offset:17248
	ds_read_b64_tr_b16 v[242:243], v169 offset:25696
	s_nop 5
	s_waitcnt lgkmcnt(14)
	v_mfma_f32_16x16x32_bf16 v[88:91], v[204:207], v[40:43], v[100:103]
	ds_read_b64_tr_b16 v[204:205], v169 offset:384
	ds_read_b64_tr_b16 v[206:207], v169 offset:8832
	s_waitcnt lgkmcnt(14)
	v_mfma_f32_16x16x32_bf16 v[88:91], v[208:211], v[36:39], v[88:91]
	ds_read_b64_tr_b16 v[208:209], v169 offset:17280
	ds_read_b64_tr_b16 v[210:211], v169 offset:25728
	s_waitcnt lgkmcnt(14)
	v_mfma_f32_16x16x32_bf16 v[92:95], v[218:221], v[40:43], v[112:115]
	ds_read_b64_tr_b16 v[218:219], v169 offset:416
	ds_read_b64_tr_b16 v[220:221], v169 offset:8864
	s_waitcnt lgkmcnt(14)
	v_mfma_f32_16x16x32_bf16 v[92:95], v[224:227], v[36:39], v[92:95]
	ds_read_b64_tr_b16 v[224:225], v169 offset:17312
	ds_read_b64_tr_b16 v[226:227], v169 offset:25760
	s_waitcnt lgkmcnt(14)
	v_mfma_f32_16x16x32_bf16 v[96:99], v[228:231], v[40:43], v[116:119]
	ds_read_b64_tr_b16 v[228:229], v169 offset:448
	ds_read_b64_tr_b16 v[230:231], v169 offset:8896
	s_waitcnt lgkmcnt(14)
	v_mfma_f32_16x16x32_bf16 v[96:99], v[232:235], v[36:39], v[96:99]
	ds_read_b64_tr_b16 v[232:233], v169 offset:17344
	ds_read_b64_tr_b16 v[234:235], v169 offset:25792
	s_waitcnt lgkmcnt(14)
	v_mfma_f32_16x16x32_bf16 v[100:103], v[236:239], v[40:43], v[132:135]
	ds_read_b64_tr_b16 v[236:237], v169 offset:480
	ds_read_b64_tr_b16 v[238:239], v169 offset:8928
	s_waitcnt lgkmcnt(14)
	v_mfma_f32_16x16x32_bf16 v[112:115], v[240:243], v[36:39], v[100:103]
	s_nop 5
	s_waitcnt lgkmcnt(12)
	v_mfma_f32_16x16x32_bf16 v[100:103], v[204:207], v[40:43], v[136:139]
	s_waitcnt lgkmcnt(10)
	v_mfma_f32_16x16x32_bf16 v[100:103], v[208:211], v[36:39], v[100:103]
	v_add_u32_e32 v136, s14, v1
	v_add_f32_e32 v1, v156, v157
	s_nop 1
	s_waitcnt lgkmcnt(8)
	v_mfma_f32_16x16x32_bf16 v[104:107], v[218:221], v[40:43], v[140:143]
	v_ashrrev_i32_e32 v137, 31, v136
	s_nop 1
	s_waitcnt lgkmcnt(6)
	v_mfma_f32_16x16x32_bf16 v[104:107], v[224:227], v[36:39], v[104:107]
	s_waitcnt lgkmcnt(4)
	v_mfma_f32_16x16x32_bf16 v[108:111], v[228:231], v[40:43], v[144:147]
	s_waitcnt lgkmcnt(2)
	v_mfma_f32_16x16x32_bf16 v[108:111], v[232:235], v[36:39], v[108:111]
	ds_read_b64_tr_b16 v[124:125], v169 offset:17376
	ds_read_b64_tr_b16 v[126:127], v169 offset:25824
	s_waitcnt vmcnt(3)
	ds_write_b128 v168, v[44:47]
	s_waitcnt vmcnt(2)
	ds_write_b128 v168, v[48:51] offset:128
	s_waitcnt vmcnt(1)
	ds_write_b128 v168, v[52:55] offset:256
	s_waitcnt vmcnt(0)
	ds_write_b128 v168, v[56:59] offset:384
	s_waitcnt lgkmcnt(0)
	s_waitcnt lgkmcnt(6)
	v_mfma_f32_16x16x32_bf16 v[40:43], v[236:239], v[40:43], v[76:79]
	s_nop 7
	s_barrier
	v_cvt_pk_bf16_f32 v52, v177, v178
	s_waitcnt lgkmcnt(4)
	v_mfma_f32_16x16x32_bf16 v[36:39], v[124:127], v[36:39], v[40:43]
	s_nop 3
	ds_read_b64_tr_b16 v[204:205], v3
	ds_read_b64_tr_b16 v[206:207], v3 offset:8448
	ds_read_b64_tr_b16 v[208:209], v3 offset:16896
	ds_read_b64_tr_b16 v[210:211], v3 offset:25344
	ds_read_b64_tr_b16 v[218:219], v3 offset:32
	ds_read_b64_tr_b16 v[220:221], v3 offset:8480
	ds_read_b64_tr_b16 v[224:225], v3 offset:16928
	ds_read_b64_tr_b16 v[226:227], v3 offset:25376
	ds_read_b64_tr_b16 v[228:229], v3 offset:64
	ds_read_b64_tr_b16 v[230:231], v3 offset:8512
	ds_read_b64_tr_b16 v[232:233], v3 offset:16960
	ds_read_b64_tr_b16 v[234:235], v3 offset:25408
	ds_read_b64_tr_b16 v[236:237], v3 offset:96
	ds_read_b64_tr_b16 v[238:239], v3 offset:8544
	ds_read_b64_tr_b16 v[240:241], v3 offset:16992
	ds_read_b64_tr_b16 v[242:243], v3 offset:25440
	v_cvt_pk_bf16_f32 v53, v179, v180
	v_cvt_pk_bf16_f32 v54, v187, v190
	v_cvt_pk_bf16_f32 v55, v191, v192
	v_cvt_pk_bf16_f32 v48, v193, v194
	v_cvt_pk_bf16_f32 v49, v158, v159
	s_nop 1
	s_waitcnt lgkmcnt(14)
	v_mfma_f32_16x16x32_bf16 v[40:43], v[204:207], v[52:55], v[60:63]
	ds_read_b64_tr_b16 v[204:205], v3 offset:128
	ds_read_b64_tr_b16 v[206:207], v3 offset:8576
	v_cvt_pk_bf16_f32 v50, v195, v196
	v_cvt_pk_bf16_f32 v51, v197, v198
	s_nop 0
	s_waitcnt lgkmcnt(14)
	v_mfma_f32_16x16x32_bf16 v[44:47], v[208:211], v[48:51], v[40:43]
	ds_read_b64_tr_b16 v[208:209], v3 offset:17024
	ds_read_b64_tr_b16 v[210:211], v3 offset:25472
	s_nop 1
	s_waitcnt lgkmcnt(14)
	v_mfma_f32_16x16x32_bf16 v[56:59], v[218:221], v[52:55], v[64:67]
	ds_read_b64_tr_b16 v[218:219], v3 offset:160
	ds_read_b64_tr_b16 v[220:221], v3 offset:8608
	s_waitcnt lgkmcnt(14)
	v_mfma_f32_16x16x32_bf16 v[40:43], v[224:227], v[48:51], v[56:59]
	ds_read_b64_tr_b16 v[224:225], v3 offset:17056
	ds_read_b64_tr_b16 v[226:227], v3 offset:25504
	s_nop 5
	s_waitcnt lgkmcnt(14)
	v_mfma_f32_16x16x32_bf16 v[56:59], v[228:231], v[52:55], v[68:71]
	ds_read_b64_tr_b16 v[228:229], v3 offset:192
	ds_read_b64_tr_b16 v[230:231], v3 offset:8640
	s_waitcnt lgkmcnt(14)
	v_mfma_f32_16x16x32_bf16 v[56:59], v[232:235], v[48:51], v[56:59]
	ds_read_b64_tr_b16 v[232:233], v3 offset:17088
	ds_read_b64_tr_b16 v[234:235], v3 offset:25536
	s_waitcnt lgkmcnt(14)
	v_mfma_f32_16x16x32_bf16 v[60:63], v[236:239], v[52:55], v[128:131]
	ds_read_b64_tr_b16 v[236:237], v3 offset:224
	ds_read_b64_tr_b16 v[238:239], v3 offset:8672
	s_waitcnt lgkmcnt(14)
	v_mfma_f32_16x16x32_bf16 v[60:63], v[240:243], v[48:51], v[60:63]
	ds_read_b64_tr_b16 v[240:241], v3 offset:17120
	ds_read_b64_tr_b16 v[242:243], v3 offset:25568
	s_waitcnt lgkmcnt(14)
	v_mfma_f32_16x16x32_bf16 v[64:67], v[204:207], v[52:55], v[72:75]
	ds_read_b64_tr_b16 v[204:205], v3 offset:256
	ds_read_b64_tr_b16 v[206:207], v3 offset:8704
	s_waitcnt lgkmcnt(14)
	v_mfma_f32_16x16x32_bf16 v[64:67], v[208:211], v[48:51], v[64:67]
	ds_read_b64_tr_b16 v[208:209], v3 offset:17152
	ds_read_b64_tr_b16 v[210:211], v3 offset:25600
	s_waitcnt lgkmcnt(14)
	v_mfma_f32_16x16x32_bf16 v[68:71], v[218:221], v[52:55], v[80:83]
	ds_read_b64_tr_b16 v[218:219], v3 offset:288
	ds_read_b64_tr_b16 v[220:221], v3 offset:8736
	s_waitcnt lgkmcnt(14)
	v_mfma_f32_16x16x32_bf16 v[68:71], v[224:227], v[48:51], v[68:71]
	ds_read_b64_tr_b16 v[224:225], v3 offset:17184
	ds_read_b64_tr_b16 v[226:227], v3 offset:25632
	s_waitcnt lgkmcnt(14)
	v_mfma_f32_16x16x32_bf16 v[72:75], v[228:231], v[52:55], v[84:87]
	ds_read_b64_tr_b16 v[228:229], v3 offset:320
	ds_read_b64_tr_b16 v[230:231], v3 offset:8768
	s_waitcnt lgkmcnt(14)
	v_mfma_f32_16x16x32_bf16 v[72:75], v[232:235], v[48:51], v[72:75]
	ds_read_b64_tr_b16 v[232:233], v3 offset:17216
	ds_read_b64_tr_b16 v[234:235], v3 offset:25664
	s_waitcnt lgkmcnt(14)
	v_mfma_f32_16x16x32_bf16 v[76:79], v[236:239], v[52:55], v[120:123]
	ds_read_b64_tr_b16 v[236:237], v3 offset:352
	ds_read_b64_tr_b16 v[238:239], v3 offset:8800
	s_waitcnt lgkmcnt(14)
	v_mfma_f32_16x16x32_bf16 v[76:79], v[240:243], v[48:51], v[76:79]
	ds_read_b64_tr_b16 v[240:241], v3 offset:17248
	ds_read_b64_tr_b16 v[242:243], v3 offset:25696
	s_waitcnt lgkmcnt(14)
	v_mfma_f32_16x16x32_bf16 v[80:83], v[204:207], v[52:55], v[88:91]
	ds_read_b64_tr_b16 v[204:205], v3 offset:384
	ds_read_b64_tr_b16 v[206:207], v3 offset:8832
	s_waitcnt lgkmcnt(14)
	v_mfma_f32_16x16x32_bf16 v[80:83], v[208:211], v[48:51], v[80:83]
	ds_read_b64_tr_b16 v[208:209], v3 offset:17280
	ds_read_b64_tr_b16 v[210:211], v3 offset:25728
	s_waitcnt lgkmcnt(14)
	v_mfma_f32_16x16x32_bf16 v[84:87], v[218:221], v[52:55], v[92:95]
	ds_read_b64_tr_b16 v[218:219], v3 offset:416
	ds_read_b64_tr_b16 v[220:221], v3 offset:8864
	s_waitcnt lgkmcnt(14)
	v_mfma_f32_16x16x32_bf16 v[84:87], v[224:227], v[48:51], v[84:87]
	ds_read_b64_tr_b16 v[224:225], v3 offset:17312
	ds_read_b64_tr_b16 v[226:227], v3 offset:25760
	s_waitcnt lgkmcnt(14)
	v_mfma_f32_16x16x32_bf16 v[88:91], v[228:231], v[52:55], v[96:99]
	ds_read_b64_tr_b16 v[228:229], v3 offset:448
	ds_read_b64_tr_b16 v[230:231], v3 offset:8896
	s_waitcnt lgkmcnt(14)
	v_mfma_f32_16x16x32_bf16 v[88:91], v[232:235], v[48:51], v[88:91]
	ds_read_b64_tr_b16 v[232:233], v3 offset:17344
	ds_read_b64_tr_b16 v[234:235], v3 offset:25792
	s_waitcnt lgkmcnt(14)
	v_mfma_f32_16x16x32_bf16 v[92:95], v[236:239], v[52:55], v[112:115]
	ds_read_b64_tr_b16 v[236:237], v3 offset:480
	ds_read_b64_tr_b16 v[238:239], v3 offset:8928
	s_waitcnt lgkmcnt(14)
	v_mfma_f32_16x16x32_bf16 v[92:95], v[240:243], v[48:51], v[92:95]
	ds_read_b64_tr_b16 v[240:241], v3 offset:17376
	ds_read_b64_tr_b16 v[242:243], v3 offset:25824
	s_waitcnt lgkmcnt(14)
	v_mfma_f32_16x16x32_bf16 v[96:99], v[204:207], v[52:55], v[100:103]
	s_waitcnt lgkmcnt(12)
	v_mfma_f32_16x16x32_bf16 v[96:99], v[208:211], v[48:51], v[96:99]
	s_nop 0
	s_waitcnt lgkmcnt(10)
	v_mfma_f32_16x16x32_bf16 v[100:103], v[218:221], v[52:55], v[104:107]
	s_waitcnt lgkmcnt(8)
	v_mfma_f32_16x16x32_bf16 v[100:103], v[224:227], v[48:51], v[100:103]
	s_nop 0
	s_waitcnt lgkmcnt(6)
	v_mfma_f32_16x16x32_bf16 v[104:107], v[228:231], v[52:55], v[108:111]
	s_waitcnt lgkmcnt(4)
	v_mfma_f32_16x16x32_bf16 v[104:107], v[232:235], v[48:51], v[104:107]
	s_nop 0
	s_waitcnt lgkmcnt(2)
	v_mfma_f32_16x16x32_bf16 v[36:39], v[236:239], v[52:55], v[36:39]
	s_waitcnt lgkmcnt(0)
	v_mfma_f32_16x16x32_bf16 v[36:39], v[240:243], v[48:51], v[36:39]
	s_nop 7
	v_div_scale_f32 v48, s[12:13], v1, v1, 1.0
	v_rcp_f32_e32 v49, v48
	v_readlane_b32 s12, v253, 35
	v_readlane_b32 s13, v253, 36
	s_add_u32 s10, s12, s10
	v_fma_f32 v50, -v48, v49, 1.0
	v_fmac_f32_e32 v49, v50, v49
	v_div_scale_f32 v50, vcc, 1.0, v1, 1.0
	v_mul_f32_e32 v51, v50, v49
	v_fma_f32 v52, -v48, v51, v50
	v_fmac_f32_e32 v51, v52, v49
	v_fma_f32 v48, -v48, v51, v50
	v_div_fmas_f32 v48, v48, v49, v51
	s_addc_u32 s11, s13, s11
	v_lshlrev_b64 v[50:51], 11, v[136:137]
	v_lshl_add_u64 v[50:51], s[10:11], 0, v[50:51]
	v_div_fixup_f32 v48, v48, v1, 1.0
	v_mad_i64_i32 v[50:51], s[12:13], s6, v155, v[50:51]
	v_lshl_add_u64 v[50:51], v[50:51], 0, s[8:9]
	v_mov_b32_e32 v1, v181
	v_pk_mul_f32 v[40:41], v[48:49], v[40:41] op_sel_hi:[0,1]
	v_pk_mul_f32 v[42:43], v[48:49], v[42:43] op_sel_hi:[0,1]
	v_lshl_add_u64 v[50:51], v[50:51], 0, v[0:1]
	v_cvt_pk_bf16_f32 v40, v40, v41
	v_cvt_pk_bf16_f32 v41, v42, v43
	global_store_dwordx2 v[50:51], v[40:41], off offset:32
	v_pk_mul_f32 v[40:41], v[48:49], v[56:57] op_sel_hi:[0,1]
	v_pk_mul_f32 v[42:43], v[48:49], v[58:59] op_sel_hi:[0,1]
	v_cvt_pk_bf16_f32 v40, v40, v41
	v_cvt_pk_bf16_f32 v41, v42, v43
	global_store_dwordx2 v[50:51], v[40:41], off offset:64
	v_pk_mul_f32 v[40:41], v[48:49], v[60:61] op_sel_hi:[0,1]
	v_pk_mul_f32 v[42:43], v[48:49], v[62:63] op_sel_hi:[0,1]
	v_cvt_pk_bf16_f32 v40, v40, v41
	v_cvt_pk_bf16_f32 v41, v42, v43
	global_store_dwordx2 v[50:51], v[40:41], off offset:96
	v_pk_mul_f32 v[40:41], v[48:49], v[64:65] op_sel_hi:[0,1]
	v_pk_mul_f32 v[42:43], v[48:49], v[66:67] op_sel_hi:[0,1]
	v_cvt_pk_bf16_f32 v40, v40, v41
	v_cvt_pk_bf16_f32 v41, v42, v43
	global_store_dwordx2 v[50:51], v[40:41], off offset:128
	v_pk_mul_f32 v[40:41], v[48:49], v[68:69] op_sel_hi:[0,1]
	v_pk_mul_f32 v[42:43], v[48:49], v[70:71] op_sel_hi:[0,1]
	v_cvt_pk_bf16_f32 v40, v40, v41
	v_cvt_pk_bf16_f32 v41, v42, v43
	global_store_dwordx2 v[50:51], v[40:41], off offset:160
	v_pk_mul_f32 v[40:41], v[48:49], v[72:73] op_sel_hi:[0,1]
	v_pk_mul_f32 v[42:43], v[48:49], v[74:75] op_sel_hi:[0,1]
	v_cvt_pk_bf16_f32 v40, v40, v41
	v_cvt_pk_bf16_f32 v41, v42, v43
	global_store_dwordx2 v[50:51], v[40:41], off offset:192
	v_pk_mul_f32 v[40:41], v[48:49], v[76:77] op_sel_hi:[0,1]
	v_pk_mul_f32 v[42:43], v[48:49], v[78:79] op_sel_hi:[0,1]
	v_cvt_pk_bf16_f32 v40, v40, v41
	v_cvt_pk_bf16_f32 v41, v42, v43
	global_store_dwordx2 v[50:51], v[40:41], off offset:224
	v_pk_mul_f32 v[40:41], v[48:49], v[80:81] op_sel_hi:[0,1]
	v_pk_mul_f32 v[42:43], v[48:49], v[82:83] op_sel_hi:[0,1]
	v_cvt_pk_bf16_f32 v40, v40, v41
	v_cvt_pk_bf16_f32 v41, v42, v43
	global_store_dwordx2 v[50:51], v[40:41], off offset:256
	v_pk_mul_f32 v[40:41], v[48:49], v[84:85] op_sel_hi:[0,1]
	v_pk_mul_f32 v[42:43], v[48:49], v[86:87] op_sel_hi:[0,1]
	v_cvt_pk_bf16_f32 v40, v40, v41
	v_cvt_pk_bf16_f32 v41, v42, v43
	global_store_dwordx2 v[50:51], v[40:41], off offset:288
	v_pk_mul_f32 v[40:41], v[48:49], v[88:89] op_sel_hi:[0,1]
	v_pk_mul_f32 v[42:43], v[48:49], v[90:91] op_sel_hi:[0,1]
	v_cvt_pk_bf16_f32 v40, v40, v41
	v_cvt_pk_bf16_f32 v41, v42, v43
	global_store_dwordx2 v[50:51], v[40:41], off offset:320
	v_pk_mul_f32 v[40:41], v[48:49], v[92:93] op_sel_hi:[0,1]
	v_pk_mul_f32 v[42:43], v[48:49], v[94:95] op_sel_hi:[0,1]
	v_cvt_pk_bf16_f32 v40, v40, v41
	v_cvt_pk_bf16_f32 v41, v42, v43
	global_store_dwordx2 v[50:51], v[40:41], off offset:352
	v_pk_mul_f32 v[40:41], v[48:49], v[96:97] op_sel_hi:[0,1]
	v_pk_mul_f32 v[42:43], v[48:49], v[98:99] op_sel_hi:[0,1]
	v_cvt_pk_bf16_f32 v40, v40, v41
	v_cvt_pk_bf16_f32 v41, v42, v43
	global_store_dwordx2 v[50:51], v[40:41], off offset:384
	v_pk_mul_f32 v[40:41], v[48:49], v[100:101] op_sel_hi:[0,1]
	v_pk_mul_f32 v[42:43], v[48:49], v[102:103] op_sel_hi:[0,1]
	v_cvt_pk_bf16_f32 v40, v40, v41
	v_cvt_pk_bf16_f32 v41, v42, v43
	v_pk_mul_f32 v[44:45], v[48:49], v[44:45] op_sel_hi:[0,1]
	v_pk_mul_f32 v[46:47], v[48:49], v[46:47] op_sel_hi:[0,1]
	global_store_dwordx2 v[50:51], v[40:41], off offset:416
	v_pk_mul_f32 v[40:41], v[48:49], v[104:105] op_sel_hi:[0,1]
	v_pk_mul_f32 v[42:43], v[48:49], v[106:107] op_sel_hi:[0,1]
	v_pk_mul_f32 v[36:37], v[48:49], v[36:37] op_sel_hi:[0,1]
	v_pk_mul_f32 v[38:39], v[48:49], v[38:39] op_sel_hi:[0,1]
	v_cvt_pk_bf16_f32 v44, v44, v45
	v_cvt_pk_bf16_f32 v45, v46, v47
	v_cvt_pk_bf16_f32 v40, v40, v41
	v_cvt_pk_bf16_f32 v41, v42, v43
	v_cvt_pk_bf16_f32 v36, v36, v37
	v_cvt_pk_bf16_f32 v37, v38, v39
	global_store_dwordx2 v[50:51], v[44:45], off
	global_store_dwordx2 v[50:51], v[40:41], off offset:448
	global_store_dwordx2 v[50:51], v[36:37], off offset:480
	s_waitcnt lgkmcnt(0)
	s_barrier
	s_waitcnt lgkmcnt(0)
	s_barrier
	ds_write_b128 v176, v[4:7]
	ds_write_b128 v176, v[8:11] offset:256
	ds_write_b128 v176, v[12:15] offset:8448
	ds_write_b128 v176, v[16:19] offset:8704
	ds_write_b128 v176, v[20:23] offset:16896
	ds_write_b128 v176, v[24:27] offset:17152
	ds_write_b128 v176, v[28:31] offset:25344
	ds_write_b128 v176, v[32:35] offset:25600
	s_waitcnt lgkmcnt(0)
	s_barrier
	ds_read_b128 v[64:67], v175
	ds_read_b128 v[60:63], v175 offset:64
	ds_read_b128 v[56:59], v175 offset:128
	ds_read_b128 v[52:55], v175 offset:192
	ds_read_b128 v[48:51], v175 offset:256
	ds_read_b128 v[44:47], v175 offset:320
	ds_read_b128 v[8:11], v175 offset:384
	ds_read_b128 v[4:7], v175 offset:448
	global_load_dwordx4 v[28:31], v[166:167], off
	global_load_dwordx4 v[12:15], v[164:165], off
	global_load_dwordx4 v[32:35], v[166:167], off offset:128
	global_load_dwordx4 v[16:19], v[164:165], off offset:128
	global_load_dwordx4 v[36:39], v[166:167], off offset:256
	global_load_dwordx4 v[20:23], v[164:165], off offset:256
	global_load_dwordx4 v[40:43], v[166:167], off offset:384
	global_load_dwordx4 v[24:27], v[164:165], off offset:384
	s_waitcnt vmcnt(7)
	ds_write_b128 v170, v[28:31]
	s_waitcnt vmcnt(5)
	ds_write_b128 v170, v[32:35] offset:128
	s_waitcnt vmcnt(3)
	ds_write_b128 v170, v[36:39] offset:256
	s_waitcnt vmcnt(1)
	ds_write_b128 v170, v[40:43] offset:384
	global_load_dwordx4 v[28:31], v[162:163], off
	global_load_dwordx4 v[32:35], v[162:163], off offset:128
	global_load_dwordx4 v[36:39], v[162:163], off offset:256
	global_load_dwordx4 v[40:43], v[162:163], off offset:384
	s_waitcnt lgkmcnt(0)
	s_barrier
	ds_read_b128 v[204:207], v174
	ds_read_b128 v[208:211], v174 offset:64
	ds_read_b128 v[218:221], v174 offset:128
	ds_read_b128 v[224:227], v174 offset:192
	ds_read_b128 v[228:231], v174 offset:256
	ds_read_b128 v[232:235], v174 offset:320
	ds_read_b128 v[236:239], v174 offset:384
	ds_read_b128 v[240:243], v174 offset:448
	s_waitcnt lgkmcnt(7)
	v_mfma_f32_16x16x32_bf16 v[68:71], v[204:207], v[64:67], 0
	ds_read_b128 v[204:207], v174 offset:8448
	s_waitcnt lgkmcnt(7)
	v_mfma_f32_16x16x32_bf16 v[68:71], v[208:211], v[60:63], v[68:71]
	ds_read_b128 v[208:211], v174 offset:8512
	s_waitcnt lgkmcnt(7)
	v_mfma_f32_16x16x32_bf16 v[68:71], v[218:221], v[56:59], v[68:71]
	ds_read_b128 v[218:221], v174 offset:8576
	s_waitcnt lgkmcnt(7)
	v_mfma_f32_16x16x32_bf16 v[68:71], v[224:227], v[52:55], v[68:71]
	ds_read_b128 v[224:227], v174 offset:8640
	s_waitcnt lgkmcnt(7)
	v_mfma_f32_16x16x32_bf16 v[68:71], v[228:231], v[48:51], v[68:71]
	ds_read_b128 v[228:231], v174 offset:8704
	s_waitcnt lgkmcnt(7)
	v_mfma_f32_16x16x32_bf16 v[68:71], v[232:235], v[44:47], v[68:71]
	ds_read_b128 v[232:235], v174 offset:8768
	s_waitcnt lgkmcnt(7)
	v_mfma_f32_16x16x32_bf16 v[68:71], v[236:239], v[8:11], v[68:71]
	ds_read_b128 v[236:239], v174 offset:8832
	s_waitcnt lgkmcnt(7)
	v_mfma_f32_16x16x32_bf16 v[68:71], v[240:243], v[4:7], v[68:71]
	ds_read_b128 v[240:243], v174 offset:8896
	s_waitcnt lgkmcnt(7)
	v_mfma_f32_16x16x32_bf16 v[72:75], v[204:207], v[64:67], 0
	ds_read_b128 v[204:207], v174 offset:16896
	s_waitcnt lgkmcnt(7)
	v_mfma_f32_16x16x32_bf16 v[72:75], v[208:211], v[60:63], v[72:75]
	ds_read_b128 v[208:211], v174 offset:16960
	s_waitcnt lgkmcnt(7)
	v_mfma_f32_16x16x32_bf16 v[72:75], v[218:221], v[56:59], v[72:75]
	ds_read_b128 v[218:221], v174 offset:17024
	s_waitcnt lgkmcnt(7)
	v_mfma_f32_16x16x32_bf16 v[72:75], v[224:227], v[52:55], v[72:75]
	ds_read_b128 v[224:227], v174 offset:17088
	s_waitcnt lgkmcnt(7)
	v_mfma_f32_16x16x32_bf16 v[72:75], v[228:231], v[48:51], v[72:75]
	ds_read_b128 v[228:231], v174 offset:17152
	s_waitcnt lgkmcnt(7)
	v_mfma_f32_16x16x32_bf16 v[72:75], v[232:235], v[44:47], v[72:75]
	ds_read_b128 v[232:235], v174 offset:17216
	s_waitcnt lgkmcnt(7)
	v_mfma_f32_16x16x32_bf16 v[72:75], v[236:239], v[8:11], v[72:75]
	ds_read_b128 v[236:239], v174 offset:17280
	s_waitcnt lgkmcnt(7)
	v_mfma_f32_16x16x32_bf16 v[72:75], v[240:243], v[4:7], v[72:75]
	ds_read_b128 v[240:243], v174 offset:17344
	s_waitcnt lgkmcnt(7)
	v_mfma_f32_16x16x32_bf16 v[76:79], v[204:207], v[64:67], 0
	ds_read_b128 v[204:207], v174 offset:25344
	s_waitcnt lgkmcnt(7)
	v_mfma_f32_16x16x32_bf16 v[76:79], v[208:211], v[60:63], v[76:79]
	ds_read_b128 v[208:211], v174 offset:25408
	s_waitcnt lgkmcnt(7)
	v_mfma_f32_16x16x32_bf16 v[76:79], v[218:221], v[56:59], v[76:79]
	ds_read_b128 v[218:221], v174 offset:25472
	s_waitcnt lgkmcnt(7)
	v_mfma_f32_16x16x32_bf16 v[76:79], v[224:227], v[52:55], v[76:79]
	ds_read_b128 v[224:227], v174 offset:25536
	s_waitcnt lgkmcnt(7)
	v_mfma_f32_16x16x32_bf16 v[76:79], v[228:231], v[48:51], v[76:79]
	ds_read_b128 v[228:231], v174 offset:25600
	s_waitcnt lgkmcnt(7)
	v_mfma_f32_16x16x32_bf16 v[76:79], v[232:235], v[44:47], v[76:79]
	ds_read_b128 v[232:235], v174 offset:25664
	s_waitcnt lgkmcnt(7)
	v_mfma_f32_16x16x32_bf16 v[76:79], v[236:239], v[8:11], v[76:79]
	ds_read_b128 v[236:239], v174 offset:25728
	s_waitcnt lgkmcnt(7)
	v_mfma_f32_16x16x32_bf16 v[76:79], v[240:243], v[4:7], v[76:79]
	s_waitcnt lgkmcnt(6)
	v_mfma_f32_16x16x32_bf16 v[80:83], v[204:207], v[64:67], 0
	s_waitcnt lgkmcnt(5)
	v_mfma_f32_16x16x32_bf16 v[80:83], v[208:211], v[60:63], v[80:83]
	s_waitcnt lgkmcnt(4)
	v_mfma_f32_16x16x32_bf16 v[80:83], v[218:221], v[56:59], v[80:83]
	s_waitcnt lgkmcnt(3)
	v_mfma_f32_16x16x32_bf16 v[80:83], v[224:227], v[52:55], v[80:83]
	s_waitcnt lgkmcnt(2)
	v_mfma_f32_16x16x32_bf16 v[80:83], v[228:231], v[48:51], v[80:83]
	s_waitcnt lgkmcnt(1)
	v_mfma_f32_16x16x32_bf16 v[80:83], v[232:235], v[44:47], v[80:83]
	s_waitcnt lgkmcnt(0)
	v_mfma_f32_16x16x32_bf16 v[80:83], v[236:239], v[8:11], v[80:83]
	s_nop 7
	ds_read_b128 v[84:87], v174 offset:25792
	ds_write_b128 v168, v[12:15]
	ds_write_b128 v168, v[16:19] offset:128
	ds_write_b128 v168, v[20:23] offset:256
	s_waitcnt vmcnt(4)
	ds_write_b128 v168, v[24:27] offset:384
	global_load_dwordx4 v[12:15], v[160:161], off
	global_load_dwordx4 v[16:19], v[160:161], off offset:128
	global_load_dwordx4 v[20:23], v[160:161], off offset:256
	global_load_dwordx4 v[24:27], v[160:161], off offset:384
	s_waitcnt lgkmcnt(0)
	s_barrier
	s_waitcnt lgkmcnt(4)
	v_mfma_f32_16x16x32_bf16 v[80:83], v[84:87], v[4:7], v[80:83]
	ds_read_b128 v[204:207], v173
	ds_read_b128 v[208:211], v173 offset:64
	ds_read_b128 v[218:221], v173 offset:128
	ds_read_b128 v[224:227], v173 offset:192
	ds_read_b128 v[228:231], v173 offset:256
	ds_read_b128 v[232:235], v173 offset:320
	ds_read_b128 v[236:239], v173 offset:384
	ds_read_b128 v[240:243], v173 offset:448
	s_waitcnt lgkmcnt(7)
	v_mfma_f32_16x16x32_bf16 v[84:87], v[204:207], v[64:67], 0
	ds_read_b128 v[204:207], v173 offset:8448
	s_waitcnt lgkmcnt(7)
	v_mfma_f32_16x16x32_bf16 v[84:87], v[208:211], v[60:63], v[84:87]
	ds_read_b128 v[208:211], v173 offset:8512
	s_waitcnt lgkmcnt(7)
	v_mfma_f32_16x16x32_bf16 v[84:87], v[218:221], v[56:59], v[84:87]
	ds_read_b128 v[218:221], v173 offset:8576
	s_waitcnt lgkmcnt(7)
	v_mfma_f32_16x16x32_bf16 v[84:87], v[224:227], v[52:55], v[84:87]
	ds_read_b128 v[224:227], v173 offset:8640
	s_waitcnt lgkmcnt(7)
	v_mfma_f32_16x16x32_bf16 v[84:87], v[228:231], v[48:51], v[84:87]
	ds_read_b128 v[228:231], v173 offset:8704
	s_waitcnt lgkmcnt(7)
	v_mfma_f32_16x16x32_bf16 v[84:87], v[232:235], v[44:47], v[84:87]
	ds_read_b128 v[232:235], v173 offset:8768
	s_waitcnt lgkmcnt(7)
	v_mfma_f32_16x16x32_bf16 v[84:87], v[236:239], v[8:11], v[84:87]
	ds_read_b128 v[236:239], v173 offset:8832
	s_waitcnt lgkmcnt(7)
	v_mfma_f32_16x16x32_bf16 v[84:87], v[240:243], v[4:7], v[84:87]
	ds_read_b128 v[240:243], v173 offset:8896
	s_waitcnt lgkmcnt(7)
	v_mfma_f32_16x16x32_bf16 v[88:91], v[204:207], v[64:67], 0
	ds_read_b128 v[204:207], v173 offset:16896
	s_waitcnt lgkmcnt(7)
	v_mfma_f32_16x16x32_bf16 v[88:91], v[208:211], v[60:63], v[88:91]
	ds_read_b128 v[208:211], v173 offset:16960
	s_waitcnt lgkmcnt(7)
	v_mfma_f32_16x16x32_bf16 v[88:91], v[218:221], v[56:59], v[88:91]
	ds_read_b128 v[218:221], v173 offset:17024
	s_waitcnt lgkmcnt(7)
	v_mfma_f32_16x16x32_bf16 v[88:91], v[224:227], v[52:55], v[88:91]
	ds_read_b128 v[224:227], v173 offset:17088
	s_waitcnt lgkmcnt(7)
	v_mfma_f32_16x16x32_bf16 v[88:91], v[228:231], v[48:51], v[88:91]
	ds_read_b128 v[228:231], v173 offset:17152
	s_waitcnt lgkmcnt(7)
	v_mfma_f32_16x16x32_bf16 v[88:91], v[232:235], v[44:47], v[88:91]
	ds_read_b128 v[232:235], v173 offset:17216
	s_waitcnt lgkmcnt(7)
	v_mfma_f32_16x16x32_bf16 v[88:91], v[236:239], v[8:11], v[88:91]
	ds_read_b128 v[236:239], v173 offset:17280
	s_waitcnt lgkmcnt(7)
	v_mfma_f32_16x16x32_bf16 v[88:91], v[240:243], v[4:7], v[88:91]
	ds_read_b128 v[240:243], v173 offset:17344
	s_waitcnt lgkmcnt(7)
	v_mfma_f32_16x16x32_bf16 v[92:95], v[204:207], v[64:67], 0
	ds_read_b128 v[204:207], v173 offset:25344
	s_waitcnt lgkmcnt(7)
	v_mfma_f32_16x16x32_bf16 v[92:95], v[208:211], v[60:63], v[92:95]
	ds_read_b128 v[208:211], v173 offset:25408
	s_waitcnt lgkmcnt(7)
	v_mfma_f32_16x16x32_bf16 v[92:95], v[218:221], v[56:59], v[92:95]
	ds_read_b128 v[218:221], v173 offset:25472
	s_waitcnt lgkmcnt(7)
	v_mfma_f32_16x16x32_bf16 v[92:95], v[224:227], v[52:55], v[92:95]
	ds_read_b128 v[224:227], v173 offset:25536
	s_waitcnt lgkmcnt(7)
	v_mfma_f32_16x16x32_bf16 v[92:95], v[228:231], v[48:51], v[92:95]
	ds_read_b128 v[228:231], v173 offset:25600
	s_waitcnt lgkmcnt(7)
	v_mfma_f32_16x16x32_bf16 v[92:95], v[232:235], v[44:47], v[92:95]
	ds_read_b128 v[232:235], v173 offset:25664
	s_waitcnt lgkmcnt(7)
	v_mfma_f32_16x16x32_bf16 v[92:95], v[236:239], v[8:11], v[92:95]
	ds_read_b128 v[236:239], v173 offset:25728
	s_waitcnt lgkmcnt(7)
	v_mfma_f32_16x16x32_bf16 v[92:95], v[240:243], v[4:7], v[92:95]
	s_waitcnt lgkmcnt(6)
	v_mfma_f32_16x16x32_bf16 v[96:99], v[204:207], v[64:67], 0
	s_waitcnt lgkmcnt(5)
	v_mfma_f32_16x16x32_bf16 v[96:99], v[208:211], v[60:63], v[96:99]
	s_waitcnt lgkmcnt(4)
	v_mfma_f32_16x16x32_bf16 v[96:99], v[218:221], v[56:59], v[96:99]
	s_waitcnt lgkmcnt(3)
	v_mfma_f32_16x16x32_bf16 v[96:99], v[224:227], v[52:55], v[96:99]
	s_waitcnt lgkmcnt(2)
	v_mfma_f32_16x16x32_bf16 v[96:99], v[228:231], v[48:51], v[96:99]
	s_waitcnt lgkmcnt(1)
	v_mfma_f32_16x16x32_bf16 v[96:99], v[232:235], v[44:47], v[96:99]
	s_waitcnt lgkmcnt(0)
	v_mfma_f32_16x16x32_bf16 v[96:99], v[236:239], v[8:11], v[96:99]
	s_nop 7
	ds_read_b128 v[100:103], v173 offset:25792
	s_waitcnt vmcnt(7)
	ds_write_b128 v170, v[28:31]
	s_waitcnt vmcnt(6)
	ds_write_b128 v170, v[32:35] offset:128
	s_waitcnt vmcnt(5)
	ds_write_b128 v170, v[36:39] offset:256
	s_waitcnt vmcnt(4)
	ds_write_b128 v170, v[40:43] offset:384
	global_load_dwordx4 v[28:31], v[166:167], off offset:2048
	global_load_dwordx4 v[32:35], v[166:167], off offset:2176
	global_load_dwordx4 v[36:39], v[166:167], off offset:2304
	global_load_dwordx4 v[40:43], v[166:167], off offset:2432
	s_waitcnt lgkmcnt(0)
	s_barrier
	s_waitcnt lgkmcnt(4)
	v_mfma_f32_16x16x32_bf16 v[96:99], v[100:103], v[4:7], v[96:99]
	ds_read_b128 v[204:207], v174
	ds_read_b128 v[208:211], v174 offset:64
	ds_read_b128 v[218:221], v174 offset:128
	ds_read_b128 v[224:227], v174 offset:192
	ds_read_b128 v[228:231], v174 offset:256
	ds_read_b128 v[232:235], v174 offset:320
	ds_read_b128 v[236:239], v174 offset:384
	ds_read_b128 v[240:243], v174 offset:448
	s_waitcnt lgkmcnt(7)
	v_mfma_f32_16x16x32_bf16 v[100:103], v[204:207], v[64:67], 0
	ds_read_b128 v[204:207], v174 offset:8448
	s_waitcnt lgkmcnt(7)
	v_mfma_f32_16x16x32_bf16 v[100:103], v[208:211], v[60:63], v[100:103]
	ds_read_b128 v[208:211], v174 offset:8512
	s_waitcnt lgkmcnt(7)
	v_mfma_f32_16x16x32_bf16 v[100:103], v[218:221], v[56:59], v[100:103]
	ds_read_b128 v[218:221], v174 offset:8576
	s_waitcnt lgkmcnt(7)
	v_mfma_f32_16x16x32_bf16 v[100:103], v[224:227], v[52:55], v[100:103]
	ds_read_b128 v[224:227], v174 offset:8640
	s_waitcnt lgkmcnt(7)
	v_mfma_f32_16x16x32_bf16 v[100:103], v[228:231], v[48:51], v[100:103]
	ds_read_b128 v[228:231], v174 offset:8704
	s_waitcnt lgkmcnt(7)
	v_mfma_f32_16x16x32_bf16 v[100:103], v[232:235], v[44:47], v[100:103]
	ds_read_b128 v[232:235], v174 offset:8768
	s_waitcnt lgkmcnt(7)
	v_mfma_f32_16x16x32_bf16 v[100:103], v[236:239], v[8:11], v[100:103]
	ds_read_b128 v[236:239], v174 offset:8832
	s_waitcnt lgkmcnt(7)
	v_mfma_f32_16x16x32_bf16 v[100:103], v[240:243], v[4:7], v[100:103]
	ds_read_b128 v[240:243], v174 offset:8896
	s_waitcnt lgkmcnt(7)
	v_mfma_f32_16x16x32_bf16 v[104:107], v[204:207], v[64:67], 0
	ds_read_b128 v[204:207], v174 offset:16896
	s_waitcnt lgkmcnt(7)
	v_mfma_f32_16x16x32_bf16 v[104:107], v[208:211], v[60:63], v[104:107]
	ds_read_b128 v[208:211], v174 offset:16960
	s_waitcnt lgkmcnt(7)
	v_mfma_f32_16x16x32_bf16 v[104:107], v[218:221], v[56:59], v[104:107]
	ds_read_b128 v[218:221], v174 offset:17024
	s_waitcnt lgkmcnt(7)
	v_mfma_f32_16x16x32_bf16 v[104:107], v[224:227], v[52:55], v[104:107]
	ds_read_b128 v[224:227], v174 offset:17088
	s_waitcnt lgkmcnt(7)
	v_mfma_f32_16x16x32_bf16 v[104:107], v[228:231], v[48:51], v[104:107]
	ds_read_b128 v[228:231], v174 offset:17152
	s_waitcnt lgkmcnt(7)
	v_mfma_f32_16x16x32_bf16 v[104:107], v[232:235], v[44:47], v[104:107]
	ds_read_b128 v[232:235], v174 offset:17216
	s_waitcnt lgkmcnt(7)
	v_mfma_f32_16x16x32_bf16 v[104:107], v[236:239], v[8:11], v[104:107]
	ds_read_b128 v[236:239], v174 offset:17280
	s_waitcnt lgkmcnt(7)
	v_mfma_f32_16x16x32_bf16 v[104:107], v[240:243], v[4:7], v[104:107]
	ds_read_b128 v[240:243], v174 offset:17344
	s_waitcnt lgkmcnt(7)
	v_mfma_f32_16x16x32_bf16 v[108:111], v[204:207], v[64:67], 0
	ds_read_b128 v[204:207], v174 offset:25344
	s_waitcnt lgkmcnt(7)
	v_mfma_f32_16x16x32_bf16 v[108:111], v[208:211], v[60:63], v[108:111]
	ds_read_b128 v[208:211], v174 offset:25408
	s_waitcnt lgkmcnt(7)
	v_mfma_f32_16x16x32_bf16 v[108:111], v[218:221], v[56:59], v[108:111]
	ds_read_b128 v[218:221], v174 offset:25472
	s_waitcnt lgkmcnt(7)
	v_mfma_f32_16x16x32_bf16 v[108:111], v[224:227], v[52:55], v[108:111]
	ds_read_b128 v[224:227], v174 offset:25536
	s_waitcnt lgkmcnt(7)
	v_mfma_f32_16x16x32_bf16 v[108:111], v[228:231], v[48:51], v[108:111]
	ds_read_b128 v[228:231], v174 offset:25600
	s_waitcnt lgkmcnt(7)
	v_mfma_f32_16x16x32_bf16 v[108:111], v[232:235], v[44:47], v[108:111]
	ds_read_b128 v[232:235], v174 offset:25664
	s_waitcnt lgkmcnt(7)
	v_mfma_f32_16x16x32_bf16 v[108:111], v[236:239], v[8:11], v[108:111]
	ds_read_b128 v[236:239], v174 offset:25728
	s_waitcnt lgkmcnt(7)
	v_mfma_f32_16x16x32_bf16 v[108:111], v[240:243], v[4:7], v[108:111]
	s_waitcnt lgkmcnt(6)
	v_mfma_f32_16x16x32_bf16 v[112:115], v[204:207], v[64:67], 0
	s_waitcnt lgkmcnt(5)
	v_mfma_f32_16x16x32_bf16 v[112:115], v[208:211], v[60:63], v[112:115]
	s_waitcnt lgkmcnt(4)
	v_mfma_f32_16x16x32_bf16 v[112:115], v[218:221], v[56:59], v[112:115]
	s_waitcnt lgkmcnt(3)
	v_mfma_f32_16x16x32_bf16 v[112:115], v[224:227], v[52:55], v[112:115]
	s_waitcnt lgkmcnt(2)
	v_mfma_f32_16x16x32_bf16 v[112:115], v[228:231], v[48:51], v[112:115]
	s_waitcnt lgkmcnt(1)
	v_mfma_f32_16x16x32_bf16 v[112:115], v[232:235], v[44:47], v[112:115]
	s_waitcnt lgkmcnt(0)
	v_mfma_f32_16x16x32_bf16 v[112:115], v[236:239], v[8:11], v[112:115]
	s_nop 7
	ds_read_b128 v[116:119], v174 offset:25792
	s_waitcnt vmcnt(7)
	ds_write_b128 v168, v[12:15]
	s_waitcnt vmcnt(6)
	ds_write_b128 v168, v[16:19] offset:128
	s_waitcnt vmcnt(5)
	ds_write_b128 v168, v[20:23] offset:256
	s_waitcnt vmcnt(4)
	ds_write_b128 v168, v[24:27] offset:384
	global_load_dwordx4 v[12:15], v[164:165], off offset:2048
	global_load_dwordx4 v[16:19], v[164:165], off offset:2176
	global_load_dwordx4 v[20:23], v[164:165], off offset:2304
	global_load_dwordx4 v[24:27], v[164:165], off offset:2432
	s_waitcnt lgkmcnt(0)
	s_barrier
	s_waitcnt lgkmcnt(4)
	v_mfma_f32_16x16x32_bf16 v[112:115], v[116:119], v[4:7], v[112:115]
	ds_read_b128 v[204:207], v173
	ds_read_b128 v[208:211], v173 offset:64
	ds_read_b128 v[218:221], v173 offset:128
	ds_read_b128 v[224:227], v173 offset:192
	ds_read_b128 v[228:231], v173 offset:256
	ds_read_b128 v[232:235], v173 offset:320
	ds_read_b128 v[236:239], v173 offset:384
	ds_read_b128 v[240:243], v173 offset:448
	s_waitcnt lgkmcnt(7)
	v_mfma_f32_16x16x32_bf16 v[116:119], v[204:207], v[64:67], 0
	ds_read_b128 v[204:207], v173 offset:8448
	s_waitcnt lgkmcnt(7)
	v_mfma_f32_16x16x32_bf16 v[116:119], v[208:211], v[60:63], v[116:119]
	ds_read_b128 v[208:211], v173 offset:8512
	s_waitcnt lgkmcnt(7)
	v_mfma_f32_16x16x32_bf16 v[116:119], v[218:221], v[56:59], v[116:119]
	ds_read_b128 v[218:221], v173 offset:8576
	s_waitcnt lgkmcnt(7)
	v_mfma_f32_16x16x32_bf16 v[116:119], v[224:227], v[52:55], v[116:119]
	ds_read_b128 v[224:227], v173 offset:8640
	s_waitcnt lgkmcnt(7)
	v_mfma_f32_16x16x32_bf16 v[116:119], v[228:231], v[48:51], v[116:119]
	ds_read_b128 v[228:231], v173 offset:8704
	s_waitcnt lgkmcnt(7)
	v_mfma_f32_16x16x32_bf16 v[116:119], v[232:235], v[44:47], v[116:119]
	ds_read_b128 v[232:235], v173 offset:8768
	s_waitcnt lgkmcnt(7)
	v_mfma_f32_16x16x32_bf16 v[116:119], v[236:239], v[8:11], v[116:119]
	ds_read_b128 v[236:239], v173 offset:8832
	s_waitcnt lgkmcnt(7)
	v_mfma_f32_16x16x32_bf16 v[116:119], v[240:243], v[4:7], v[116:119]
	ds_read_b128 v[240:243], v173 offset:8896
	s_waitcnt lgkmcnt(7)
	v_mfma_f32_16x16x32_bf16 v[120:123], v[204:207], v[64:67], 0
	ds_read_b128 v[204:207], v173 offset:16896
	s_waitcnt lgkmcnt(7)
	v_mfma_f32_16x16x32_bf16 v[120:123], v[208:211], v[60:63], v[120:123]
	ds_read_b128 v[208:211], v173 offset:16960
	s_waitcnt lgkmcnt(7)
	v_mfma_f32_16x16x32_bf16 v[120:123], v[218:221], v[56:59], v[120:123]
	ds_read_b128 v[218:221], v173 offset:17024
	s_waitcnt lgkmcnt(7)
	v_mfma_f32_16x16x32_bf16 v[120:123], v[224:227], v[52:55], v[120:123]
	ds_read_b128 v[224:227], v173 offset:17088
	s_waitcnt lgkmcnt(7)
	v_mfma_f32_16x16x32_bf16 v[120:123], v[228:231], v[48:51], v[120:123]
	ds_read_b128 v[228:231], v173 offset:17152
	s_waitcnt lgkmcnt(7)
	v_mfma_f32_16x16x32_bf16 v[120:123], v[232:235], v[44:47], v[120:123]
	ds_read_b128 v[232:235], v173 offset:17216
	s_waitcnt lgkmcnt(7)
	v_mfma_f32_16x16x32_bf16 v[120:123], v[236:239], v[8:11], v[120:123]
	ds_read_b128 v[236:239], v173 offset:17280
	s_waitcnt lgkmcnt(7)
	v_mfma_f32_16x16x32_bf16 v[120:123], v[240:243], v[4:7], v[120:123]
	ds_read_b128 v[240:243], v173 offset:17344
	s_waitcnt lgkmcnt(7)
	v_mfma_f32_16x16x32_bf16 v[124:127], v[204:207], v[64:67], 0
	ds_read_b128 v[204:207], v173 offset:25344
	s_waitcnt lgkmcnt(7)
	v_mfma_f32_16x16x32_bf16 v[124:127], v[208:211], v[60:63], v[124:127]
	ds_read_b128 v[208:211], v173 offset:25408
	s_waitcnt lgkmcnt(7)
	v_mfma_f32_16x16x32_bf16 v[124:127], v[218:221], v[56:59], v[124:127]
	ds_read_b128 v[218:221], v173 offset:25472
	s_waitcnt lgkmcnt(7)
	v_mfma_f32_16x16x32_bf16 v[124:127], v[224:227], v[52:55], v[124:127]
	ds_read_b128 v[224:227], v173 offset:25536
	s_waitcnt lgkmcnt(7)
	v_mfma_f32_16x16x32_bf16 v[124:127], v[228:231], v[48:51], v[124:127]
	ds_read_b128 v[228:231], v173 offset:25600
	s_waitcnt lgkmcnt(7)
	v_mfma_f32_16x16x32_bf16 v[124:127], v[232:235], v[44:47], v[124:127]
	ds_read_b128 v[232:235], v173 offset:25664
	s_waitcnt lgkmcnt(7)
	v_mfma_f32_16x16x32_bf16 v[124:127], v[236:239], v[8:11], v[124:127]
	ds_read_b128 v[236:239], v173 offset:25728
	s_waitcnt lgkmcnt(7)
	v_mfma_f32_16x16x32_bf16 v[124:127], v[240:243], v[4:7], v[124:127]
	ds_read_b128 v[240:243], v173 offset:25792
	s_waitcnt lgkmcnt(7)
	v_mfma_f32_16x16x32_bf16 v[64:67], v[204:207], v[64:67], 0
	s_waitcnt lgkmcnt(6)
	v_mfma_f32_16x16x32_bf16 v[60:63], v[208:211], v[60:63], v[64:67]
	s_nop 4
	s_waitcnt lgkmcnt(5)
	v_mfma_f32_16x16x32_bf16 v[56:59], v[218:221], v[56:59], v[60:63]
	s_nop 2
	s_waitcnt lgkmcnt(4)
	v_mfma_f32_16x16x32_bf16 v[52:55], v[224:227], v[52:55], v[56:59]
	s_nop 2
	s_waitcnt lgkmcnt(3)
	v_mfma_f32_16x16x32_bf16 v[48:51], v[228:231], v[48:51], v[52:55]
	s_nop 2
	s_waitcnt lgkmcnt(2)
	v_mfma_f32_16x16x32_bf16 v[44:47], v[232:235], v[44:47], v[48:51]
	s_nop 2
	s_waitcnt lgkmcnt(1)
	v_mfma_f32_16x16x32_bf16 v[8:11], v[236:239], v[8:11], v[44:47]
	s_nop 2
	s_waitcnt vmcnt(7)
	ds_write_b128 v170, v[28:31]
	s_waitcnt vmcnt(6)
	ds_write_b128 v170, v[32:35] offset:128
	s_waitcnt vmcnt(5)
	ds_write_b128 v170, v[36:39] offset:256
	s_waitcnt vmcnt(4)
	ds_write_b128 v170, v[40:43] offset:384
	global_load_dwordx4 v[28:31], v[162:163], off offset:2048
	global_load_dwordx4 v[32:35], v[162:163], off offset:2176
	global_load_dwordx4 v[36:39], v[162:163], off offset:2304
	global_load_dwordx4 v[40:43], v[162:163], off offset:2432
	s_waitcnt lgkmcnt(4)
	v_mfma_f32_16x16x32_bf16 v[4:7], v[240:243], v[4:7], v[8:11]
	s_nop 7
	s_nop 2
	v_max_f32_e32 v8, v71, v71
	v_max_f32_e32 v9, v70, v70
	v_max_f32_e32 v8, v9, v8
	v_max_f32_e32 v9, v75, v75
	v_max_f32_e32 v10, v74, v74
	v_max_f32_e32 v9, v10, v9
	v_max3_f32 v8, v68, v69, v8
	v_max3_f32 v9, v72, v73, v9
	v_max3_f32 v8, v8, s7, v9
	v_max_f32_e32 v9, v79, v79
	v_max_f32_e32 v10, v78, v78
	v_max_f32_e32 v9, v10, v9
	v_max_f32_e32 v10, v83, v83
	v_max_f32_e32 v11, v82, v82
	v_max_f32_e32 v10, v11, v10
	v_max3_f32 v9, v76, v77, v9
	v_max3_f32 v10, v80, v81, v10
	v_max3_f32 v8, v8, v9, v10
	v_max_f32_e32 v9, v87, v87
	v_max_f32_e32 v10, v86, v86
	v_max_f32_e32 v9, v10, v9
	v_max_f32_e32 v10, v91, v91
	v_max_f32_e32 v11, v90, v90
	v_max_f32_e32 v10, v11, v10
	v_max3_f32 v9, v84, v85, v9
	v_max3_f32 v10, v88, v89, v10
	v_max3_f32 v8, v8, v9, v10
	v_max_f32_e32 v9, v95, v95
	v_max_f32_e32 v10, v94, v94
	v_max_f32_e32 v9, v10, v9
	v_max_f32_e32 v10, v99, v99
	v_max_f32_e32 v11, v98, v98
	v_max_f32_e32 v10, v11, v10
	v_max3_f32 v9, v92, v93, v9
	v_max3_f32 v10, v96, v97, v10
	v_max3_f32 v8, v8, v9, v10
	v_max_f32_e32 v9, v103, v103
	v_max_f32_e32 v10, v102, v102
	v_max_f32_e32 v9, v10, v9
	v_max_f32_e32 v10, v107, v107
	v_max_f32_e32 v11, v106, v106
	v_max_f32_e32 v10, v11, v10
	v_max3_f32 v9, v100, v101, v9
	v_max3_f32 v10, v104, v105, v10
	v_max3_f32 v8, v8, v9, v10
	v_max_f32_e32 v9, v111, v111
	v_max_f32_e32 v10, v110, v110
	v_max_f32_e32 v9, v10, v9
	v_max_f32_e32 v10, v115, v115
	v_max_f32_e32 v11, v114, v114
	v_max_f32_e32 v10, v11, v10
	v_max3_f32 v9, v108, v109, v9
	v_max3_f32 v10, v112, v113, v10
	v_max3_f32 v8, v8, v9, v10
	v_max_f32_e32 v9, v119, v119
	v_max_f32_e32 v10, v118, v118
	v_max_f32_e32 v9, v10, v9
	v_max_f32_e32 v10, v123, v123
	v_max_f32_e32 v11, v122, v122
	v_max_f32_e32 v10, v11, v10
	v_max3_f32 v9, v116, v117, v9
	v_max3_f32 v10, v120, v121, v10
	v_max3_f32 v8, v8, v9, v10
	v_max_f32_e32 v9, v127, v127
	v_max_f32_e32 v10, v126, v126
	v_max_f32_e32 v9, v10, v9
	v_max_f32_e32 v10, v7, v7
	v_max_f32_e32 v11, v6, v6
	v_max_f32_e32 v10, v11, v10
	v_max3_f32 v9, v124, v125, v9
	v_max3_f32 v10, v4, v5, v10
	v_max3_f32 v8, v8, v9, v10
	ds_bpermute_b32 v9, v171, v8
	s_waitcnt lgkmcnt(0)
	s_barrier
	s_waitcnt lgkmcnt(0)
	v_max_f32_e32 v9, v9, v9
	v_max_f32_e32 v8, v8, v9
	ds_bpermute_b32 v9, v172, v8
	s_waitcnt lgkmcnt(0)
	v_max_f32_e32 v9, v9, v9
	v_max_f32_e32 v52, v8, v9
	v_sub_f32_e32 v8, v68, v52
	v_mul_f32_e32 v8, 0x3d800000, v8
	v_sub_f32_e32 v9, v69, v52
	v_mul_f32_e32 v8, 0x3fb8aa3b, v8
	v_mul_f32_e32 v9, 0x3d800000, v9
	v_exp_f32_e32 v8, v8
	v_mul_f32_e32 v9, 0x3fb8aa3b, v9
	v_exp_f32_e32 v9, v9
	v_sub_f32_e32 v56, v82, v52
	v_add_f32_e32 v10, 0, v8
	v_mul_f32_e32 v56, 0x3d800000, v56
	v_add_f32_e32 v11, v9, v10
	v_sub_f32_e32 v10, v70, v52
	v_mul_f32_e32 v10, 0x3d800000, v10
	v_mul_f32_e32 v10, 0x3fb8aa3b, v10
	v_exp_f32_e32 v10, v10
	v_mul_f32_e32 v56, 0x3fb8aa3b, v56
	v_exp_f32_e32 v60, v56
	v_sub_f32_e32 v56, v83, v52
	v_add_f32_e32 v44, v10, v11
	v_sub_f32_e32 v11, v71, v52
	v_mul_f32_e32 v56, 0x3d800000, v56
	v_mul_f32_e32 v11, 0x3d800000, v11
	v_mul_f32_e32 v56, 0x3fb8aa3b, v56
	v_mul_f32_e32 v11, 0x3fb8aa3b, v11
	v_exp_f32_e32 v61, v56
	v_sub_f32_e32 v56, v84, v52
	v_exp_f32_e32 v11, v11
	v_mul_f32_e32 v56, 0x3d800000, v56
	v_mul_f32_e32 v56, 0x3fb8aa3b, v56
	v_exp_f32_e32 v62, v56
	v_sub_f32_e32 v56, v85, v52
	v_mul_f32_e32 v56, 0x3d800000, v56
	v_add_f32_e32 v45, v11, v44
	v_sub_f32_e32 v44, v72, v52
	v_mul_f32_e32 v56, 0x3fb8aa3b, v56
	v_mul_f32_e32 v44, 0x3d800000, v44
	v_exp_f32_e32 v63, v56
	v_sub_f32_e32 v56, v86, v52
	v_mul_f32_e32 v44, 0x3fb8aa3b, v44
	v_mul_f32_e32 v56, 0x3d800000, v56
	v_exp_f32_e32 v44, v44
	v_mul_f32_e32 v56, 0x3fb8aa3b, v56
	v_exp_f32_e32 v64, v56
	v_sub_f32_e32 v56, v87, v52
	v_mul_f32_e32 v56, 0x3d800000, v56
	v_mul_f32_e32 v56, 0x3fb8aa3b, v56
	v_add_f32_e32 v46, v44, v45
	v_sub_f32_e32 v45, v73, v52
	v_exp_f32_e32 v65, v56
	v_sub_f32_e32 v56, v88, v52
	v_mul_f32_e32 v45, 0x3d800000, v45
	v_mul_f32_e32 v56, 0x3d800000, v56
	v_mul_f32_e32 v45, 0x3fb8aa3b, v45
	v_mul_f32_e32 v56, 0x3fb8aa3b, v56
	v_exp_f32_e32 v45, v45
	v_exp_f32_e32 v66, v56
	v_sub_f32_e32 v56, v89, v52
	v_mul_f32_e32 v56, 0x3d800000, v56
	v_mul_f32_e32 v56, 0x3fb8aa3b, v56
	v_exp_f32_e32 v67, v56
	v_sub_f32_e32 v56, v90, v52
	v_add_f32_e32 v47, v45, v46
	v_sub_f32_e32 v46, v74, v52
	v_mul_f32_e32 v56, 0x3d800000, v56
	v_mul_f32_e32 v46, 0x3d800000, v46
	v_mul_f32_e32 v56, 0x3fb8aa3b, v56
	v_mul_f32_e32 v46, 0x3fb8aa3b, v46
	v_exp_f32_e32 v68, v56
	v_sub_f32_e32 v56, v91, v52
	v_exp_f32_e32 v46, v46
	v_mul_f32_e32 v56, 0x3d800000, v56
	v_mul_f32_e32 v56, 0x3fb8aa3b, v56
	v_exp_f32_e32 v69, v56
	v_sub_f32_e32 v56, v92, v52
	v_mul_f32_e32 v56, 0x3d800000, v56
	v_add_f32_e32 v48, v46, v47
	v_sub_f32_e32 v47, v75, v52
	v_mul_f32_e32 v56, 0x3fb8aa3b, v56
	v_mul_f32_e32 v47, 0x3d800000, v47
	v_exp_f32_e32 v70, v56
	v_sub_f32_e32 v56, v93, v52
	v_mul_f32_e32 v47, 0x3fb8aa3b, v47
	v_mul_f32_e32 v56, 0x3d800000, v56
	v_exp_f32_e32 v47, v47
	v_mul_f32_e32 v56, 0x3fb8aa3b, v56
	v_exp_f32_e32 v71, v56
	v_sub_f32_e32 v56, v94, v52
	v_mul_f32_e32 v56, 0x3d800000, v56
	v_mul_f32_e32 v56, 0x3fb8aa3b, v56
	v_add_f32_e32 v49, v47, v48
	v_sub_f32_e32 v48, v76, v52
	v_exp_f32_e32 v72, v56
	v_sub_f32_e32 v56, v95, v52
	v_mul_f32_e32 v48, 0x3d800000, v48
	v_mul_f32_e32 v56, 0x3d800000, v56
	v_mul_f32_e32 v48, 0x3fb8aa3b, v48
	v_mul_f32_e32 v56, 0x3fb8aa3b, v56
	v_exp_f32_e32 v48, v48
	v_exp_f32_e32 v73, v56
	v_sub_f32_e32 v56, v96, v52
	v_mul_f32_e32 v56, 0x3d800000, v56
	v_mul_f32_e32 v56, 0x3fb8aa3b, v56
	v_exp_f32_e32 v74, v56
	v_sub_f32_e32 v56, v97, v52
	v_add_f32_e32 v50, v48, v49
	v_sub_f32_e32 v49, v77, v52
	v_mul_f32_e32 v56, 0x3d800000, v56
	v_mul_f32_e32 v49, 0x3d800000, v49
	v_mul_f32_e32 v56, 0x3fb8aa3b, v56
	v_mul_f32_e32 v49, 0x3fb8aa3b, v49
	v_exp_f32_e32 v75, v56
	v_sub_f32_e32 v56, v98, v52
	v_exp_f32_e32 v49, v49
	v_mul_f32_e32 v56, 0x3d800000, v56
	v_mul_f32_e32 v56, 0x3fb8aa3b, v56
	v_exp_f32_e32 v76, v56
	v_sub_f32_e32 v56, v99, v52
	v_mul_f32_e32 v56, 0x3d800000, v56
	v_add_f32_e32 v51, v49, v50
	v_sub_f32_e32 v50, v78, v52
	v_mul_f32_e32 v56, 0x3fb8aa3b, v56
	v_mul_f32_e32 v50, 0x3d800000, v50
	v_exp_f32_e32 v77, v56
	v_sub_f32_e32 v56, v100, v52
	v_mul_f32_e32 v50, 0x3fb8aa3b, v50
	v_mul_f32_e32 v56, 0x3d800000, v56
	v_exp_f32_e32 v50, v50
	v_mul_f32_e32 v56, 0x3fb8aa3b, v56
	v_exp_f32_e32 v78, v56
	v_sub_f32_e32 v56, v101, v52
	v_mul_f32_e32 v56, 0x3d800000, v56
	v_mul_f32_e32 v56, 0x3fb8aa3b, v56
	v_add_f32_e32 v53, v50, v51
	v_sub_f32_e32 v51, v79, v52
	v_exp_f32_e32 v79, v56
	v_sub_f32_e32 v56, v102, v52
	v_mul_f32_e32 v56, 0x3d800000, v56
	v_mul_f32_e32 v56, 0x3fb8aa3b, v56
	v_sub_f32_e32 v54, v80, v52
	v_exp_f32_e32 v80, v56
	v_sub_f32_e32 v56, v103, v52
	v_mul_f32_e32 v56, 0x3d800000, v56
	v_mul_f32_e32 v56, 0x3fb8aa3b, v56
	v_sub_f32_e32 v55, v81, v52
	v_exp_f32_e32 v81, v56
	v_sub_f32_e32 v56, v104, v52
	v_mul_f32_e32 v56, 0x3d800000, v56
	v_mul_f32_e32 v56, 0x3fb8aa3b, v56
	v_exp_f32_e32 v82, v56
	v_sub_f32_e32 v56, v105, v52
	v_mul_f32_e32 v56, 0x3d800000, v56
	v_mul_f32_e32 v56, 0x3fb8aa3b, v56
	v_exp_f32_e32 v83, v56
	v_sub_f32_e32 v56, v106, v52
	v_mul_f32_e32 v56, 0x3d800000, v56
	v_mul_f32_e32 v56, 0x3fb8aa3b, v56
	v_exp_f32_e32 v84, v56
	v_sub_f32_e32 v56, v107, v52
	v_mul_f32_e32 v56, 0x3d800000, v56
	v_mul_f32_e32 v56, 0x3fb8aa3b, v56
	v_exp_f32_e32 v85, v56
	v_sub_f32_e32 v56, v108, v52
	v_mul_f32_e32 v56, 0x3d800000, v56
	v_mul_f32_e32 v56, 0x3fb8aa3b, v56
	v_exp_f32_e32 v86, v56
	v_sub_f32_e32 v56, v109, v52
	v_mul_f32_e32 v56, 0x3d800000, v56
	v_mul_f32_e32 v56, 0x3fb8aa3b, v56
	v_exp_f32_e32 v87, v56
	v_sub_f32_e32 v56, v110, v52
	v_mul_f32_e32 v56, 0x3d800000, v56
	v_mul_f32_e32 v56, 0x3fb8aa3b, v56
	v_exp_f32_e32 v88, v56
	v_sub_f32_e32 v56, v111, v52
	v_mul_f32_e32 v51, 0x3d800000, v51
	v_mul_f32_e32 v56, 0x3d800000, v56
	v_mul_f32_e32 v51, 0x3fb8aa3b, v51
	v_mul_f32_e32 v54, 0x3d800000, v54
	v_mul_f32_e32 v56, 0x3fb8aa3b, v56
	v_exp_f32_e32 v51, v51
	v_mul_f32_e32 v54, 0x3fb8aa3b, v54
	v_mul_f32_e32 v55, 0x3d800000, v55
	v_exp_f32_e32 v89, v56
	v_sub_f32_e32 v56, v112, v52
	v_exp_f32_e32 v54, v54
	v_mul_f32_e32 v55, 0x3fb8aa3b, v55
	v_mul_f32_e32 v56, 0x3d800000, v56
	v_exp_f32_e32 v55, v55
	v_mul_f32_e32 v56, 0x3fb8aa3b, v56
	v_exp_f32_e32 v90, v56
	v_sub_f32_e32 v56, v113, v52
	v_add_f32_e32 v53, v51, v53
	v_mul_f32_e32 v56, 0x3d800000, v56
	v_add_f32_e32 v53, v54, v53
	v_mul_f32_e32 v56, 0x3fb8aa3b, v56
	v_add_f32_e32 v53, v55, v53
	v_exp_f32_e32 v91, v56
	v_sub_f32_e32 v56, v114, v52
	v_add_f32_e32 v53, v60, v53
	v_mul_f32_e32 v56, 0x3d800000, v56
	v_add_f32_e32 v53, v61, v53
	v_mul_f32_e32 v56, 0x3fb8aa3b, v56
	v_add_f32_e32 v53, v62, v53
	v_exp_f32_e32 v92, v56
	v_sub_f32_e32 v56, v115, v52
	v_add_f32_e32 v53, v63, v53
	v_mul_f32_e32 v56, 0x3d800000, v56
	v_add_f32_e32 v53, v64, v53
	v_mul_f32_e32 v56, 0x3fb8aa3b, v56
	v_add_f32_e32 v53, v65, v53
	v_exp_f32_e32 v93, v56
	v_sub_f32_e32 v56, v116, v52
	v_add_f32_e32 v53, v66, v53
	v_mul_f32_e32 v56, 0x3d800000, v56
	v_add_f32_e32 v53, v67, v53
	v_mul_f32_e32 v56, 0x3fb8aa3b, v56
	v_add_f32_e32 v53, v68, v53
	v_exp_f32_e32 v139, v56
	v_sub_f32_e32 v56, v117, v52
	v_add_f32_e32 v53, v69, v53
	v_mul_f32_e32 v56, 0x3d800000, v56
	v_add_f32_e32 v53, v70, v53
	v_mul_f32_e32 v56, 0x3fb8aa3b, v56
	v_add_f32_e32 v53, v71, v53
	v_exp_f32_e32 v140, v56
	v_sub_f32_e32 v56, v118, v52
	v_add_f32_e32 v53, v72, v53
	v_mul_f32_e32 v56, 0x3d800000, v56
	v_add_f32_e32 v53, v73, v53
	v_mul_f32_e32 v56, 0x3fb8aa3b, v56
	v_add_f32_e32 v53, v74, v53
	v_exp_f32_e32 v141, v56
	v_sub_f32_e32 v56, v119, v52
	v_add_f32_e32 v53, v75, v53
	v_mul_f32_e32 v56, 0x3d800000, v56
	v_add_f32_e32 v53, v76, v53
	v_mul_f32_e32 v56, 0x3fb8aa3b, v56
	v_add_f32_e32 v53, v77, v53
	v_exp_f32_e32 v142, v56
	v_sub_f32_e32 v56, v120, v52
	v_add_f32_e32 v53, v78, v53
	v_mul_f32_e32 v56, 0x3d800000, v56
	v_add_f32_e32 v53, v79, v53
	v_mul_f32_e32 v56, 0x3fb8aa3b, v56
	v_add_f32_e32 v53, v80, v53
	v_exp_f32_e32 v143, v56
	v_sub_f32_e32 v56, v121, v52
	v_add_f32_e32 v53, v81, v53
	v_mul_f32_e32 v56, 0x3d800000, v56
	v_add_f32_e32 v53, v82, v53
	v_mul_f32_e32 v56, 0x3fb8aa3b, v56
	v_add_f32_e32 v53, v83, v53
	v_exp_f32_e32 v144, v56
	v_sub_f32_e32 v56, v122, v52
	v_add_f32_e32 v53, v84, v53
	v_mul_f32_e32 v56, 0x3d800000, v56
	v_add_f32_e32 v53, v85, v53
	v_mul_f32_e32 v56, 0x3fb8aa3b, v56
	v_add_f32_e32 v53, v86, v53
	v_exp_f32_e32 v145, v56
	v_sub_f32_e32 v56, v123, v52
	v_add_f32_e32 v53, v87, v53
	v_mul_f32_e32 v56, 0x3d800000, v56
	v_add_f32_e32 v53, v88, v53
	v_mul_f32_e32 v56, 0x3fb8aa3b, v56
	v_add_f32_e32 v53, v89, v53
	v_exp_f32_e32 v146, v56
	v_sub_f32_e32 v56, v124, v52
	v_add_f32_e32 v53, v90, v53
	v_mul_f32_e32 v56, 0x3d800000, v56
	v_add_f32_e32 v53, v91, v53
	v_mul_f32_e32 v56, 0x3fb8aa3b, v56
	v_add_f32_e32 v53, v92, v53
	v_exp_f32_e32 v147, v56
	v_sub_f32_e32 v56, v125, v52
	v_add_f32_e32 v53, v93, v53
	v_mul_f32_e32 v56, 0x3d800000, v56
	v_add_f32_e32 v53, v139, v53
	v_mul_f32_e32 v56, 0x3fb8aa3b, v56
	v_add_f32_e32 v53, v140, v53
	v_exp_f32_e32 v148, v56
	v_sub_f32_e32 v56, v126, v52
	v_add_f32_e32 v53, v141, v53
	v_mul_f32_e32 v56, 0x3d800000, v56
	v_add_f32_e32 v53, v142, v53
	v_mul_f32_e32 v56, 0x3fb8aa3b, v56
	v_add_f32_e32 v53, v143, v53
	v_exp_f32_e32 v149, v56
	v_sub_f32_e32 v56, v127, v52
	v_add_f32_e32 v53, v144, v53
	v_mul_f32_e32 v56, 0x3d800000, v56
	v_sub_f32_e32 v4, v4, v52
	v_add_f32_e32 v53, v145, v53
	v_mul_f32_e32 v56, 0x3fb8aa3b, v56
	v_mul_f32_e32 v4, 0x3d800000, v4
	v_sub_f32_e32 v5, v5, v52
	v_add_f32_e32 v53, v146, v53
	v_exp_f32_e32 v150, v56
	v_mul_f32_e32 v4, 0x3fb8aa3b, v4
	v_mul_f32_e32 v5, 0x3d800000, v5
	v_add_f32_e32 v53, v147, v53
	v_exp_f32_e32 v151, v4
	v_mul_f32_e32 v5, 0x3fb8aa3b, v5
	v_add_f32_e32 v53, v148, v53
	v_exp_f32_e32 v152, v5
	v_sub_f32_e32 v5, v6, v52
	v_add_f32_e32 v53, v149, v53
	v_mul_f32_e32 v5, 0x3d800000, v5
	v_add_f32_e32 v53, v150, v53
	v_mul_f32_e32 v5, 0x3fb8aa3b, v5
	v_add_f32_e32 v4, v151, v53
	v_exp_f32_e32 v153, v5
	v_sub_f32_e32 v5, v7, v52
	v_cvt_pk_bf16_f32 v52, v48, v49
	v_cvt_pk_bf16_f32 v53, v50, v51
	v_cvt_pk_bf16_f32 v54, v54, v55
	v_cvt_pk_bf16_f32 v55, v60, v61
	v_cvt_pk_bf16_f32 v48, v62, v63
	v_cvt_pk_bf16_f32 v49, v64, v65
	v_cvt_pk_bf16_f32 v50, v66, v67
	v_cvt_pk_bf16_f32 v51, v68, v69
	ds_read_b64_tr_b16 v[204:205], v169
	ds_read_b64_tr_b16 v[206:207], v169 offset:8448
	ds_read_b64_tr_b16 v[208:209], v169 offset:16896
	ds_read_b64_tr_b16 v[210:211], v169 offset:25344
	ds_read_b64_tr_b16 v[218:219], v169 offset:32
	ds_read_b64_tr_b16 v[220:221], v169 offset:8480
	ds_read_b64_tr_b16 v[224:225], v169 offset:16928
	ds_read_b64_tr_b16 v[226:227], v169 offset:25376
	ds_read_b64_tr_b16 v[228:229], v169 offset:64
	ds_read_b64_tr_b16 v[230:231], v169 offset:8512
	ds_read_b64_tr_b16 v[232:233], v169 offset:16960
	ds_read_b64_tr_b16 v[234:235], v169 offset:25408
	ds_read_b64_tr_b16 v[236:237], v169 offset:96
	ds_read_b64_tr_b16 v[238:239], v169 offset:8544
	ds_read_b64_tr_b16 v[240:241], v169 offset:16992
	ds_read_b64_tr_b16 v[242:243], v169 offset:25440
	v_cvt_pk_bf16_f32 v56, v8, v9
	v_cvt_pk_bf16_f32 v57, v10, v11
	v_cvt_pk_bf16_f32 v58, v44, v45
	v_cvt_pk_bf16_f32 v59, v46, v47
	v_cvt_pk_bf16_f32 v44, v70, v71
	v_cvt_pk_bf16_f32 v45, v72, v73
	s_nop 1
	s_waitcnt lgkmcnt(14)
	v_mfma_f32_16x16x32_bf16 v[60:63], v[204:207], v[56:59], 0
	ds_read_b64_tr_b16 v[204:205], v169 offset:128
	ds_read_b64_tr_b16 v[206:207], v169 offset:8576
	v_cvt_pk_bf16_f32 v46, v74, v75
	v_cvt_pk_bf16_f32 v47, v76, v77
	v_cvt_pk_bf16_f32 v8, v78, v79
	s_nop 1
	s_waitcnt lgkmcnt(14)
	v_mfma_f32_16x16x32_bf16 v[60:63], v[208:211], v[52:55], v[60:63]
	ds_read_b64_tr_b16 v[208:209], v169 offset:17024
	ds_read_b64_tr_b16 v[210:211], v169 offset:25472
	v_mul_f32_e32 v5, 0x3d800000, v5
	v_mul_f32_e32 v5, 0x3fb8aa3b, v5
	s_nop 1
	s_waitcnt lgkmcnt(14)
	v_mfma_f32_16x16x32_bf16 v[64:67], v[218:221], v[56:59], 0
	ds_read_b64_tr_b16 v[218:219], v169 offset:160
	ds_read_b64_tr_b16 v[220:221], v169 offset:8608
	v_exp_f32_e32 v154, v5
	v_add_f32_e32 v4, v152, v4
	v_add_f32_e32 v4, v153, v4
	s_nop 1
	s_waitcnt lgkmcnt(14)
	v_mfma_f32_16x16x32_bf16 v[64:67], v[224:227], v[52:55], v[64:67]
	ds_read_b64_tr_b16 v[224:225], v169 offset:17056
	ds_read_b64_tr_b16 v[226:227], v169 offset:25504
	v_cvt_pk_bf16_f32 v9, v80, v81
	v_cvt_pk_bf16_f32 v10, v82, v83
	s_nop 1
	s_waitcnt lgkmcnt(14)
	v_mfma_f32_16x16x32_bf16 v[68:71], v[228:231], v[56:59], 0
	ds_read_b64_tr_b16 v[228:229], v169 offset:192
	ds_read_b64_tr_b16 v[230:231], v169 offset:8640
	v_add_f32_e32 v4, v154, v4
	ds_bpermute_b32 v5, v171, v4
	v_cvt_pk_bf16_f32 v11, v84, v85
	s_nop 1
	s_waitcnt lgkmcnt(15)
	v_mfma_f32_16x16x32_bf16 v[68:71], v[232:235], v[52:55], v[68:71]
	ds_read_b64_tr_b16 v[232:233], v169 offset:17088
	ds_read_b64_tr_b16 v[234:235], v169 offset:25536
	v_cvt_pk_bf16_f32 v6, v90, v91
	s_waitcnt lgkmcnt(2)
	v_add_f32_e32 v137, v4, v5
	s_nop 1
	s_waitcnt lgkmcnt(15)
	v_mfma_f32_16x16x32_bf16 v[72:75], v[236:239], v[56:59], 0
	ds_read_b64_tr_b16 v[236:237], v169 offset:224
	ds_read_b64_tr_b16 v[238:239], v169 offset:8672
	v_cvt_pk_bf16_f32 v4, v86, v87
	v_cvt_pk_bf16_f32 v5, v88, v89
	v_cvt_pk_bf16_f32 v7, v92, v93
	s_nop 1
	s_waitcnt lgkmcnt(15)
	v_mfma_f32_16x16x32_bf16 v[108:111], v[240:243], v[52:55], v[72:75]
	ds_read_b64_tr_b16 v[240:241], v169 offset:17120
	ds_read_b64_tr_b16 v[242:243], v169 offset:25568
	s_nop 2
	ds_bpermute_b32 v138, v172, v137
	s_waitcnt lgkmcnt(15)
	v_mfma_f32_16x16x32_bf16 v[72:75], v[204:207], v[56:59], 0
	ds_read_b64_tr_b16 v[204:205], v169 offset:256
	ds_read_b64_tr_b16 v[206:207], v169 offset:8704
	s_waitcnt lgkmcnt(15)
	v_mfma_f32_16x16x32_bf16 v[72:75], v[208:211], v[52:55], v[72:75]
	ds_read_b64_tr_b16 v[208:209], v169 offset:17152
	ds_read_b64_tr_b16 v[210:211], v169 offset:25600
	s_waitcnt lgkmcnt(15)
	v_mfma_f32_16x16x32_bf16 v[76:79], v[218:221], v[56:59], 0
	ds_read_b64_tr_b16 v[218:219], v169 offset:288
	ds_read_b64_tr_b16 v[220:221], v169 offset:8736
	s_waitcnt lgkmcnt(15)
	v_mfma_f32_16x16x32_bf16 v[76:79], v[224:227], v[52:55], v[76:79]
	ds_read_b64_tr_b16 v[224:225], v169 offset:17184
	ds_read_b64_tr_b16 v[226:227], v169 offset:25632
	s_waitcnt lgkmcnt(15)
	v_mfma_f32_16x16x32_bf16 v[80:83], v[228:231], v[56:59], 0
	ds_read_b64_tr_b16 v[228:229], v169 offset:320
	ds_read_b64_tr_b16 v[230:231], v169 offset:8768
	s_waitcnt lgkmcnt(15)
	v_mfma_f32_16x16x32_bf16 v[80:83], v[232:235], v[52:55], v[80:83]
	ds_read_b64_tr_b16 v[232:233], v169 offset:17216
	ds_read_b64_tr_b16 v[234:235], v169 offset:25664
	s_waitcnt lgkmcnt(15)
	v_mfma_f32_16x16x32_bf16 v[84:87], v[236:239], v[56:59], 0
	ds_read_b64_tr_b16 v[236:237], v169 offset:352
	ds_read_b64_tr_b16 v[238:239], v169 offset:8800
	s_waitcnt lgkmcnt(15)
	v_mfma_f32_16x16x32_bf16 v[112:115], v[240:243], v[52:55], v[84:87]
	ds_read_b64_tr_b16 v[240:241], v169 offset:17248
	ds_read_b64_tr_b16 v[242:243], v169 offset:25696
	s_nop 5
	s_waitcnt lgkmcnt(14)
	v_mfma_f32_16x16x32_bf16 v[84:87], v[204:207], v[56:59], 0
	ds_read_b64_tr_b16 v[204:205], v169 offset:384
	ds_read_b64_tr_b16 v[206:207], v169 offset:8832
	s_waitcnt lgkmcnt(14)
	v_mfma_f32_16x16x32_bf16 v[84:87], v[208:211], v[52:55], v[84:87]
	ds_read_b64_tr_b16 v[208:209], v169 offset:17280
	ds_read_b64_tr_b16 v[210:211], v169 offset:25728
	s_waitcnt lgkmcnt(14)
	v_mfma_f32_16x16x32_bf16 v[88:91], v[218:221], v[56:59], 0
	ds_read_b64_tr_b16 v[218:219], v169 offset:416
	ds_read_b64_tr_b16 v[220:221], v169 offset:8864
	s_waitcnt lgkmcnt(14)
	v_mfma_f32_16x16x32_bf16 v[88:91], v[224:227], v[52:55], v[88:91]
	ds_read_b64_tr_b16 v[224:225], v169 offset:17312
	ds_read_b64_tr_b16 v[226:227], v169 offset:25760
	s_waitcnt lgkmcnt(14)
	v_mfma_f32_16x16x32_bf16 v[92:95], v[228:231], v[56:59], 0
	ds_read_b64_tr_b16 v[228:229], v169 offset:448
	ds_read_b64_tr_b16 v[230:231], v169 offset:8896
	s_waitcnt lgkmcnt(14)
	v_mfma_f32_16x16x32_bf16 v[92:95], v[232:235], v[52:55], v[92:95]
	ds_read_b64_tr_b16 v[232:233], v169 offset:17344
	ds_read_b64_tr_b16 v[234:235], v169 offset:25792
	s_waitcnt lgkmcnt(14)
	v_mfma_f32_16x16x32_bf16 v[96:99], v[236:239], v[56:59], 0
	ds_read_b64_tr_b16 v[236:237], v169 offset:480
	ds_read_b64_tr_b16 v[238:239], v169 offset:8928
	s_waitcnt lgkmcnt(14)
	v_mfma_f32_16x16x32_bf16 v[116:119], v[240:243], v[52:55], v[96:99]
	s_nop 5
	s_waitcnt lgkmcnt(12)
	v_mfma_f32_16x16x32_bf16 v[96:99], v[204:207], v[56:59], 0
	s_waitcnt lgkmcnt(10)
	v_mfma_f32_16x16x32_bf16 v[96:99], v[208:211], v[52:55], v[96:99]
	s_waitcnt lgkmcnt(8)
	v_mfma_f32_16x16x32_bf16 v[100:103], v[218:221], v[56:59], 0
	s_waitcnt lgkmcnt(6)
	v_mfma_f32_16x16x32_bf16 v[100:103], v[224:227], v[52:55], v[100:103]
	s_waitcnt lgkmcnt(4)
	v_mfma_f32_16x16x32_bf16 v[104:107], v[228:231], v[56:59], 0
	s_waitcnt lgkmcnt(2)
	v_mfma_f32_16x16x32_bf16 v[104:107], v[232:235], v[52:55], v[104:107]
	ds_read_b64_tr_b16 v[124:125], v169 offset:17376
	ds_read_b64_tr_b16 v[126:127], v169 offset:25824
	s_waitcnt vmcnt(7)
	ds_write_b128 v168, v[12:15]
	s_waitcnt vmcnt(6)
	ds_write_b128 v168, v[16:19] offset:128
	s_waitcnt vmcnt(5)
	ds_write_b128 v168, v[20:23] offset:256
	s_waitcnt vmcnt(4)
	ds_write_b128 v168, v[24:27] offset:384
	global_load_dwordx4 v[12:15], v[160:161], off offset:2048
	global_load_dwordx4 v[16:19], v[160:161], off offset:2176
	global_load_dwordx4 v[20:23], v[160:161], off offset:2304
	global_load_dwordx4 v[24:27], v[160:161], off offset:2432
	s_waitcnt lgkmcnt(6)
	v_mfma_f32_16x16x32_bf16 v[56:59], v[236:239], v[56:59], 0
	s_nop 7
	s_waitcnt lgkmcnt(0)
	s_barrier
	s_waitcnt lgkmcnt(4)
	v_mfma_f32_16x16x32_bf16 v[120:123], v[124:127], v[52:55], v[56:59]
	ds_read_b64_tr_b16 v[204:205], v3
	ds_read_b64_tr_b16 v[206:207], v3 offset:8448
	ds_read_b64_tr_b16 v[208:209], v3 offset:32
	ds_read_b64_tr_b16 v[210:211], v3 offset:8480
	ds_read_b64_tr_b16 v[218:219], v3 offset:16928
	ds_read_b64_tr_b16 v[220:221], v3 offset:25376
	ds_read_b64_tr_b16 v[224:225], v3 offset:64
	ds_read_b64_tr_b16 v[226:227], v3 offset:8512
	ds_read_b64_tr_b16 v[228:229], v3 offset:16960
	ds_read_b64_tr_b16 v[230:231], v3 offset:25408
	ds_read_b64_tr_b16 v[232:233], v3 offset:96
	ds_read_b64_tr_b16 v[234:235], v3 offset:8544
	ds_read_b64_tr_b16 v[236:237], v3 offset:16992
	ds_read_b64_tr_b16 v[238:239], v3 offset:25440
	ds_read_b64_tr_b16 v[240:241], v3 offset:128
	ds_read_b64_tr_b16 v[242:243], v3 offset:8576
	s_nop 3
	s_waitcnt lgkmcnt(14)
	v_mfma_f32_16x16x32_bf16 v[52:55], v[204:207], v[48:51], v[60:63]
	ds_read_b64_tr_b16 v[204:205], v3 offset:17024
	ds_read_b64_tr_b16 v[206:207], v3 offset:25472
	s_nop 1
	s_waitcnt lgkmcnt(14)
	v_mfma_f32_16x16x32_bf16 v[56:59], v[208:211], v[48:51], v[64:67]
	ds_read_b64_tr_b16 v[208:209], v3 offset:160
	ds_read_b64_tr_b16 v[210:211], v3 offset:8608
	s_waitcnt lgkmcnt(14)
	v_mfma_f32_16x16x32_bf16 v[56:59], v[218:221], v[44:47], v[56:59]
	ds_read_b64_tr_b16 v[218:219], v3 offset:17056
	ds_read_b64_tr_b16 v[220:221], v3 offset:25504
	s_waitcnt lgkmcnt(14)
	v_mfma_f32_16x16x32_bf16 v[60:63], v[224:227], v[48:51], v[68:71]
	ds_read_b64_tr_b16 v[224:225], v3 offset:192
	ds_read_b64_tr_b16 v[226:227], v3 offset:8640
	s_waitcnt lgkmcnt(14)
	v_mfma_f32_16x16x32_bf16 v[60:63], v[228:231], v[44:47], v[60:63]
	ds_read_b64_tr_b16 v[228:229], v3 offset:16896
	ds_read_b64_tr_b16 v[230:231], v3 offset:25344
	s_waitcnt lgkmcnt(14)
	v_mfma_f32_16x16x32_bf16 v[64:67], v[232:235], v[48:51], v[108:111]
	ds_read_b64_tr_b16 v[232:233], v3 offset:17088
	ds_read_b64_tr_b16 v[234:235], v3 offset:25536
	s_waitcnt lgkmcnt(14)
	v_mfma_f32_16x16x32_bf16 v[64:67], v[236:239], v[44:47], v[64:67]
	ds_read_b64_tr_b16 v[236:237], v3 offset:224
	ds_read_b64_tr_b16 v[238:239], v3 offset:8672
	s_waitcnt lgkmcnt(14)
	v_mfma_f32_16x16x32_bf16 v[68:71], v[240:243], v[48:51], v[72:75]
	ds_read_b64_tr_b16 v[240:241], v3 offset:17120
	ds_read_b64_tr_b16 v[242:243], v3 offset:25568
	s_waitcnt lgkmcnt(14)
	v_mfma_f32_16x16x32_bf16 v[68:71], v[204:207], v[44:47], v[68:71]
	ds_read_b64_tr_b16 v[204:205], v3 offset:256
	ds_read_b64_tr_b16 v[206:207], v3 offset:8704
	s_nop 0
	s_waitcnt lgkmcnt(14)
	v_mfma_f32_16x16x32_bf16 v[72:75], v[208:211], v[48:51], v[76:79]
	ds_read_b64_tr_b16 v[208:209], v3 offset:17152
	ds_read_b64_tr_b16 v[210:211], v3 offset:25600
	s_waitcnt lgkmcnt(14)
	v_mfma_f32_16x16x32_bf16 v[108:111], v[218:221], v[44:47], v[72:75]
	ds_read_b64_tr_b16 v[218:219], v3 offset:288
	ds_read_b64_tr_b16 v[220:221], v3 offset:8736
	s_nop 5
	s_waitcnt lgkmcnt(14)
	v_mfma_f32_16x16x32_bf16 v[72:75], v[224:227], v[48:51], v[80:83]
	ds_read_b64_tr_b16 v[224:225], v3 offset:17184
	ds_read_b64_tr_b16 v[226:227], v3 offset:25632
	s_waitcnt lgkmcnt(14)
	v_mfma_f32_16x16x32_bf16 v[52:55], v[228:231], v[44:47], v[52:55]
	ds_read_b64_tr_b16 v[228:229], v3 offset:320
	ds_read_b64_tr_b16 v[230:231], v3 offset:8768
	s_waitcnt lgkmcnt(14)
	v_mfma_f32_16x16x32_bf16 v[124:127], v[232:235], v[44:47], v[72:75]
	ds_read_b64_tr_b16 v[232:233], v3 offset:17216
	ds_read_b64_tr_b16 v[234:235], v3 offset:25664
	s_nop 4
	s_waitcnt lgkmcnt(14)
	v_mfma_f32_16x16x32_bf16 v[72:75], v[236:239], v[48:51], v[112:115]
	ds_read_b64_tr_b16 v[236:237], v3 offset:352
	ds_read_b64_tr_b16 v[238:239], v3 offset:8800
	s_waitcnt lgkmcnt(14)
	v_mfma_f32_16x16x32_bf16 v[132:135], v[240:243], v[44:47], v[72:75]
	ds_read_b64_tr_b16 v[240:241], v3 offset:17248
	ds_read_b64_tr_b16 v[242:243], v3 offset:25696
	s_nop 5
	s_waitcnt lgkmcnt(14)
	v_mfma_f32_16x16x32_bf16 v[72:75], v[204:207], v[48:51], v[84:87]
	ds_read_b64_tr_b16 v[204:205], v3 offset:384
	ds_read_b64_tr_b16 v[206:207], v3 offset:8832
	s_waitcnt lgkmcnt(14)
	v_mfma_f32_16x16x32_bf16 v[112:115], v[208:211], v[44:47], v[72:75]
	ds_read_b64_tr_b16 v[208:209], v3 offset:17280
	ds_read_b64_tr_b16 v[210:211], v3 offset:25728
	s_nop 5
	s_waitcnt lgkmcnt(14)
	v_mfma_f32_16x16x32_bf16 v[72:75], v[218:221], v[48:51], v[88:91]
	ds_read_b64_tr_b16 v[218:219], v3 offset:416
	ds_read_b64_tr_b16 v[220:221], v3 offset:8864
	s_waitcnt lgkmcnt(14)
	v_mfma_f32_16x16x32_bf16 v[128:131], v[224:227], v[44:47], v[72:75]
	ds_read_b64_tr_b16 v[224:225], v3 offset:17312
	ds_read_b64_tr_b16 v[226:227], v3 offset:25760
	s_nop 5
	s_waitcnt lgkmcnt(14)
	v_mfma_f32_16x16x32_bf16 v[72:75], v[228:231], v[48:51], v[92:95]
	ds_read_b64_tr_b16 v[228:229], v3 offset:448
	ds_read_b64_tr_b16 v[230:231], v3 offset:8896
	s_waitcnt lgkmcnt(14)
	v_mfma_f32_16x16x32_bf16 v[92:95], v[232:235], v[44:47], v[72:75]
	ds_read_b64_tr_b16 v[232:233], v3 offset:17344
	ds_read_b64_tr_b16 v[234:235], v3 offset:25792
	s_nop 5
	s_waitcnt lgkmcnt(14)
	v_mfma_f32_16x16x32_bf16 v[72:75], v[236:239], v[48:51], v[116:119]
	s_waitcnt lgkmcnt(12)
	v_mfma_f32_16x16x32_bf16 v[116:119], v[240:243], v[44:47], v[72:75]
	s_nop 5
	s_waitcnt lgkmcnt(10)
	v_mfma_f32_16x16x32_bf16 v[72:75], v[204:207], v[48:51], v[96:99]
	s_waitcnt lgkmcnt(8)
	v_mfma_f32_16x16x32_bf16 v[96:99], v[208:211], v[44:47], v[72:75]
	s_nop 5
	s_waitcnt lgkmcnt(6)
	v_mfma_f32_16x16x32_bf16 v[72:75], v[218:221], v[48:51], v[100:103]
	s_waitcnt lgkmcnt(4)
	v_mfma_f32_16x16x32_bf16 v[100:103], v[224:227], v[44:47], v[72:75]
	s_nop 5
	s_waitcnt lgkmcnt(2)
	v_mfma_f32_16x16x32_bf16 v[72:75], v[228:231], v[48:51], v[104:107]
	s_waitcnt lgkmcnt(0)
	v_mfma_f32_16x16x32_bf16 v[104:107], v[232:235], v[44:47], v[72:75]
	s_nop 7
	s_nop 5
	ds_read_b64_tr_b16 v[72:73], v3 offset:480
	ds_read_b64_tr_b16 v[74:75], v3 offset:8928
	ds_read_b64_tr_b16 v[76:77], v3 offset:17376
	ds_read_b64_tr_b16 v[78:79], v3 offset:25824
	s_waitcnt vmcnt(7)
	ds_write_b128 v170, v[28:31]
	s_waitcnt vmcnt(6)
	ds_write_b128 v170, v[32:35] offset:128
	s_waitcnt vmcnt(5)
	ds_write_b128 v170, v[36:39] offset:256
	s_waitcnt vmcnt(4)
	ds_write_b128 v170, v[40:43] offset:384
	s_waitcnt lgkmcnt(0)
	s_barrier
	ds_read_b64_tr_b16 v[204:205], v169
	ds_read_b64_tr_b16 v[206:207], v169 offset:8448
	ds_read_b64_tr_b16 v[208:209], v169 offset:16896
	ds_read_b64_tr_b16 v[210:211], v169 offset:25344
	ds_read_b64_tr_b16 v[218:219], v169 offset:32
	ds_read_b64_tr_b16 v[220:221], v169 offset:8480
	ds_read_b64_tr_b16 v[224:225], v169 offset:16928
	ds_read_b64_tr_b16 v[226:227], v169 offset:25376
	ds_read_b64_tr_b16 v[228:229], v169 offset:64
	ds_read_b64_tr_b16 v[230:231], v169 offset:8512
	ds_read_b64_tr_b16 v[232:233], v169 offset:16960
	ds_read_b64_tr_b16 v[234:235], v169 offset:25408
	ds_read_b64_tr_b16 v[236:237], v169 offset:96
	ds_read_b64_tr_b16 v[238:239], v169 offset:8544
	ds_read_b64_tr_b16 v[240:241], v169 offset:16992
	ds_read_b64_tr_b16 v[242:243], v169 offset:25440
	v_mfma_f32_16x16x32_bf16 v[48:51], v[72:75], v[48:51], v[120:123]
	s_waitcnt lgkmcnt(14)
	v_mfma_f32_16x16x32_bf16 v[28:31], v[204:207], v[8:11], v[52:55]
	ds_read_b64_tr_b16 v[204:205], v169 offset:128
	ds_read_b64_tr_b16 v[206:207], v169 offset:8576
	v_mfma_f32_16x16x32_bf16 v[88:91], v[76:79], v[44:47], v[48:51]
	s_waitcnt lgkmcnt(14)
	v_mfma_f32_16x16x32_bf16 v[76:79], v[208:211], v[4:7], v[28:31]
	ds_read_b64_tr_b16 v[208:209], v169 offset:17024
	ds_read_b64_tr_b16 v[210:211], v169 offset:25472
	s_nop 3
	s_waitcnt lgkmcnt(14)
	v_mfma_f32_16x16x32_bf16 v[32:35], v[218:221], v[8:11], v[56:59]
	ds_read_b64_tr_b16 v[218:219], v169 offset:160
	ds_read_b64_tr_b16 v[220:221], v169 offset:8608
	s_waitcnt lgkmcnt(14)
	v_mfma_f32_16x16x32_bf16 v[80:83], v[224:227], v[4:7], v[32:35]
	ds_read_b64_tr_b16 v[224:225], v169 offset:17056
	ds_read_b64_tr_b16 v[226:227], v169 offset:25504
	s_nop 3
	s_waitcnt lgkmcnt(14)
	v_mfma_f32_16x16x32_bf16 v[28:31], v[228:231], v[8:11], v[60:63]
	ds_read_b64_tr_b16 v[228:229], v169 offset:192
	ds_read_b64_tr_b16 v[230:231], v169 offset:8640
	s_waitcnt lgkmcnt(14)
	v_mfma_f32_16x16x32_bf16 v[84:87], v[232:235], v[4:7], v[28:31]
	ds_read_b64_tr_b16 v[232:233], v169 offset:17088
	ds_read_b64_tr_b16 v[234:235], v169 offset:25536
	s_nop 5
	s_waitcnt lgkmcnt(14)
	v_mfma_f32_16x16x32_bf16 v[28:31], v[236:239], v[8:11], v[64:67]
	ds_read_b64_tr_b16 v[236:237], v169 offset:224
	ds_read_b64_tr_b16 v[238:239], v169 offset:8672
	s_waitcnt lgkmcnt(14)
	v_mfma_f32_16x16x32_bf16 v[72:75], v[240:243], v[4:7], v[28:31]
	ds_read_b64_tr_b16 v[240:241], v169 offset:17120
	ds_read_b64_tr_b16 v[242:243], v169 offset:25568
	s_nop 5
	s_waitcnt lgkmcnt(14)
	v_mfma_f32_16x16x32_bf16 v[28:31], v[204:207], v[8:11], v[68:71]
	ds_read_b64_tr_b16 v[204:205], v169 offset:256
	ds_read_b64_tr_b16 v[206:207], v169 offset:8704
	s_waitcnt lgkmcnt(14)
	v_mfma_f32_16x16x32_bf16 v[28:31], v[208:211], v[4:7], v[28:31]
	ds_read_b64_tr_b16 v[208:209], v169 offset:17152
	ds_read_b64_tr_b16 v[210:211], v169 offset:25600
	s_waitcnt lgkmcnt(14)
	v_mfma_f32_16x16x32_bf16 v[32:35], v[218:221], v[8:11], v[108:111]
	ds_read_b64_tr_b16 v[218:219], v169 offset:288
	ds_read_b64_tr_b16 v[220:221], v169 offset:8736
	s_waitcnt lgkmcnt(14)
	v_mfma_f32_16x16x32_bf16 v[32:35], v[224:227], v[4:7], v[32:35]
	ds_read_b64_tr_b16 v[224:225], v169 offset:17184
	ds_read_b64_tr_b16 v[226:227], v169 offset:25632
	s_waitcnt lgkmcnt(14)
	v_mfma_f32_16x16x32_bf16 v[36:39], v[228:231], v[8:11], v[124:127]
	ds_read_b64_tr_b16 v[228:229], v169 offset:320
	ds_read_b64_tr_b16 v[230:231], v169 offset:8768
	s_waitcnt lgkmcnt(14)
	v_mfma_f32_16x16x32_bf16 v[36:39], v[232:235], v[4:7], v[36:39]
	ds_read_b64_tr_b16 v[232:233], v169 offset:17216
	ds_read_b64_tr_b16 v[234:235], v169 offset:25664
	s_waitcnt lgkmcnt(14)
	v_mfma_f32_16x16x32_bf16 v[40:43], v[236:239], v[8:11], v[132:135]
	ds_read_b64_tr_b16 v[236:237], v169 offset:352
	ds_read_b64_tr_b16 v[238:239], v169 offset:8800
	s_waitcnt lgkmcnt(14)
	v_mfma_f32_16x16x32_bf16 v[64:67], v[240:243], v[4:7], v[40:43]
	ds_read_b64_tr_b16 v[240:241], v169 offset:17248
	ds_read_b64_tr_b16 v[242:243], v169 offset:25696
	s_nop 5
	s_waitcnt lgkmcnt(14)
	v_mfma_f32_16x16x32_bf16 v[40:43], v[204:207], v[8:11], v[112:115]
	ds_read_b64_tr_b16 v[204:205], v169 offset:384
	ds_read_b64_tr_b16 v[206:207], v169 offset:8832
	s_waitcnt lgkmcnt(14)
	v_mfma_f32_16x16x32_bf16 v[40:43], v[208:211], v[4:7], v[40:43]
	ds_read_b64_tr_b16 v[208:209], v169 offset:17280
	ds_read_b64_tr_b16 v[210:211], v169 offset:25728
	s_waitcnt lgkmcnt(14)
	v_mfma_f32_16x16x32_bf16 v[44:47], v[218:221], v[8:11], v[128:131]
	ds_read_b64_tr_b16 v[218:219], v169 offset:416
	ds_read_b64_tr_b16 v[220:221], v169 offset:8864
	s_waitcnt lgkmcnt(14)
	v_mfma_f32_16x16x32_bf16 v[44:47], v[224:227], v[4:7], v[44:47]
	ds_read_b64_tr_b16 v[224:225], v169 offset:17312
	ds_read_b64_tr_b16 v[226:227], v169 offset:25760
	s_waitcnt lgkmcnt(14)
	v_mfma_f32_16x16x32_bf16 v[48:51], v[228:231], v[8:11], v[92:95]
	ds_read_b64_tr_b16 v[228:229], v169 offset:448
	ds_read_b64_tr_b16 v[230:231], v169 offset:8896
	s_waitcnt lgkmcnt(14)
	v_mfma_f32_16x16x32_bf16 v[48:51], v[232:235], v[4:7], v[48:51]
	ds_read_b64_tr_b16 v[232:233], v169 offset:17344
	ds_read_b64_tr_b16 v[234:235], v169 offset:25792
	s_waitcnt lgkmcnt(14)
	v_mfma_f32_16x16x32_bf16 v[52:55], v[236:239], v[8:11], v[116:119]
	ds_read_b64_tr_b16 v[236:237], v169 offset:480
	ds_read_b64_tr_b16 v[238:239], v169 offset:8928
	s_waitcnt lgkmcnt(14)
	v_mfma_f32_16x16x32_bf16 v[68:71], v[240:243], v[4:7], v[52:55]
	s_nop 5
	s_waitcnt lgkmcnt(12)
	v_mfma_f32_16x16x32_bf16 v[52:55], v[204:207], v[8:11], v[96:99]
	s_waitcnt lgkmcnt(10)
	v_mfma_f32_16x16x32_bf16 v[52:55], v[208:211], v[4:7], v[52:55]
	s_waitcnt lgkmcnt(8)
	v_mfma_f32_16x16x32_bf16 v[56:59], v[218:221], v[8:11], v[100:103]
	s_waitcnt lgkmcnt(6)
	v_mfma_f32_16x16x32_bf16 v[56:59], v[224:227], v[4:7], v[56:59]
	s_waitcnt lgkmcnt(4)
	v_mfma_f32_16x16x32_bf16 v[60:63], v[228:231], v[8:11], v[104:107]
	s_waitcnt lgkmcnt(2)
	v_mfma_f32_16x16x32_bf16 v[60:63], v[232:235], v[4:7], v[60:63]
	ds_read_b64_tr_b16 v[96:97], v169 offset:17376
	ds_read_b64_tr_b16 v[98:99], v169 offset:25824
	s_waitcnt vmcnt(3)
	ds_write_b128 v168, v[12:15]
	s_waitcnt vmcnt(2)
	ds_write_b128 v168, v[16:19] offset:128
	s_waitcnt vmcnt(1)
	ds_write_b128 v168, v[20:23] offset:256
	s_waitcnt vmcnt(0)
	ds_write_b128 v168, v[24:27] offset:384
	s_waitcnt lgkmcnt(0)
	s_waitcnt lgkmcnt(6)
	v_mfma_f32_16x16x32_bf16 v[8:11], v[236:239], v[8:11], v[88:91]
	s_nop 7
	s_barrier
	v_cvt_pk_bf16_f32 v20, v139, v140
	s_waitcnt lgkmcnt(4)
	v_mfma_f32_16x16x32_bf16 v[4:7], v[96:99], v[4:7], v[8:11]
	s_nop 3
	ds_read_b64_tr_b16 v[204:205], v3
	ds_read_b64_tr_b16 v[206:207], v3 offset:8448
	ds_read_b64_tr_b16 v[208:209], v3 offset:16896
	ds_read_b64_tr_b16 v[210:211], v3 offset:25344
	ds_read_b64_tr_b16 v[218:219], v3 offset:32
	ds_read_b64_tr_b16 v[220:221], v3 offset:8480
	ds_read_b64_tr_b16 v[224:225], v3 offset:16928
	ds_read_b64_tr_b16 v[226:227], v3 offset:25376
	ds_read_b64_tr_b16 v[228:229], v3 offset:64
	ds_read_b64_tr_b16 v[230:231], v3 offset:8512
	ds_read_b64_tr_b16 v[232:233], v3 offset:16960
	ds_read_b64_tr_b16 v[234:235], v3 offset:25408
	ds_read_b64_tr_b16 v[236:237], v3 offset:96
	ds_read_b64_tr_b16 v[238:239], v3 offset:8544
	ds_read_b64_tr_b16 v[240:241], v3 offset:16992
	ds_read_b64_tr_b16 v[242:243], v3 offset:25440
	v_cvt_pk_bf16_f32 v21, v141, v142
	v_cvt_pk_bf16_f32 v22, v143, v144
	v_cvt_pk_bf16_f32 v23, v145, v146
	v_cvt_pk_bf16_f32 v16, v147, v148
	v_cvt_pk_bf16_f32 v17, v149, v150
	s_nop 1
	s_waitcnt lgkmcnt(14)
	v_mfma_f32_16x16x32_bf16 v[8:11], v[204:207], v[20:23], v[76:79]
	ds_read_b64_tr_b16 v[204:205], v3 offset:128
	ds_read_b64_tr_b16 v[206:207], v3 offset:8576
	v_cvt_pk_bf16_f32 v18, v151, v152
	v_cvt_pk_bf16_f32 v19, v153, v154
	v_add_u32_e32 v88, 0x80, v136
	v_ashrrev_i32_e32 v89, 31, v88
	s_nop 1
	s_waitcnt lgkmcnt(14)
	v_mfma_f32_16x16x32_bf16 v[12:15], v[208:211], v[16:19], v[8:11]
	ds_read_b64_tr_b16 v[208:209], v3 offset:17024
	ds_read_b64_tr_b16 v[210:211], v3 offset:25472
	s_nop 1
	s_waitcnt lgkmcnt(14)
	v_mfma_f32_16x16x32_bf16 v[24:27], v[218:221], v[20:23], v[80:83]
	ds_read_b64_tr_b16 v[218:219], v3 offset:160
	ds_read_b64_tr_b16 v[220:221], v3 offset:8608
	s_waitcnt lgkmcnt(14)
	v_mfma_f32_16x16x32_bf16 v[8:11], v[224:227], v[16:19], v[24:27]
	ds_read_b64_tr_b16 v[224:225], v3 offset:17056
	ds_read_b64_tr_b16 v[226:227], v3 offset:25504
	s_nop 5
	s_waitcnt lgkmcnt(14)
	v_mfma_f32_16x16x32_bf16 v[24:27], v[228:231], v[20:23], v[84:87]
	ds_read_b64_tr_b16 v[228:229], v3 offset:192
	ds_read_b64_tr_b16 v[230:231], v3 offset:8640
	s_waitcnt lgkmcnt(14)
	v_mfma_f32_16x16x32_bf16 v[24:27], v[232:235], v[16:19], v[24:27]
	ds_read_b64_tr_b16 v[232:233], v3 offset:17088
	ds_read_b64_tr_b16 v[234:235], v3 offset:25536
	s_waitcnt lgkmcnt(14)
	v_mfma_f32_16x16x32_bf16 v[72:75], v[236:239], v[20:23], v[72:75]
	ds_read_b64_tr_b16 v[236:237], v3 offset:224
	ds_read_b64_tr_b16 v[238:239], v3 offset:8672
	s_waitcnt lgkmcnt(14)
	v_mfma_f32_16x16x32_bf16 v[72:75], v[240:243], v[16:19], v[72:75]
	ds_read_b64_tr_b16 v[240:241], v3 offset:17120
	ds_read_b64_tr_b16 v[242:243], v3 offset:25568
	s_waitcnt lgkmcnt(14)
	v_mfma_f32_16x16x32_bf16 v[28:31], v[204:207], v[20:23], v[28:31]
	ds_read_b64_tr_b16 v[204:205], v3 offset:256
	ds_read_b64_tr_b16 v[206:207], v3 offset:8704
	s_waitcnt lgkmcnt(14)
	v_mfma_f32_16x16x32_bf16 v[28:31], v[208:211], v[16:19], v[28:31]
	ds_read_b64_tr_b16 v[208:209], v3 offset:17152
	ds_read_b64_tr_b16 v[210:211], v3 offset:25600
	s_waitcnt lgkmcnt(14)
	v_mfma_f32_16x16x32_bf16 v[32:35], v[218:221], v[20:23], v[32:35]
	ds_read_b64_tr_b16 v[218:219], v3 offset:288
	ds_read_b64_tr_b16 v[220:221], v3 offset:8736
	s_waitcnt lgkmcnt(14)
	v_mfma_f32_16x16x32_bf16 v[32:35], v[224:227], v[16:19], v[32:35]
	ds_read_b64_tr_b16 v[224:225], v3 offset:17184
	ds_read_b64_tr_b16 v[226:227], v3 offset:25632
	s_waitcnt lgkmcnt(14)
	v_mfma_f32_16x16x32_bf16 v[36:39], v[228:231], v[20:23], v[36:39]
	ds_read_b64_tr_b16 v[228:229], v3 offset:320
	ds_read_b64_tr_b16 v[230:231], v3 offset:8768
	s_waitcnt lgkmcnt(14)
	v_mfma_f32_16x16x32_bf16 v[36:39], v[232:235], v[16:19], v[36:39]
	ds_read_b64_tr_b16 v[232:233], v3 offset:17216
	ds_read_b64_tr_b16 v[234:235], v3 offset:25664
	s_waitcnt lgkmcnt(14)
	v_mfma_f32_16x16x32_bf16 v[64:67], v[236:239], v[20:23], v[64:67]
	ds_read_b64_tr_b16 v[236:237], v3 offset:352
	ds_read_b64_tr_b16 v[238:239], v3 offset:8800
	s_waitcnt lgkmcnt(14)
	v_mfma_f32_16x16x32_bf16 v[64:67], v[240:243], v[16:19], v[64:67]
	ds_read_b64_tr_b16 v[240:241], v3 offset:17248
	ds_read_b64_tr_b16 v[242:243], v3 offset:25696
	s_waitcnt lgkmcnt(14)
	v_mfma_f32_16x16x32_bf16 v[40:43], v[204:207], v[20:23], v[40:43]
	ds_read_b64_tr_b16 v[204:205], v3 offset:384
	ds_read_b64_tr_b16 v[206:207], v3 offset:8832
	s_waitcnt lgkmcnt(14)
	v_mfma_f32_16x16x32_bf16 v[40:43], v[208:211], v[16:19], v[40:43]
	ds_read_b64_tr_b16 v[208:209], v3 offset:17280
	ds_read_b64_tr_b16 v[210:211], v3 offset:25728
	s_waitcnt lgkmcnt(14)
	v_mfma_f32_16x16x32_bf16 v[44:47], v[218:221], v[20:23], v[44:47]
	ds_read_b64_tr_b16 v[218:219], v3 offset:416
	ds_read_b64_tr_b16 v[220:221], v3 offset:8864
	s_waitcnt lgkmcnt(14)
	v_mfma_f32_16x16x32_bf16 v[44:47], v[224:227], v[16:19], v[44:47]
	ds_read_b64_tr_b16 v[224:225], v3 offset:17312
	ds_read_b64_tr_b16 v[226:227], v3 offset:25760
	s_waitcnt lgkmcnt(14)
	v_mfma_f32_16x16x32_bf16 v[48:51], v[228:231], v[20:23], v[48:51]
	ds_read_b64_tr_b16 v[228:229], v3 offset:448
	ds_read_b64_tr_b16 v[230:231], v3 offset:8896
	s_waitcnt lgkmcnt(14)
	v_mfma_f32_16x16x32_bf16 v[48:51], v[232:235], v[16:19], v[48:51]
	ds_read_b64_tr_b16 v[232:233], v3 offset:17344
	ds_read_b64_tr_b16 v[234:235], v3 offset:25792
	s_waitcnt lgkmcnt(14)
	v_mfma_f32_16x16x32_bf16 v[68:71], v[236:239], v[20:23], v[68:71]
	ds_read_b64_tr_b16 v[236:237], v3 offset:480
	ds_read_b64_tr_b16 v[238:239], v3 offset:8928
	s_waitcnt lgkmcnt(14)
	v_mfma_f32_16x16x32_bf16 v[68:71], v[240:243], v[16:19], v[68:71]
	ds_read_b64_tr_b16 v[240:241], v3 offset:17376
	ds_read_b64_tr_b16 v[242:243], v3 offset:25824
	s_waitcnt lgkmcnt(14)
	v_mfma_f32_16x16x32_bf16 v[52:55], v[204:207], v[20:23], v[52:55]
	s_waitcnt lgkmcnt(12)
	v_mfma_f32_16x16x32_bf16 v[52:55], v[208:211], v[16:19], v[52:55]
	s_waitcnt lgkmcnt(10)
	v_mfma_f32_16x16x32_bf16 v[56:59], v[218:221], v[20:23], v[56:59]
	s_waitcnt lgkmcnt(8)
	v_mfma_f32_16x16x32_bf16 v[56:59], v[224:227], v[16:19], v[56:59]
	s_waitcnt lgkmcnt(6)
	v_mfma_f32_16x16x32_bf16 v[60:63], v[228:231], v[20:23], v[60:63]
	s_waitcnt lgkmcnt(4)
	v_mfma_f32_16x16x32_bf16 v[60:63], v[232:235], v[16:19], v[60:63]
	v_add_f32_e32 v3, v137, v138
	s_nop 1
	s_waitcnt lgkmcnt(2)
	v_mfma_f32_16x16x32_bf16 v[4:7], v[236:239], v[20:23], v[4:7]
	s_waitcnt lgkmcnt(0)
	v_mfma_f32_16x16x32_bf16 v[4:7], v[240:243], v[16:19], v[4:7]
	s_nop 7
	v_div_scale_f32 v16, s[12:13], v3, v3, 1.0
	v_rcp_f32_e32 v17, v16
	s_nop 0
	v_fma_f32 v18, -v16, v17, 1.0
	v_fmac_f32_e32 v17, v18, v17
	v_div_scale_f32 v18, vcc, 1.0, v3, 1.0
	v_mul_f32_e32 v19, v18, v17
	v_fma_f32 v20, -v16, v19, v18
	v_fmac_f32_e32 v19, v20, v17
	v_fma_f32 v16, -v16, v19, v18
	v_div_fmas_f32 v16, v16, v17, v19
	v_lshlrev_b64 v[18:19], 11, v[88:89]
	v_lshl_add_u64 v[18:19], s[10:11], 0, v[18:19]
	v_div_fixup_f32 v16, v16, v3, 1.0
	v_mad_i64_i32 v[18:19], s[6:7], s6, v155, v[18:19]
	v_lshl_add_u64 v[18:19], v[18:19], 0, s[8:9]
	v_pk_mul_f32 v[8:9], v[16:17], v[8:9] op_sel_hi:[0,1]
	v_pk_mul_f32 v[10:11], v[16:17], v[10:11] op_sel_hi:[0,1]
	v_lshl_add_u64 v[0:1], v[18:19], 0, v[0:1]
	v_cvt_pk_bf16_f32 v8, v8, v9
	v_cvt_pk_bf16_f32 v9, v10, v11
	global_store_dwordx2 v[0:1], v[8:9], off offset:32
	v_pk_mul_f32 v[8:9], v[16:17], v[24:25] op_sel_hi:[0,1]
	v_pk_mul_f32 v[10:11], v[16:17], v[26:27] op_sel_hi:[0,1]
	v_cvt_pk_bf16_f32 v8, v8, v9
	v_cvt_pk_bf16_f32 v9, v10, v11
	global_store_dwordx2 v[0:1], v[8:9], off offset:64
	v_pk_mul_f32 v[8:9], v[16:17], v[72:73] op_sel_hi:[0,1]
	v_pk_mul_f32 v[10:11], v[16:17], v[74:75] op_sel_hi:[0,1]
	v_cvt_pk_bf16_f32 v8, v8, v9
	v_cvt_pk_bf16_f32 v9, v10, v11
	global_store_dwordx2 v[0:1], v[8:9], off offset:96
	v_pk_mul_f32 v[8:9], v[16:17], v[28:29] op_sel_hi:[0,1]
	v_pk_mul_f32 v[10:11], v[16:17], v[30:31] op_sel_hi:[0,1]
	v_cvt_pk_bf16_f32 v8, v8, v9
	v_cvt_pk_bf16_f32 v9, v10, v11
	global_store_dwordx2 v[0:1], v[8:9], off offset:128
	v_pk_mul_f32 v[8:9], v[16:17], v[32:33] op_sel_hi:[0,1]
	v_pk_mul_f32 v[10:11], v[16:17], v[34:35] op_sel_hi:[0,1]
	v_cvt_pk_bf16_f32 v8, v8, v9
	v_cvt_pk_bf16_f32 v9, v10, v11
	global_store_dwordx2 v[0:1], v[8:9], off offset:160
	v_pk_mul_f32 v[8:9], v[16:17], v[36:37] op_sel_hi:[0,1]
	v_pk_mul_f32 v[10:11], v[16:17], v[38:39] op_sel_hi:[0,1]
	v_cvt_pk_bf16_f32 v8, v8, v9
	v_cvt_pk_bf16_f32 v9, v10, v11
	global_store_dwordx2 v[0:1], v[8:9], off offset:192
	v_pk_mul_f32 v[8:9], v[16:17], v[64:65] op_sel_hi:[0,1]
	v_pk_mul_f32 v[10:11], v[16:17], v[66:67] op_sel_hi:[0,1]
	v_cvt_pk_bf16_f32 v8, v8, v9
	v_cvt_pk_bf16_f32 v9, v10, v11
	global_store_dwordx2 v[0:1], v[8:9], off offset:224
	v_pk_mul_f32 v[8:9], v[16:17], v[40:41] op_sel_hi:[0,1]
	v_pk_mul_f32 v[10:11], v[16:17], v[42:43] op_sel_hi:[0,1]
	v_cvt_pk_bf16_f32 v8, v8, v9
	v_cvt_pk_bf16_f32 v9, v10, v11
	global_store_dwordx2 v[0:1], v[8:9], off offset:256
	v_pk_mul_f32 v[8:9], v[16:17], v[44:45] op_sel_hi:[0,1]
	v_pk_mul_f32 v[10:11], v[16:17], v[46:47] op_sel_hi:[0,1]
	v_cvt_pk_bf16_f32 v8, v8, v9
	v_cvt_pk_bf16_f32 v9, v10, v11
	global_store_dwordx2 v[0:1], v[8:9], off offset:288
	v_pk_mul_f32 v[8:9], v[16:17], v[48:49] op_sel_hi:[0,1]
	v_pk_mul_f32 v[10:11], v[16:17], v[50:51] op_sel_hi:[0,1]
	v_cvt_pk_bf16_f32 v8, v8, v9
	v_cvt_pk_bf16_f32 v9, v10, v11
	global_store_dwordx2 v[0:1], v[8:9], off offset:320
	v_pk_mul_f32 v[8:9], v[16:17], v[68:69] op_sel_hi:[0,1]
	v_pk_mul_f32 v[10:11], v[16:17], v[70:71] op_sel_hi:[0,1]
	v_cvt_pk_bf16_f32 v8, v8, v9
	v_cvt_pk_bf16_f32 v9, v10, v11
	global_store_dwordx2 v[0:1], v[8:9], off offset:352
	v_pk_mul_f32 v[8:9], v[16:17], v[52:53] op_sel_hi:[0,1]
	v_pk_mul_f32 v[10:11], v[16:17], v[54:55] op_sel_hi:[0,1]
	v_cvt_pk_bf16_f32 v8, v8, v9
	v_cvt_pk_bf16_f32 v9, v10, v11
	global_store_dwordx2 v[0:1], v[8:9], off offset:384
	v_pk_mul_f32 v[8:9], v[16:17], v[56:57] op_sel_hi:[0,1]
	v_pk_mul_f32 v[10:11], v[16:17], v[58:59] op_sel_hi:[0,1]
	v_cvt_pk_bf16_f32 v8, v8, v9
	v_cvt_pk_bf16_f32 v9, v10, v11
	v_pk_mul_f32 v[12:13], v[16:17], v[12:13] op_sel_hi:[0,1]
	v_pk_mul_f32 v[14:15], v[16:17], v[14:15] op_sel_hi:[0,1]
	global_store_dwordx2 v[0:1], v[8:9], off offset:416
	v_pk_mul_f32 v[8:9], v[16:17], v[60:61] op_sel_hi:[0,1]
	v_pk_mul_f32 v[10:11], v[16:17], v[62:63] op_sel_hi:[0,1]
	v_pk_mul_f32 v[4:5], v[16:17], v[4:5] op_sel_hi:[0,1]
	v_pk_mul_f32 v[6:7], v[16:17], v[6:7] op_sel_hi:[0,1]
	v_cvt_pk_bf16_f32 v12, v12, v13
	v_cvt_pk_bf16_f32 v13, v14, v15
	v_cvt_pk_bf16_f32 v8, v8, v9
	v_cvt_pk_bf16_f32 v9, v10, v11
	v_cvt_pk_bf16_f32 v4, v4, v5
	v_cvt_pk_bf16_f32 v5, v6, v7
	global_store_dwordx2 v[0:1], v[12:13], off
	global_store_dwordx2 v[0:1], v[8:9], off offset:448
	global_store_dwordx2 v[0:1], v[4:5], off offset:480
	s_waitcnt lgkmcnt(0)
	s_barrier
